# P0 adaLN modulation GEMV rewritten by hand (pipelined loads, LDS broadcast reads) + attention s_nop cleanup
# speedup vs baseline: 1.0415x; 1.0105x over previous
; #define LAS __attribute__((address_space(3)))
; __device__ __forceinline__ float silu_f(float x) { const float e = __builtin_amdgcn_exp2f(-x * 1.4426950408889634f); return x * __builtin_amdgcn_rcpf(1.f + e); }
; __global__ void __launch_bounds__(512, 2) mega_fwd(Args a) {
;     ...
;         for (int it = bx; it < 96; it += G) {
;             LAS float* sl = (LAS float*)lds; LAS float* red = (LAS float*)(lds + 65536);
;             for (int e = tid; e < 16384; e += 512) { const int r = e >> 10, k = e & 1023; const float c = r < 8 ? c_p[r * 1024 + k] : c_s[(r - 8) * 1024 + k]; sl[e] = silu_f(c); }
;             __syncthreads();
;             float acc[16];
; #pragma unroll
;             for (int r = 0; r < 16; ++r) acc[r] = 0.f;
;             const float* wp = w_ada + (size_t)(wid * 128) * 6144 + it * 64 + lane;
;             for (int k = 0; k < 128; k += 16) {
;                 float wv[16];
; #pragma unroll
;                 for (int j = 0; j < 16; ++j) wv[j] = __builtin_nontemporal_load(wp + (size_t)(k + j) * 6144);
.LBB0_5:
	s_or_b64 exec, exec, s[4:5]
	s_load_dwordx16 s[4:19], s[0:1], 0x0
	v_mov_b32_e32 v174, v211
	s_waitcnt lgkmcnt(0)
	v_writelane_b32 v238, s4, 4
	s_nop 1
	v_writelane_b32 v238, s5, 5
	v_writelane_b32 v238, s6, 6
	v_writelane_b32 v238, s7, 7
	v_writelane_b32 v238, s8, 8
	v_writelane_b32 v238, s9, 9
	v_writelane_b32 v238, s10, 10
	v_writelane_b32 v238, s11, 11
	v_writelane_b32 v238, s12, 12
	v_writelane_b32 v238, s13, 13
	v_writelane_b32 v238, s14, 14
	v_writelane_b32 v238, s15, 15
	v_writelane_b32 v238, s16, 16
	v_writelane_b32 v238, s17, 17
	v_writelane_b32 v238, s18, 18
	v_readfirstlane_b32 s3, v174
	v_writelane_b32 v238, s19, 19
	s_ashr_i32 s7, s3, 6
	s_cmpk_lt_i32 s2, 0x60
	s_cselect_b64 s[82:83], -1, 0
	s_cmpk_gt_i32 s2, 0x5f
	v_and_b32_e32 v1, 63, v174
	s_cbranch_scc1 .LBB0_18
	s_load_dwordx16 s[8:23], s[0:1], 0x0
	v_lshlrev_b32_e32 v2, 2, v174
	v_lshlrev_b32_e32 v3, 2, v1
	s_lshl_b32 s3, s7, 9
	v_mov_b32_e32 v4, s3
	s_mov_b32 s61, s2
	s_waitcnt lgkmcnt(0)
.Lada_it:
	s_mov_b64 s[40:41], s[16:17]
	global_load_dword v48, v2, s[40:41]
	s_add_u32 s40, s40, 0x800
	s_addc_u32 s41, s41, 0
	global_load_dword v49, v2, s[40:41]
	s_add_u32 s40, s40, 0x800
	s_addc_u32 s41, s41, 0
	global_load_dword v50, v2, s[40:41]
	s_add_u32 s40, s40, 0x800
	s_addc_u32 s41, s41, 0
	global_load_dword v51, v2, s[40:41]
	s_add_u32 s40, s40, 0x800
	s_addc_u32 s41, s41, 0
	global_load_dword v52, v2, s[40:41]
	s_add_u32 s40, s40, 0x800
	s_addc_u32 s41, s41, 0
	global_load_dword v53, v2, s[40:41]
	s_add_u32 s40, s40, 0x800
	s_addc_u32 s41, s41, 0
	global_load_dword v54, v2, s[40:41]
	s_add_u32 s40, s40, 0x800
	s_addc_u32 s41, s41, 0
	global_load_dword v55, v2, s[40:41]
	s_add_u32 s40, s40, 0x800
	s_addc_u32 s41, s41, 0
	global_load_dword v56, v2, s[40:41]
	s_add_u32 s40, s40, 0x800
	s_addc_u32 s41, s41, 0
	global_load_dword v57, v2, s[40:41]
	s_add_u32 s40, s40, 0x800
	s_addc_u32 s41, s41, 0
	global_load_dword v58, v2, s[40:41]
	s_add_u32 s40, s40, 0x800
	s_addc_u32 s41, s41, 0
	global_load_dword v59, v2, s[40:41]
	s_add_u32 s40, s40, 0x800
	s_addc_u32 s41, s41, 0
	global_load_dword v60, v2, s[40:41]
	s_add_u32 s40, s40, 0x800
	s_addc_u32 s41, s41, 0
	global_load_dword v61, v2, s[40:41]
	s_add_u32 s40, s40, 0x800
	s_addc_u32 s41, s41, 0
	global_load_dword v62, v2, s[40:41]
	s_add_u32 s40, s40, 0x800
	s_addc_u32 s41, s41, 0
	global_load_dword v63, v2, s[40:41]
	s_mov_b64 s[40:41], s[18:19]
	global_load_dword v64, v2, s[40:41]
	s_add_u32 s40, s40, 0x800
	s_addc_u32 s41, s41, 0
	global_load_dword v65, v2, s[40:41]
	s_add_u32 s40, s40, 0x800
	s_addc_u32 s41, s41, 0
	global_load_dword v66, v2, s[40:41]
	s_add_u32 s40, s40, 0x800
	s_addc_u32 s41, s41, 0
	global_load_dword v67, v2, s[40:41]
	s_add_u32 s40, s40, 0x800
	s_addc_u32 s41, s41, 0
	global_load_dword v68, v2, s[40:41]
	s_add_u32 s40, s40, 0x800
	s_addc_u32 s41, s41, 0
	global_load_dword v69, v2, s[40:41]
	s_add_u32 s40, s40, 0x800
	s_addc_u32 s41, s41, 0
	global_load_dword v70, v2, s[40:41]
	s_add_u32 s40, s40, 0x800
	s_addc_u32 s41, s41, 0
	global_load_dword v71, v2, s[40:41]
	s_add_u32 s40, s40, 0x800
	s_addc_u32 s41, s41, 0
	global_load_dword v72, v2, s[40:41]
	s_add_u32 s40, s40, 0x800
	s_addc_u32 s41, s41, 0
	global_load_dword v73, v2, s[40:41]
	s_add_u32 s40, s40, 0x800
	s_addc_u32 s41, s41, 0
	global_load_dword v74, v2, s[40:41]
	s_add_u32 s40, s40, 0x800
	s_addc_u32 s41, s41, 0
	global_load_dword v75, v2, s[40:41]
	s_add_u32 s40, s40, 0x800
	s_addc_u32 s41, s41, 0
	global_load_dword v76, v2, s[40:41]
	s_add_u32 s40, s40, 0x800
	s_addc_u32 s41, s41, 0
	global_load_dword v77, v2, s[40:41]
	s_add_u32 s40, s40, 0x800
	s_addc_u32 s41, s41, 0
	global_load_dword v78, v2, s[40:41]
	s_add_u32 s40, s40, 0x800
	s_addc_u32 s41, s41, 0
	global_load_dword v79, v2, s[40:41]
	s_mul_i32 s3, s7, 0x300000
	s_add_u32 s42, s20, s3
	s_addc_u32 s43, s21, 0
	s_lshl_b32 s3, s61, 8
	s_add_u32 s42, s42, s3
	s_addc_u32 s43, s43, 0
	global_load_dword v80, v3, s[42:43] nt
	s_add_u32 s42, s42, 0x6000
	s_addc_u32 s43, s43, 0
	global_load_dword v81, v3, s[42:43] nt
	s_add_u32 s42, s42, 0x6000
	s_addc_u32 s43, s43, 0
	global_load_dword v82, v3, s[42:43] nt
	s_add_u32 s42, s42, 0x6000
	s_addc_u32 s43, s43, 0
	global_load_dword v83, v3, s[42:43] nt
	s_add_u32 s42, s42, 0x6000
	s_addc_u32 s43, s43, 0
	global_load_dword v84, v3, s[42:43] nt
	s_add_u32 s42, s42, 0x6000
	s_addc_u32 s43, s43, 0
	global_load_dword v85, v3, s[42:43] nt
	s_add_u32 s42, s42, 0x6000
	s_addc_u32 s43, s43, 0
	global_load_dword v86, v3, s[42:43] nt
	s_add_u32 s42, s42, 0x6000
	s_addc_u32 s43, s43, 0
	global_load_dword v87, v3, s[42:43] nt
	s_add_u32 s42, s42, 0x6000
	s_addc_u32 s43, s43, 0
	global_load_dword v88, v3, s[42:43] nt
	s_add_u32 s42, s42, 0x6000
	s_addc_u32 s43, s43, 0
	global_load_dword v89, v3, s[42:43] nt
	s_add_u32 s42, s42, 0x6000
	s_addc_u32 s43, s43, 0
	global_load_dword v90, v3, s[42:43] nt
	s_add_u32 s42, s42, 0x6000
	s_addc_u32 s43, s43, 0
	global_load_dword v91, v3, s[42:43] nt
	s_add_u32 s42, s42, 0x6000
	s_addc_u32 s43, s43, 0
	global_load_dword v92, v3, s[42:43] nt
	s_add_u32 s42, s42, 0x6000
	s_addc_u32 s43, s43, 0
	global_load_dword v93, v3, s[42:43] nt
	s_add_u32 s42, s42, 0x6000
	s_addc_u32 s43, s43, 0
	global_load_dword v94, v3, s[42:43] nt
	s_add_u32 s42, s42, 0x6000
	s_addc_u32 s43, s43, 0
	global_load_dword v95, v3, s[42:43] nt
	s_add_u32 s42, s42, 0x6000
	s_addc_u32 s43, s43, 0
	global_load_dword v96, v3, s[42:43] nt
	s_add_u32 s42, s42, 0x6000
	s_addc_u32 s43, s43, 0
	global_load_dword v97, v3, s[42:43] nt
	s_add_u32 s42, s42, 0x6000
	s_addc_u32 s43, s43, 0
	global_load_dword v98, v3, s[42:43] nt
	s_add_u32 s42, s42, 0x6000
	s_addc_u32 s43, s43, 0
	global_load_dword v99, v3, s[42:43] nt
	s_add_u32 s42, s42, 0x6000
	s_addc_u32 s43, s43, 0
	global_load_dword v100, v3, s[42:43] nt
	s_add_u32 s42, s42, 0x6000
	s_addc_u32 s43, s43, 0
	global_load_dword v101, v3, s[42:43] nt
	s_add_u32 s42, s42, 0x6000
	s_addc_u32 s43, s43, 0
	global_load_dword v102, v3, s[42:43] nt
	s_add_u32 s42, s42, 0x6000
	s_addc_u32 s43, s43, 0
	global_load_dword v103, v3, s[42:43] nt
	s_add_u32 s42, s42, 0x6000
	s_addc_u32 s43, s43, 0
	global_load_dword v104, v3, s[42:43] nt
	s_add_u32 s42, s42, 0x6000
	s_addc_u32 s43, s43, 0
	global_load_dword v105, v3, s[42:43] nt
	s_add_u32 s42, s42, 0x6000
	s_addc_u32 s43, s43, 0
	global_load_dword v106, v3, s[42:43] nt
	s_add_u32 s42, s42, 0x6000
	s_addc_u32 s43, s43, 0
	global_load_dword v107, v3, s[42:43] nt
	s_add_u32 s42, s42, 0x6000
	s_addc_u32 s43, s43, 0
	global_load_dword v108, v3, s[42:43] nt
	s_add_u32 s42, s42, 0x6000
	s_addc_u32 s43, s43, 0
	global_load_dword v109, v3, s[42:43] nt
	s_add_u32 s42, s42, 0x6000
	s_addc_u32 s43, s43, 0
	global_load_dword v110, v3, s[42:43] nt
	s_add_u32 s42, s42, 0x6000
	s_addc_u32 s43, s43, 0
	global_load_dword v111, v3, s[42:43] nt
	s_add_u32 s42, s42, 0x6000
	s_addc_u32 s43, s43, 0
	s_waitcnt vmcnt(32)
; __device__ __forceinline__ float silu_f(float x) { const float e = __builtin_amdgcn_exp2f(-x * 1.4426950408889634f); return x * __builtin_amdgcn_rcpf(1.f + e); }
; __global__ void __launch_bounds__(512, 2) mega_fwd(Args a) {
;     ...
;             for (int e = tid; e < 16384; e += 512) { const int r = e >> 10, k = e & 1023; const float c = r < 8 ? c_p[r * 1024 + k] : c_s[(r - 8) * 1024 + k]; sl[e] = silu_f(c); }
;             __syncthreads();
;             float acc[16];
; #pragma unroll
;             for (int r = 0; r < 16; ++r) acc[r] = 0.f;
	v_mul_f32_e32 v5, 0xbfb8aa3b, v48
	v_exp_f32_e32 v5, v5
	s_nop 0
	v_add_f32_e32 v5, 1.0, v5
	v_rcp_f32_e32 v5, v5
	s_nop 0
	v_mul_f32_e32 v48, v48, v5
	ds_write_b32 v2, v48
	v_mul_f32_e32 v5, 0xbfb8aa3b, v49
	v_exp_f32_e32 v5, v5
	s_nop 0
	v_add_f32_e32 v5, 1.0, v5
	v_rcp_f32_e32 v5, v5
	s_nop 0
	v_mul_f32_e32 v49, v49, v5
	ds_write_b32 v2, v49 offset:2048
	v_mul_f32_e32 v5, 0xbfb8aa3b, v50
	v_exp_f32_e32 v5, v5
	s_nop 0
	v_add_f32_e32 v5, 1.0, v5
	v_rcp_f32_e32 v5, v5
	s_nop 0
	v_mul_f32_e32 v50, v50, v5
	ds_write_b32 v2, v50 offset:4096
	v_mul_f32_e32 v5, 0xbfb8aa3b, v51
	v_exp_f32_e32 v5, v5
	s_nop 0
	v_add_f32_e32 v5, 1.0, v5
	v_rcp_f32_e32 v5, v5
	s_nop 0
	v_mul_f32_e32 v51, v51, v5
	ds_write_b32 v2, v51 offset:6144
	v_mul_f32_e32 v5, 0xbfb8aa3b, v52
	v_exp_f32_e32 v5, v5
	s_nop 0
	v_add_f32_e32 v5, 1.0, v5
	v_rcp_f32_e32 v5, v5
	s_nop 0
	v_mul_f32_e32 v52, v52, v5
	ds_write_b32 v2, v52 offset:8192
	v_mul_f32_e32 v5, 0xbfb8aa3b, v53
	v_exp_f32_e32 v5, v5
	s_nop 0
	v_add_f32_e32 v5, 1.0, v5
	v_rcp_f32_e32 v5, v5
	s_nop 0
	v_mul_f32_e32 v53, v53, v5
	ds_write_b32 v2, v53 offset:10240
	v_mul_f32_e32 v5, 0xbfb8aa3b, v54
	v_exp_f32_e32 v5, v5
	s_nop 0
	v_add_f32_e32 v5, 1.0, v5
	v_rcp_f32_e32 v5, v5
	s_nop 0
	v_mul_f32_e32 v54, v54, v5
	ds_write_b32 v2, v54 offset:12288
	v_mul_f32_e32 v5, 0xbfb8aa3b, v55
	v_exp_f32_e32 v5, v5
	s_nop 0
	v_add_f32_e32 v5, 1.0, v5
	v_rcp_f32_e32 v5, v5
	s_nop 0
	v_mul_f32_e32 v55, v55, v5
	ds_write_b32 v2, v55 offset:14336
	v_mul_f32_e32 v5, 0xbfb8aa3b, v56
	v_exp_f32_e32 v5, v5
	s_nop 0
	v_add_f32_e32 v5, 1.0, v5
	v_rcp_f32_e32 v5, v5
	s_nop 0
	v_mul_f32_e32 v56, v56, v5
	ds_write_b32 v2, v56 offset:16384
	v_mul_f32_e32 v5, 0xbfb8aa3b, v57
	v_exp_f32_e32 v5, v5
	s_nop 0
	v_add_f32_e32 v5, 1.0, v5
	v_rcp_f32_e32 v5, v5
	s_nop 0
	v_mul_f32_e32 v57, v57, v5
	ds_write_b32 v2, v57 offset:18432
	v_mul_f32_e32 v5, 0xbfb8aa3b, v58
	v_exp_f32_e32 v5, v5
	s_nop 0
	v_add_f32_e32 v5, 1.0, v5
	v_rcp_f32_e32 v5, v5
	s_nop 0
	v_mul_f32_e32 v58, v58, v5
	ds_write_b32 v2, v58 offset:20480
	v_mul_f32_e32 v5, 0xbfb8aa3b, v59
	v_exp_f32_e32 v5, v5
	s_nop 0
	v_add_f32_e32 v5, 1.0, v5
	v_rcp_f32_e32 v5, v5
	s_nop 0
	v_mul_f32_e32 v59, v59, v5
	ds_write_b32 v2, v59 offset:22528
	v_mul_f32_e32 v5, 0xbfb8aa3b, v60
	v_exp_f32_e32 v5, v5
	s_nop 0
	v_add_f32_e32 v5, 1.0, v5
	v_rcp_f32_e32 v5, v5
	s_nop 0
	v_mul_f32_e32 v60, v60, v5
	ds_write_b32 v2, v60 offset:24576
	v_mul_f32_e32 v5, 0xbfb8aa3b, v61
	v_exp_f32_e32 v5, v5
	s_nop 0
	v_add_f32_e32 v5, 1.0, v5
	v_rcp_f32_e32 v5, v5
	s_nop 0
	v_mul_f32_e32 v61, v61, v5
	ds_write_b32 v2, v61 offset:26624
	v_mul_f32_e32 v5, 0xbfb8aa3b, v62
	v_exp_f32_e32 v5, v5
	s_nop 0
	v_add_f32_e32 v5, 1.0, v5
	v_rcp_f32_e32 v5, v5
	s_nop 0
	v_mul_f32_e32 v62, v62, v5
	ds_write_b32 v2, v62 offset:28672
	v_mul_f32_e32 v5, 0xbfb8aa3b, v63
	v_exp_f32_e32 v5, v5
	s_nop 0
	v_add_f32_e32 v5, 1.0, v5
	v_rcp_f32_e32 v5, v5
	s_nop 0
	v_mul_f32_e32 v63, v63, v5
	ds_write_b32 v2, v63 offset:30720
	v_mul_f32_e32 v5, 0xbfb8aa3b, v64
	v_exp_f32_e32 v5, v5
	s_nop 0
	v_add_f32_e32 v5, 1.0, v5
	v_rcp_f32_e32 v5, v5
	s_nop 0
	v_mul_f32_e32 v64, v64, v5
	ds_write_b32 v2, v64 offset:32768
	v_mul_f32_e32 v5, 0xbfb8aa3b, v65
	v_exp_f32_e32 v5, v5
	s_nop 0
	v_add_f32_e32 v5, 1.0, v5
	v_rcp_f32_e32 v5, v5
	s_nop 0
	v_mul_f32_e32 v65, v65, v5
	ds_write_b32 v2, v65 offset:34816
	v_mul_f32_e32 v5, 0xbfb8aa3b, v66
	v_exp_f32_e32 v5, v5
	s_nop 0
	v_add_f32_e32 v5, 1.0, v5
	v_rcp_f32_e32 v5, v5
	s_nop 0
	v_mul_f32_e32 v66, v66, v5
	ds_write_b32 v2, v66 offset:36864
	v_mul_f32_e32 v5, 0xbfb8aa3b, v67
	v_exp_f32_e32 v5, v5
	s_nop 0
	v_add_f32_e32 v5, 1.0, v5
	v_rcp_f32_e32 v5, v5
	s_nop 0
	v_mul_f32_e32 v67, v67, v5
	ds_write_b32 v2, v67 offset:38912
	v_mul_f32_e32 v5, 0xbfb8aa3b, v68
	v_exp_f32_e32 v5, v5
	s_nop 0
	v_add_f32_e32 v5, 1.0, v5
	v_rcp_f32_e32 v5, v5
	s_nop 0
	v_mul_f32_e32 v68, v68, v5
	ds_write_b32 v2, v68 offset:40960
	v_mul_f32_e32 v5, 0xbfb8aa3b, v69
	v_exp_f32_e32 v5, v5
	s_nop 0
	v_add_f32_e32 v5, 1.0, v5
	v_rcp_f32_e32 v5, v5
	s_nop 0
	v_mul_f32_e32 v69, v69, v5
	ds_write_b32 v2, v69 offset:43008
	v_mul_f32_e32 v5, 0xbfb8aa3b, v70
	v_exp_f32_e32 v5, v5
	s_nop 0
	v_add_f32_e32 v5, 1.0, v5
	v_rcp_f32_e32 v5, v5
	s_nop 0
	v_mul_f32_e32 v70, v70, v5
	ds_write_b32 v2, v70 offset:45056
	v_mul_f32_e32 v5, 0xbfb8aa3b, v71
	v_exp_f32_e32 v5, v5
	s_nop 0
	v_add_f32_e32 v5, 1.0, v5
	v_rcp_f32_e32 v5, v5
	s_nop 0
	v_mul_f32_e32 v71, v71, v5
	ds_write_b32 v2, v71 offset:47104
	v_mul_f32_e32 v5, 0xbfb8aa3b, v72
	v_exp_f32_e32 v5, v5
	s_nop 0
	v_add_f32_e32 v5, 1.0, v5
	v_rcp_f32_e32 v5, v5
	s_nop 0
	v_mul_f32_e32 v72, v72, v5
	ds_write_b32 v2, v72 offset:49152
	v_mul_f32_e32 v5, 0xbfb8aa3b, v73
	v_exp_f32_e32 v5, v5
	s_nop 0
	v_add_f32_e32 v5, 1.0, v5
	v_rcp_f32_e32 v5, v5
	s_nop 0
	v_mul_f32_e32 v73, v73, v5
	ds_write_b32 v2, v73 offset:51200
	v_mul_f32_e32 v5, 0xbfb8aa3b, v74
	v_exp_f32_e32 v5, v5
	s_nop 0
	v_add_f32_e32 v5, 1.0, v5
	v_rcp_f32_e32 v5, v5
	s_nop 0
	v_mul_f32_e32 v74, v74, v5
	ds_write_b32 v2, v74 offset:53248
	v_mul_f32_e32 v5, 0xbfb8aa3b, v75
	v_exp_f32_e32 v5, v5
	s_nop 0
	v_add_f32_e32 v5, 1.0, v5
	v_rcp_f32_e32 v5, v5
	s_nop 0
	v_mul_f32_e32 v75, v75, v5
	ds_write_b32 v2, v75 offset:55296
	v_mul_f32_e32 v5, 0xbfb8aa3b, v76
	v_exp_f32_e32 v5, v5
	s_nop 0
	v_add_f32_e32 v5, 1.0, v5
	v_rcp_f32_e32 v5, v5
	s_nop 0
	v_mul_f32_e32 v76, v76, v5
	ds_write_b32 v2, v76 offset:57344
	v_mul_f32_e32 v5, 0xbfb8aa3b, v77
	v_exp_f32_e32 v5, v5
	s_nop 0
	v_add_f32_e32 v5, 1.0, v5
	v_rcp_f32_e32 v5, v5
	s_nop 0
	v_mul_f32_e32 v77, v77, v5
	ds_write_b32 v2, v77 offset:59392
	v_mul_f32_e32 v5, 0xbfb8aa3b, v78
	v_exp_f32_e32 v5, v5
	s_nop 0
	v_add_f32_e32 v5, 1.0, v5
	v_rcp_f32_e32 v5, v5
	s_nop 0
	v_mul_f32_e32 v78, v78, v5
	ds_write_b32 v2, v78 offset:61440
	v_mul_f32_e32 v5, 0xbfb8aa3b, v79
	v_exp_f32_e32 v5, v5
	s_nop 0
	v_add_f32_e32 v5, 1.0, v5
	v_rcp_f32_e32 v5, v5
	s_nop 0
	v_mul_f32_e32 v79, v79, v5
	ds_write_b32 v2, v79 offset:63488
	v_mov_b32_e32 v16, 0
	v_mov_b32_e32 v17, 0
	v_mov_b32_e32 v18, 0
	v_mov_b32_e32 v19, 0
	v_mov_b32_e32 v20, 0
	v_mov_b32_e32 v21, 0
	v_mov_b32_e32 v22, 0
	v_mov_b32_e32 v23, 0
	v_mov_b32_e32 v24, 0
	v_mov_b32_e32 v25, 0
	v_mov_b32_e32 v26, 0
	v_mov_b32_e32 v27, 0
	v_mov_b32_e32 v28, 0
	v_mov_b32_e32 v29, 0
	v_mov_b32_e32 v30, 0
	v_mov_b32_e32 v31, 0
	s_waitcnt lgkmcnt(0)
	s_barrier
; #define LAS __attribute__((address_space(3)))
; __global__ void __launch_bounds__(512, 2) mega_fwd(Args a) {
;     ...
;             const float* wp = w_ada + (size_t)(wid * 128) * 6144 + it * 64 + lane;
;             for (int k = 0; k < 128; k += 16) {
;                 float wv[16];
; #pragma unroll
;                 for (int j = 0; j < 16; ++j) wv[j] = __builtin_nontemporal_load(wp + (size_t)(k + j) * 6144);
; #pragma unroll
;                 for (int jj = 0; jj < 4; ++jj)
; #pragma unroll
;                     for (int r = 0; r < 16; ++r) { const f32x4 s4 = *(const LAS f32x4*)(sl + r * 1024 + wid * 128 + k + 4 * jj);
;                         acc[r] += (s4[0] * wv[4 * jj] + s4[1] * wv[4 * jj + 1]) + (s4[2] * wv[4 * jj + 2] + s4[3] * wv[4 * jj + 3]); }
	s_waitcnt vmcnt(31)
	global_load_dword v112, v3, s[42:43] nt
	s_add_u32 s42, s42, 0x6000
	s_addc_u32 s43, s43, 0
	global_load_dword v113, v3, s[42:43] nt
	s_add_u32 s42, s42, 0x6000
	s_addc_u32 s43, s43, 0
	global_load_dword v114, v3, s[42:43] nt
	s_add_u32 s42, s42, 0x6000
	s_addc_u32 s43, s43, 0
	global_load_dword v115, v3, s[42:43] nt
	s_add_u32 s42, s42, 0x6000
	s_addc_u32 s43, s43, 0
	global_load_dword v116, v3, s[42:43] nt
	s_add_u32 s42, s42, 0x6000
	s_addc_u32 s43, s43, 0
	global_load_dword v117, v3, s[42:43] nt
	s_add_u32 s42, s42, 0x6000
	s_addc_u32 s43, s43, 0
	global_load_dword v118, v3, s[42:43] nt
	s_add_u32 s42, s42, 0x6000
	s_addc_u32 s43, s43, 0
	global_load_dword v119, v3, s[42:43] nt
	s_add_u32 s42, s42, 0x6000
	s_addc_u32 s43, s43, 0
	global_load_dword v120, v3, s[42:43] nt
	s_add_u32 s42, s42, 0x6000
	s_addc_u32 s43, s43, 0
	global_load_dword v121, v3, s[42:43] nt
	s_add_u32 s42, s42, 0x6000
	s_addc_u32 s43, s43, 0
	global_load_dword v122, v3, s[42:43] nt
	s_add_u32 s42, s42, 0x6000
	s_addc_u32 s43, s43, 0
	global_load_dword v123, v3, s[42:43] nt
	s_add_u32 s42, s42, 0x6000
	s_addc_u32 s43, s43, 0
	global_load_dword v124, v3, s[42:43] nt
	s_add_u32 s42, s42, 0x6000
	s_addc_u32 s43, s43, 0
	global_load_dword v125, v3, s[42:43] nt
	s_add_u32 s42, s42, 0x6000
	s_addc_u32 s43, s43, 0
	global_load_dword v126, v3, s[42:43] nt
	s_add_u32 s42, s42, 0x6000
	s_addc_u32 s43, s43, 0
	global_load_dword v127, v3, s[42:43] nt
	s_add_u32 s42, s42, 0x6000
	s_addc_u32 s43, s43, 0
	global_load_dword v128, v3, s[42:43] nt
	s_add_u32 s42, s42, 0x6000
	s_addc_u32 s43, s43, 0
	global_load_dword v129, v3, s[42:43] nt
	s_add_u32 s42, s42, 0x6000
	s_addc_u32 s43, s43, 0
	global_load_dword v130, v3, s[42:43] nt
	s_add_u32 s42, s42, 0x6000
	s_addc_u32 s43, s43, 0
	global_load_dword v131, v3, s[42:43] nt
	s_add_u32 s42, s42, 0x6000
	s_addc_u32 s43, s43, 0
	global_load_dword v132, v3, s[42:43] nt
	s_add_u32 s42, s42, 0x6000
	s_addc_u32 s43, s43, 0
	global_load_dword v133, v3, s[42:43] nt
	s_add_u32 s42, s42, 0x6000
	s_addc_u32 s43, s43, 0
	global_load_dword v134, v3, s[42:43] nt
	s_add_u32 s42, s42, 0x6000
	s_addc_u32 s43, s43, 0
	global_load_dword v135, v3, s[42:43] nt
	s_add_u32 s42, s42, 0x6000
	s_addc_u32 s43, s43, 0
	global_load_dword v136, v3, s[42:43] nt
	s_add_u32 s42, s42, 0x6000
	s_addc_u32 s43, s43, 0
	global_load_dword v137, v3, s[42:43] nt
	s_add_u32 s42, s42, 0x6000
	s_addc_u32 s43, s43, 0
	global_load_dword v138, v3, s[42:43] nt
	s_add_u32 s42, s42, 0x6000
	s_addc_u32 s43, s43, 0
	global_load_dword v139, v3, s[42:43] nt
	s_add_u32 s42, s42, 0x6000
	s_addc_u32 s43, s43, 0
	global_load_dword v140, v3, s[42:43] nt
	s_add_u32 s42, s42, 0x6000
	s_addc_u32 s43, s43, 0
	global_load_dword v141, v3, s[42:43] nt
	s_add_u32 s42, s42, 0x6000
	s_addc_u32 s43, s43, 0
	global_load_dword v142, v3, s[42:43] nt
	s_add_u32 s42, s42, 0x6000
	s_addc_u32 s43, s43, 0
	global_load_dword v143, v3, s[42:43] nt
	s_add_u32 s42, s42, 0x6000
	s_addc_u32 s43, s43, 0
	ds_read_b128 v[32:35], v4
	ds_read_b128 v[36:39], v4 offset:4096
	ds_read_b128 v[40:43], v4 offset:8192
	ds_read_b128 v[44:47], v4 offset:12288
	ds_read_b128 v[212:215], v4 offset:16384
	ds_read_b128 v[216:219], v4 offset:20480
	ds_read_b128 v[220:223], v4 offset:24576
	ds_read_b128 v[224:227], v4 offset:28672
	ds_read_b128 v[48:51], v4 offset:32768
	ds_read_b128 v[52:55], v4 offset:36864
	ds_read_b128 v[56:59], v4 offset:40960
	ds_read_b128 v[60:63], v4 offset:45056
	s_waitcnt vmcnt(32)
	s_waitcnt lgkmcnt(8)
	v_fmac_f32_e32 v16, v32, v80
	v_fmac_f32_e32 v16, v33, v81
	v_fmac_f32_e32 v16, v34, v82
	v_fmac_f32_e32 v16, v35, v83
	v_fmac_f32_e32 v17, v36, v80
	v_fmac_f32_e32 v17, v37, v81
	v_fmac_f32_e32 v17, v38, v82
	v_fmac_f32_e32 v17, v39, v83
	v_fmac_f32_e32 v18, v40, v80
	v_fmac_f32_e32 v18, v41, v81
	v_fmac_f32_e32 v18, v42, v82
	v_fmac_f32_e32 v18, v43, v83
	v_fmac_f32_e32 v19, v44, v80
	v_fmac_f32_e32 v19, v45, v81
	v_fmac_f32_e32 v19, v46, v82
	v_fmac_f32_e32 v19, v47, v83
	ds_read_b128 v[64:67], v4 offset:49152
	ds_read_b128 v[68:71], v4 offset:53248
	ds_read_b128 v[72:75], v4 offset:57344
	ds_read_b128 v[76:79], v4 offset:61440
	s_waitcnt lgkmcnt(8)
	v_fmac_f32_e32 v20, v212, v80
	v_fmac_f32_e32 v20, v213, v81
	v_fmac_f32_e32 v20, v214, v82
	v_fmac_f32_e32 v20, v215, v83
	v_fmac_f32_e32 v21, v216, v80
	v_fmac_f32_e32 v21, v217, v81
	v_fmac_f32_e32 v21, v218, v82
	v_fmac_f32_e32 v21, v219, v83
	v_fmac_f32_e32 v22, v220, v80
	v_fmac_f32_e32 v22, v221, v81
	v_fmac_f32_e32 v22, v222, v82
	v_fmac_f32_e32 v22, v223, v83
	v_fmac_f32_e32 v23, v224, v80
	v_fmac_f32_e32 v23, v225, v81
	v_fmac_f32_e32 v23, v226, v82
	v_fmac_f32_e32 v23, v227, v83
	ds_read_b128 v[32:35], v4 offset:16
	ds_read_b128 v[36:39], v4 offset:4112
	ds_read_b128 v[40:43], v4 offset:8208
	ds_read_b128 v[44:47], v4 offset:12304
	s_waitcnt lgkmcnt(8)
	v_fmac_f32_e32 v24, v48, v80
	v_fmac_f32_e32 v24, v49, v81
	v_fmac_f32_e32 v24, v50, v82
	v_fmac_f32_e32 v24, v51, v83
	v_fmac_f32_e32 v25, v52, v80
	v_fmac_f32_e32 v25, v53, v81
	v_fmac_f32_e32 v25, v54, v82
	v_fmac_f32_e32 v25, v55, v83
	v_fmac_f32_e32 v26, v56, v80
	v_fmac_f32_e32 v26, v57, v81
	v_fmac_f32_e32 v26, v58, v82
	v_fmac_f32_e32 v26, v59, v83
	v_fmac_f32_e32 v27, v60, v80
	v_fmac_f32_e32 v27, v61, v81
	v_fmac_f32_e32 v27, v62, v82
	v_fmac_f32_e32 v27, v63, v83
	ds_read_b128 v[212:215], v4 offset:16400
	ds_read_b128 v[216:219], v4 offset:20496
	ds_read_b128 v[220:223], v4 offset:24592
	ds_read_b128 v[224:227], v4 offset:28688
	s_waitcnt lgkmcnt(8)
; #define LAS __attribute__((address_space(3)))
; __global__ void __launch_bounds__(512, 2) mega_fwd(Args a) {
;     ...
;             for (int k = 0; k < 128; k += 16) {
;                 float wv[16];
; #pragma unroll
;                 for (int j = 0; j < 16; ++j) wv[j] = __builtin_nontemporal_load(wp + (size_t)(k + j) * 6144);
; #pragma unroll
;                 for (int jj = 0; jj < 4; ++jj)
; #pragma unroll
;                     for (int r = 0; r < 16; ++r) { const f32x4 s4 = *(const LAS f32x4*)(sl + r * 1024 + wid * 128 + k + 4 * jj);
;                         acc[r] += (s4[0] * wv[4 * jj] + s4[1] * wv[4 * jj + 1]) + (s4[2] * wv[4 * jj + 2] + s4[3] * wv[4 * jj + 3]); }
	v_fmac_f32_e32 v28, v64, v80
	v_fmac_f32_e32 v28, v65, v81
	v_fmac_f32_e32 v28, v66, v82
	v_fmac_f32_e32 v28, v67, v83
	v_fmac_f32_e32 v29, v68, v80
	v_fmac_f32_e32 v29, v69, v81
	v_fmac_f32_e32 v29, v70, v82
	v_fmac_f32_e32 v29, v71, v83
	v_fmac_f32_e32 v30, v72, v80
	v_fmac_f32_e32 v30, v73, v81
	v_fmac_f32_e32 v30, v74, v82
	v_fmac_f32_e32 v30, v75, v83
	v_fmac_f32_e32 v31, v76, v80
	v_fmac_f32_e32 v31, v77, v81
	v_fmac_f32_e32 v31, v78, v82
	v_fmac_f32_e32 v31, v79, v83
	ds_read_b128 v[48:51], v4 offset:32784
	ds_read_b128 v[52:55], v4 offset:36880
	ds_read_b128 v[56:59], v4 offset:40976
	ds_read_b128 v[60:63], v4 offset:45072
	s_waitcnt lgkmcnt(8)
	v_fmac_f32_e32 v16, v32, v84
	v_fmac_f32_e32 v16, v33, v85
	v_fmac_f32_e32 v16, v34, v86
	v_fmac_f32_e32 v16, v35, v87
	v_fmac_f32_e32 v17, v36, v84
	v_fmac_f32_e32 v17, v37, v85
	v_fmac_f32_e32 v17, v38, v86
	v_fmac_f32_e32 v17, v39, v87
	v_fmac_f32_e32 v18, v40, v84
	v_fmac_f32_e32 v18, v41, v85
	v_fmac_f32_e32 v18, v42, v86
	v_fmac_f32_e32 v18, v43, v87
	v_fmac_f32_e32 v19, v44, v84
	v_fmac_f32_e32 v19, v45, v85
	v_fmac_f32_e32 v19, v46, v86
	v_fmac_f32_e32 v19, v47, v87
	ds_read_b128 v[64:67], v4 offset:49168
	ds_read_b128 v[68:71], v4 offset:53264
	ds_read_b128 v[72:75], v4 offset:57360
	ds_read_b128 v[76:79], v4 offset:61456
	s_waitcnt lgkmcnt(8)
	v_fmac_f32_e32 v20, v212, v84
	v_fmac_f32_e32 v20, v213, v85
	v_fmac_f32_e32 v20, v214, v86
	v_fmac_f32_e32 v20, v215, v87
	v_fmac_f32_e32 v21, v216, v84
	v_fmac_f32_e32 v21, v217, v85
	v_fmac_f32_e32 v21, v218, v86
	v_fmac_f32_e32 v21, v219, v87
	v_fmac_f32_e32 v22, v220, v84
	v_fmac_f32_e32 v22, v221, v85
	v_fmac_f32_e32 v22, v222, v86
	v_fmac_f32_e32 v22, v223, v87
	v_fmac_f32_e32 v23, v224, v84
	v_fmac_f32_e32 v23, v225, v85
	v_fmac_f32_e32 v23, v226, v86
	v_fmac_f32_e32 v23, v227, v87
	ds_read_b128 v[32:35], v4 offset:32
	ds_read_b128 v[36:39], v4 offset:4128
	ds_read_b128 v[40:43], v4 offset:8224
	ds_read_b128 v[44:47], v4 offset:12320
	s_waitcnt lgkmcnt(8)
	v_fmac_f32_e32 v24, v48, v84
	v_fmac_f32_e32 v24, v49, v85
	v_fmac_f32_e32 v24, v50, v86
	v_fmac_f32_e32 v24, v51, v87
	v_fmac_f32_e32 v25, v52, v84
	v_fmac_f32_e32 v25, v53, v85
	v_fmac_f32_e32 v25, v54, v86
	v_fmac_f32_e32 v25, v55, v87
	v_fmac_f32_e32 v26, v56, v84
	v_fmac_f32_e32 v26, v57, v85
	v_fmac_f32_e32 v26, v58, v86
	v_fmac_f32_e32 v26, v59, v87
	v_fmac_f32_e32 v27, v60, v84
	v_fmac_f32_e32 v27, v61, v85
	v_fmac_f32_e32 v27, v62, v86
	v_fmac_f32_e32 v27, v63, v87
	ds_read_b128 v[212:215], v4 offset:16416
	ds_read_b128 v[216:219], v4 offset:20512
	ds_read_b128 v[220:223], v4 offset:24608
	ds_read_b128 v[224:227], v4 offset:28704
	s_waitcnt lgkmcnt(8)
	v_fmac_f32_e32 v28, v64, v84
	v_fmac_f32_e32 v28, v65, v85
	v_fmac_f32_e32 v28, v66, v86
	v_fmac_f32_e32 v28, v67, v87
	v_fmac_f32_e32 v29, v68, v84
	v_fmac_f32_e32 v29, v69, v85
	v_fmac_f32_e32 v29, v70, v86
	v_fmac_f32_e32 v29, v71, v87
	v_fmac_f32_e32 v30, v72, v84
	v_fmac_f32_e32 v30, v73, v85
	v_fmac_f32_e32 v30, v74, v86
	v_fmac_f32_e32 v30, v75, v87
	v_fmac_f32_e32 v31, v76, v84
	v_fmac_f32_e32 v31, v77, v85
	v_fmac_f32_e32 v31, v78, v86
	v_fmac_f32_e32 v31, v79, v87
	ds_read_b128 v[48:51], v4 offset:32800
	ds_read_b128 v[52:55], v4 offset:36896
	ds_read_b128 v[56:59], v4 offset:40992
	ds_read_b128 v[60:63], v4 offset:45088
	s_waitcnt lgkmcnt(8)
	v_fmac_f32_e32 v16, v32, v88
	v_fmac_f32_e32 v16, v33, v89
	v_fmac_f32_e32 v16, v34, v90
	v_fmac_f32_e32 v16, v35, v91
	v_fmac_f32_e32 v17, v36, v88
	v_fmac_f32_e32 v17, v37, v89
	v_fmac_f32_e32 v17, v38, v90
	v_fmac_f32_e32 v17, v39, v91
	v_fmac_f32_e32 v18, v40, v88
	v_fmac_f32_e32 v18, v41, v89
	v_fmac_f32_e32 v18, v42, v90
	v_fmac_f32_e32 v18, v43, v91
	v_fmac_f32_e32 v19, v44, v88
	v_fmac_f32_e32 v19, v45, v89
	v_fmac_f32_e32 v19, v46, v90
	v_fmac_f32_e32 v19, v47, v91
	ds_read_b128 v[64:67], v4 offset:49184
	ds_read_b128 v[68:71], v4 offset:53280
	ds_read_b128 v[72:75], v4 offset:57376
	ds_read_b128 v[76:79], v4 offset:61472
	s_waitcnt lgkmcnt(8)
	v_fmac_f32_e32 v20, v212, v88
	v_fmac_f32_e32 v20, v213, v89
	v_fmac_f32_e32 v20, v214, v90
	v_fmac_f32_e32 v20, v215, v91
	v_fmac_f32_e32 v21, v216, v88
	v_fmac_f32_e32 v21, v217, v89
	v_fmac_f32_e32 v21, v218, v90
	v_fmac_f32_e32 v21, v219, v91
	v_fmac_f32_e32 v22, v220, v88
	v_fmac_f32_e32 v22, v221, v89
	v_fmac_f32_e32 v22, v222, v90
	v_fmac_f32_e32 v22, v223, v91
	v_fmac_f32_e32 v23, v224, v88
	v_fmac_f32_e32 v23, v225, v89
	v_fmac_f32_e32 v23, v226, v90
	v_fmac_f32_e32 v23, v227, v91
	ds_read_b128 v[32:35], v4 offset:48
	ds_read_b128 v[36:39], v4 offset:4144
	ds_read_b128 v[40:43], v4 offset:8240
	ds_read_b128 v[44:47], v4 offset:12336
	s_waitcnt lgkmcnt(8)
	v_fmac_f32_e32 v24, v48, v88
	v_fmac_f32_e32 v24, v49, v89
	v_fmac_f32_e32 v24, v50, v90
	v_fmac_f32_e32 v24, v51, v91
	v_fmac_f32_e32 v25, v52, v88
	v_fmac_f32_e32 v25, v53, v89
	v_fmac_f32_e32 v25, v54, v90
	v_fmac_f32_e32 v25, v55, v91
	v_fmac_f32_e32 v26, v56, v88
	v_fmac_f32_e32 v26, v57, v89
	v_fmac_f32_e32 v26, v58, v90
	v_fmac_f32_e32 v26, v59, v91
	v_fmac_f32_e32 v27, v60, v88
	v_fmac_f32_e32 v27, v61, v89
	v_fmac_f32_e32 v27, v62, v90
	v_fmac_f32_e32 v27, v63, v91
	ds_read_b128 v[212:215], v4 offset:16432
	ds_read_b128 v[216:219], v4 offset:20528
	ds_read_b128 v[220:223], v4 offset:24624
	ds_read_b128 v[224:227], v4 offset:28720
	s_waitcnt lgkmcnt(8)
; #define LAS __attribute__((address_space(3)))
; __global__ void __launch_bounds__(512, 2) mega_fwd(Args a) {
;     ...
;             for (int k = 0; k < 128; k += 16) {
;                 float wv[16];
; #pragma unroll
;                 for (int j = 0; j < 16; ++j) wv[j] = __builtin_nontemporal_load(wp + (size_t)(k + j) * 6144);
; #pragma unroll
;                 for (int jj = 0; jj < 4; ++jj)
; #pragma unroll
;                     for (int r = 0; r < 16; ++r) { const f32x4 s4 = *(const LAS f32x4*)(sl + r * 1024 + wid * 128 + k + 4 * jj);
;                         acc[r] += (s4[0] * wv[4 * jj] + s4[1] * wv[4 * jj + 1]) + (s4[2] * wv[4 * jj + 2] + s4[3] * wv[4 * jj + 3]); }
	v_fmac_f32_e32 v28, v64, v88
	v_fmac_f32_e32 v28, v65, v89
	v_fmac_f32_e32 v28, v66, v90
	v_fmac_f32_e32 v28, v67, v91
	v_fmac_f32_e32 v29, v68, v88
	v_fmac_f32_e32 v29, v69, v89
	v_fmac_f32_e32 v29, v70, v90
	v_fmac_f32_e32 v29, v71, v91
	v_fmac_f32_e32 v30, v72, v88
	v_fmac_f32_e32 v30, v73, v89
	v_fmac_f32_e32 v30, v74, v90
	v_fmac_f32_e32 v30, v75, v91
	v_fmac_f32_e32 v31, v76, v88
	v_fmac_f32_e32 v31, v77, v89
	v_fmac_f32_e32 v31, v78, v90
	v_fmac_f32_e32 v31, v79, v91
	ds_read_b128 v[48:51], v4 offset:32816
	ds_read_b128 v[52:55], v4 offset:36912
	ds_read_b128 v[56:59], v4 offset:41008
	ds_read_b128 v[60:63], v4 offset:45104
	s_waitcnt lgkmcnt(8)
	v_fmac_f32_e32 v16, v32, v92
	v_fmac_f32_e32 v16, v33, v93
	v_fmac_f32_e32 v16, v34, v94
	v_fmac_f32_e32 v16, v35, v95
	v_fmac_f32_e32 v17, v36, v92
	v_fmac_f32_e32 v17, v37, v93
	v_fmac_f32_e32 v17, v38, v94
	v_fmac_f32_e32 v17, v39, v95
	v_fmac_f32_e32 v18, v40, v92
	v_fmac_f32_e32 v18, v41, v93
	v_fmac_f32_e32 v18, v42, v94
	v_fmac_f32_e32 v18, v43, v95
	v_fmac_f32_e32 v19, v44, v92
	v_fmac_f32_e32 v19, v45, v93
	v_fmac_f32_e32 v19, v46, v94
	v_fmac_f32_e32 v19, v47, v95
	ds_read_b128 v[64:67], v4 offset:49200
	ds_read_b128 v[68:71], v4 offset:53296
	ds_read_b128 v[72:75], v4 offset:57392
	ds_read_b128 v[76:79], v4 offset:61488
	s_waitcnt lgkmcnt(8)
	v_fmac_f32_e32 v20, v212, v92
	v_fmac_f32_e32 v20, v213, v93
	v_fmac_f32_e32 v20, v214, v94
	v_fmac_f32_e32 v20, v215, v95
	v_fmac_f32_e32 v21, v216, v92
	v_fmac_f32_e32 v21, v217, v93
	v_fmac_f32_e32 v21, v218, v94
	v_fmac_f32_e32 v21, v219, v95
	v_fmac_f32_e32 v22, v220, v92
	v_fmac_f32_e32 v22, v221, v93
	v_fmac_f32_e32 v22, v222, v94
	v_fmac_f32_e32 v22, v223, v95
	v_fmac_f32_e32 v23, v224, v92
	v_fmac_f32_e32 v23, v225, v93
	v_fmac_f32_e32 v23, v226, v94
	v_fmac_f32_e32 v23, v227, v95
	ds_read_b128 v[32:35], v4 offset:64
	ds_read_b128 v[36:39], v4 offset:4160
	ds_read_b128 v[40:43], v4 offset:8256
	ds_read_b128 v[44:47], v4 offset:12352
	s_waitcnt lgkmcnt(8)
	v_fmac_f32_e32 v24, v48, v92
	v_fmac_f32_e32 v24, v49, v93
	v_fmac_f32_e32 v24, v50, v94
	v_fmac_f32_e32 v24, v51, v95
	v_fmac_f32_e32 v25, v52, v92
	v_fmac_f32_e32 v25, v53, v93
	v_fmac_f32_e32 v25, v54, v94
	v_fmac_f32_e32 v25, v55, v95
	v_fmac_f32_e32 v26, v56, v92
	v_fmac_f32_e32 v26, v57, v93
	v_fmac_f32_e32 v26, v58, v94
	v_fmac_f32_e32 v26, v59, v95
	v_fmac_f32_e32 v27, v60, v92
	v_fmac_f32_e32 v27, v61, v93
	v_fmac_f32_e32 v27, v62, v94
	v_fmac_f32_e32 v27, v63, v95
	ds_read_b128 v[212:215], v4 offset:16448
	ds_read_b128 v[216:219], v4 offset:20544
	ds_read_b128 v[220:223], v4 offset:24640
	ds_read_b128 v[224:227], v4 offset:28736
	s_waitcnt lgkmcnt(8)
	v_fmac_f32_e32 v28, v64, v92
	v_fmac_f32_e32 v28, v65, v93
	v_fmac_f32_e32 v28, v66, v94
	v_fmac_f32_e32 v28, v67, v95
	v_fmac_f32_e32 v29, v68, v92
	v_fmac_f32_e32 v29, v69, v93
	v_fmac_f32_e32 v29, v70, v94
	v_fmac_f32_e32 v29, v71, v95
	v_fmac_f32_e32 v30, v72, v92
	v_fmac_f32_e32 v30, v73, v93
	v_fmac_f32_e32 v30, v74, v94
	v_fmac_f32_e32 v30, v75, v95
	v_fmac_f32_e32 v31, v76, v92
	v_fmac_f32_e32 v31, v77, v93
	v_fmac_f32_e32 v31, v78, v94
	v_fmac_f32_e32 v31, v79, v95
	ds_read_b128 v[48:51], v4 offset:32832
	ds_read_b128 v[52:55], v4 offset:36928
	ds_read_b128 v[56:59], v4 offset:41024
	ds_read_b128 v[60:63], v4 offset:45120
	s_waitcnt lgkmcnt(8)
	v_fmac_f32_e32 v16, v32, v96
	v_fmac_f32_e32 v16, v33, v97
	v_fmac_f32_e32 v16, v34, v98
	v_fmac_f32_e32 v16, v35, v99
	v_fmac_f32_e32 v17, v36, v96
	v_fmac_f32_e32 v17, v37, v97
	v_fmac_f32_e32 v17, v38, v98
	v_fmac_f32_e32 v17, v39, v99
	v_fmac_f32_e32 v18, v40, v96
	v_fmac_f32_e32 v18, v41, v97
	v_fmac_f32_e32 v18, v42, v98
	v_fmac_f32_e32 v18, v43, v99
	v_fmac_f32_e32 v19, v44, v96
	v_fmac_f32_e32 v19, v45, v97
	v_fmac_f32_e32 v19, v46, v98
	v_fmac_f32_e32 v19, v47, v99
	ds_read_b128 v[64:67], v4 offset:49216
	ds_read_b128 v[68:71], v4 offset:53312
	ds_read_b128 v[72:75], v4 offset:57408
	ds_read_b128 v[76:79], v4 offset:61504
	s_waitcnt lgkmcnt(8)
	v_fmac_f32_e32 v20, v212, v96
	v_fmac_f32_e32 v20, v213, v97
	v_fmac_f32_e32 v20, v214, v98
	v_fmac_f32_e32 v20, v215, v99
	v_fmac_f32_e32 v21, v216, v96
	v_fmac_f32_e32 v21, v217, v97
	v_fmac_f32_e32 v21, v218, v98
	v_fmac_f32_e32 v21, v219, v99
	v_fmac_f32_e32 v22, v220, v96
	v_fmac_f32_e32 v22, v221, v97
	v_fmac_f32_e32 v22, v222, v98
	v_fmac_f32_e32 v22, v223, v99
	v_fmac_f32_e32 v23, v224, v96
	v_fmac_f32_e32 v23, v225, v97
	v_fmac_f32_e32 v23, v226, v98
	v_fmac_f32_e32 v23, v227, v99
	ds_read_b128 v[32:35], v4 offset:80
	ds_read_b128 v[36:39], v4 offset:4176
	ds_read_b128 v[40:43], v4 offset:8272
	ds_read_b128 v[44:47], v4 offset:12368
	s_waitcnt lgkmcnt(8)
	v_fmac_f32_e32 v24, v48, v96
	v_fmac_f32_e32 v24, v49, v97
	v_fmac_f32_e32 v24, v50, v98
	v_fmac_f32_e32 v24, v51, v99
	v_fmac_f32_e32 v25, v52, v96
	v_fmac_f32_e32 v25, v53, v97
	v_fmac_f32_e32 v25, v54, v98
	v_fmac_f32_e32 v25, v55, v99
	v_fmac_f32_e32 v26, v56, v96
	v_fmac_f32_e32 v26, v57, v97
	v_fmac_f32_e32 v26, v58, v98
	v_fmac_f32_e32 v26, v59, v99
	v_fmac_f32_e32 v27, v60, v96
	v_fmac_f32_e32 v27, v61, v97
	v_fmac_f32_e32 v27, v62, v98
	v_fmac_f32_e32 v27, v63, v99
	ds_read_b128 v[212:215], v4 offset:16464
	ds_read_b128 v[216:219], v4 offset:20560
	ds_read_b128 v[220:223], v4 offset:24656
	ds_read_b128 v[224:227], v4 offset:28752
	s_waitcnt lgkmcnt(8)
; #define LAS __attribute__((address_space(3)))
; __global__ void __launch_bounds__(512, 2) mega_fwd(Args a) {
;     ...
;             for (int k = 0; k < 128; k += 16) {
;                 float wv[16];
; #pragma unroll
;                 for (int j = 0; j < 16; ++j) wv[j] = __builtin_nontemporal_load(wp + (size_t)(k + j) * 6144);
; #pragma unroll
;                 for (int jj = 0; jj < 4; ++jj)
; #pragma unroll
;                     for (int r = 0; r < 16; ++r) { const f32x4 s4 = *(const LAS f32x4*)(sl + r * 1024 + wid * 128 + k + 4 * jj);
;                         acc[r] += (s4[0] * wv[4 * jj] + s4[1] * wv[4 * jj + 1]) + (s4[2] * wv[4 * jj + 2] + s4[3] * wv[4 * jj + 3]); }
	v_fmac_f32_e32 v28, v64, v96
	v_fmac_f32_e32 v28, v65, v97
	v_fmac_f32_e32 v28, v66, v98
	v_fmac_f32_e32 v28, v67, v99
	v_fmac_f32_e32 v29, v68, v96
	v_fmac_f32_e32 v29, v69, v97
	v_fmac_f32_e32 v29, v70, v98
	v_fmac_f32_e32 v29, v71, v99
	v_fmac_f32_e32 v30, v72, v96
	v_fmac_f32_e32 v30, v73, v97
	v_fmac_f32_e32 v30, v74, v98
	v_fmac_f32_e32 v30, v75, v99
	v_fmac_f32_e32 v31, v76, v96
	v_fmac_f32_e32 v31, v77, v97
	v_fmac_f32_e32 v31, v78, v98
	v_fmac_f32_e32 v31, v79, v99
	ds_read_b128 v[48:51], v4 offset:32848
	ds_read_b128 v[52:55], v4 offset:36944
	ds_read_b128 v[56:59], v4 offset:41040
	ds_read_b128 v[60:63], v4 offset:45136
	s_waitcnt lgkmcnt(8)
	v_fmac_f32_e32 v16, v32, v100
	v_fmac_f32_e32 v16, v33, v101
	v_fmac_f32_e32 v16, v34, v102
	v_fmac_f32_e32 v16, v35, v103
	v_fmac_f32_e32 v17, v36, v100
	v_fmac_f32_e32 v17, v37, v101
	v_fmac_f32_e32 v17, v38, v102
	v_fmac_f32_e32 v17, v39, v103
	v_fmac_f32_e32 v18, v40, v100
	v_fmac_f32_e32 v18, v41, v101
	v_fmac_f32_e32 v18, v42, v102
	v_fmac_f32_e32 v18, v43, v103
	v_fmac_f32_e32 v19, v44, v100
	v_fmac_f32_e32 v19, v45, v101
	v_fmac_f32_e32 v19, v46, v102
	v_fmac_f32_e32 v19, v47, v103
	ds_read_b128 v[64:67], v4 offset:49232
	ds_read_b128 v[68:71], v4 offset:53328
	ds_read_b128 v[72:75], v4 offset:57424
	ds_read_b128 v[76:79], v4 offset:61520
	s_waitcnt lgkmcnt(8)
	v_fmac_f32_e32 v20, v212, v100
	v_fmac_f32_e32 v20, v213, v101
	v_fmac_f32_e32 v20, v214, v102
	v_fmac_f32_e32 v20, v215, v103
	v_fmac_f32_e32 v21, v216, v100
	v_fmac_f32_e32 v21, v217, v101
	v_fmac_f32_e32 v21, v218, v102
	v_fmac_f32_e32 v21, v219, v103
	v_fmac_f32_e32 v22, v220, v100
	v_fmac_f32_e32 v22, v221, v101
	v_fmac_f32_e32 v22, v222, v102
	v_fmac_f32_e32 v22, v223, v103
	v_fmac_f32_e32 v23, v224, v100
	v_fmac_f32_e32 v23, v225, v101
	v_fmac_f32_e32 v23, v226, v102
	v_fmac_f32_e32 v23, v227, v103
	ds_read_b128 v[32:35], v4 offset:96
	ds_read_b128 v[36:39], v4 offset:4192
	ds_read_b128 v[40:43], v4 offset:8288
	ds_read_b128 v[44:47], v4 offset:12384
	s_waitcnt lgkmcnt(8)
	v_fmac_f32_e32 v24, v48, v100
	v_fmac_f32_e32 v24, v49, v101
	v_fmac_f32_e32 v24, v50, v102
	v_fmac_f32_e32 v24, v51, v103
	v_fmac_f32_e32 v25, v52, v100
	v_fmac_f32_e32 v25, v53, v101
	v_fmac_f32_e32 v25, v54, v102
	v_fmac_f32_e32 v25, v55, v103
	v_fmac_f32_e32 v26, v56, v100
	v_fmac_f32_e32 v26, v57, v101
	v_fmac_f32_e32 v26, v58, v102
	v_fmac_f32_e32 v26, v59, v103
	v_fmac_f32_e32 v27, v60, v100
	v_fmac_f32_e32 v27, v61, v101
	v_fmac_f32_e32 v27, v62, v102
	v_fmac_f32_e32 v27, v63, v103
	ds_read_b128 v[212:215], v4 offset:16480
	ds_read_b128 v[216:219], v4 offset:20576
	ds_read_b128 v[220:223], v4 offset:24672
	ds_read_b128 v[224:227], v4 offset:28768
	s_waitcnt lgkmcnt(8)
	v_fmac_f32_e32 v28, v64, v100
	v_fmac_f32_e32 v28, v65, v101
	v_fmac_f32_e32 v28, v66, v102
	v_fmac_f32_e32 v28, v67, v103
	v_fmac_f32_e32 v29, v68, v100
	v_fmac_f32_e32 v29, v69, v101
	v_fmac_f32_e32 v29, v70, v102
	v_fmac_f32_e32 v29, v71, v103
	v_fmac_f32_e32 v30, v72, v100
	v_fmac_f32_e32 v30, v73, v101
	v_fmac_f32_e32 v30, v74, v102
	v_fmac_f32_e32 v30, v75, v103
	v_fmac_f32_e32 v31, v76, v100
	v_fmac_f32_e32 v31, v77, v101
	v_fmac_f32_e32 v31, v78, v102
	v_fmac_f32_e32 v31, v79, v103
	ds_read_b128 v[48:51], v4 offset:32864
	ds_read_b128 v[52:55], v4 offset:36960
	ds_read_b128 v[56:59], v4 offset:41056
	ds_read_b128 v[60:63], v4 offset:45152
	s_waitcnt lgkmcnt(8)
	v_fmac_f32_e32 v16, v32, v104
	v_fmac_f32_e32 v16, v33, v105
	v_fmac_f32_e32 v16, v34, v106
	v_fmac_f32_e32 v16, v35, v107
	v_fmac_f32_e32 v17, v36, v104
	v_fmac_f32_e32 v17, v37, v105
	v_fmac_f32_e32 v17, v38, v106
	v_fmac_f32_e32 v17, v39, v107
	v_fmac_f32_e32 v18, v40, v104
	v_fmac_f32_e32 v18, v41, v105
	v_fmac_f32_e32 v18, v42, v106
	v_fmac_f32_e32 v18, v43, v107
	v_fmac_f32_e32 v19, v44, v104
	v_fmac_f32_e32 v19, v45, v105
	v_fmac_f32_e32 v19, v46, v106
	v_fmac_f32_e32 v19, v47, v107
	ds_read_b128 v[64:67], v4 offset:49248
	ds_read_b128 v[68:71], v4 offset:53344
	ds_read_b128 v[72:75], v4 offset:57440
	ds_read_b128 v[76:79], v4 offset:61536
	s_waitcnt lgkmcnt(8)
	v_fmac_f32_e32 v20, v212, v104
	v_fmac_f32_e32 v20, v213, v105
	v_fmac_f32_e32 v20, v214, v106
	v_fmac_f32_e32 v20, v215, v107
	v_fmac_f32_e32 v21, v216, v104
	v_fmac_f32_e32 v21, v217, v105
	v_fmac_f32_e32 v21, v218, v106
	v_fmac_f32_e32 v21, v219, v107
	v_fmac_f32_e32 v22, v220, v104
	v_fmac_f32_e32 v22, v221, v105
	v_fmac_f32_e32 v22, v222, v106
	v_fmac_f32_e32 v22, v223, v107
	v_fmac_f32_e32 v23, v224, v104
	v_fmac_f32_e32 v23, v225, v105
	v_fmac_f32_e32 v23, v226, v106
	v_fmac_f32_e32 v23, v227, v107
	ds_read_b128 v[32:35], v4 offset:112
	ds_read_b128 v[36:39], v4 offset:4208
	ds_read_b128 v[40:43], v4 offset:8304
	ds_read_b128 v[44:47], v4 offset:12400
	s_waitcnt lgkmcnt(8)
	v_fmac_f32_e32 v24, v48, v104
	v_fmac_f32_e32 v24, v49, v105
	v_fmac_f32_e32 v24, v50, v106
	v_fmac_f32_e32 v24, v51, v107
	v_fmac_f32_e32 v25, v52, v104
	v_fmac_f32_e32 v25, v53, v105
	v_fmac_f32_e32 v25, v54, v106
	v_fmac_f32_e32 v25, v55, v107
	v_fmac_f32_e32 v26, v56, v104
	v_fmac_f32_e32 v26, v57, v105
	v_fmac_f32_e32 v26, v58, v106
	v_fmac_f32_e32 v26, v59, v107
	v_fmac_f32_e32 v27, v60, v104
	v_fmac_f32_e32 v27, v61, v105
	v_fmac_f32_e32 v27, v62, v106
	v_fmac_f32_e32 v27, v63, v107
	ds_read_b128 v[212:215], v4 offset:16496
	ds_read_b128 v[216:219], v4 offset:20592
	ds_read_b128 v[220:223], v4 offset:24688
	ds_read_b128 v[224:227], v4 offset:28784
	s_waitcnt lgkmcnt(8)
; #define LAS __attribute__((address_space(3)))
; __global__ void __launch_bounds__(512, 2) mega_fwd(Args a) {
;     ...
;             for (int k = 0; k < 128; k += 16) {
;                 float wv[16];
; #pragma unroll
;                 for (int j = 0; j < 16; ++j) wv[j] = __builtin_nontemporal_load(wp + (size_t)(k + j) * 6144);
; #pragma unroll
;                 for (int jj = 0; jj < 4; ++jj)
; #pragma unroll
;                     for (int r = 0; r < 16; ++r) { const f32x4 s4 = *(const LAS f32x4*)(sl + r * 1024 + wid * 128 + k + 4 * jj);
;                         acc[r] += (s4[0] * wv[4 * jj] + s4[1] * wv[4 * jj + 1]) + (s4[2] * wv[4 * jj + 2] + s4[3] * wv[4 * jj + 3]); }
	v_fmac_f32_e32 v28, v64, v104
	v_fmac_f32_e32 v28, v65, v105
	v_fmac_f32_e32 v28, v66, v106
	v_fmac_f32_e32 v28, v67, v107
	v_fmac_f32_e32 v29, v68, v104
	v_fmac_f32_e32 v29, v69, v105
	v_fmac_f32_e32 v29, v70, v106
	v_fmac_f32_e32 v29, v71, v107
	v_fmac_f32_e32 v30, v72, v104
	v_fmac_f32_e32 v30, v73, v105
	v_fmac_f32_e32 v30, v74, v106
	v_fmac_f32_e32 v30, v75, v107
	v_fmac_f32_e32 v31, v76, v104
	v_fmac_f32_e32 v31, v77, v105
	v_fmac_f32_e32 v31, v78, v106
	v_fmac_f32_e32 v31, v79, v107
	ds_read_b128 v[48:51], v4 offset:32880
	ds_read_b128 v[52:55], v4 offset:36976
	ds_read_b128 v[56:59], v4 offset:41072
	ds_read_b128 v[60:63], v4 offset:45168
	s_waitcnt lgkmcnt(8)
	v_fmac_f32_e32 v16, v32, v108
	v_fmac_f32_e32 v16, v33, v109
	v_fmac_f32_e32 v16, v34, v110
	v_fmac_f32_e32 v16, v35, v111
	v_fmac_f32_e32 v17, v36, v108
	v_fmac_f32_e32 v17, v37, v109
	v_fmac_f32_e32 v17, v38, v110
	v_fmac_f32_e32 v17, v39, v111
	v_fmac_f32_e32 v18, v40, v108
	v_fmac_f32_e32 v18, v41, v109
	v_fmac_f32_e32 v18, v42, v110
	v_fmac_f32_e32 v18, v43, v111
	v_fmac_f32_e32 v19, v44, v108
	v_fmac_f32_e32 v19, v45, v109
	v_fmac_f32_e32 v19, v46, v110
	v_fmac_f32_e32 v19, v47, v111
	ds_read_b128 v[64:67], v4 offset:49264
	ds_read_b128 v[68:71], v4 offset:53360
	ds_read_b128 v[72:75], v4 offset:57456
	ds_read_b128 v[76:79], v4 offset:61552
	s_waitcnt lgkmcnt(8)
	v_fmac_f32_e32 v20, v212, v108
	v_fmac_f32_e32 v20, v213, v109
	v_fmac_f32_e32 v20, v214, v110
	v_fmac_f32_e32 v20, v215, v111
	v_fmac_f32_e32 v21, v216, v108
	v_fmac_f32_e32 v21, v217, v109
	v_fmac_f32_e32 v21, v218, v110
	v_fmac_f32_e32 v21, v219, v111
	v_fmac_f32_e32 v22, v220, v108
	v_fmac_f32_e32 v22, v221, v109
	v_fmac_f32_e32 v22, v222, v110
	v_fmac_f32_e32 v22, v223, v111
	v_fmac_f32_e32 v23, v224, v108
	v_fmac_f32_e32 v23, v225, v109
	v_fmac_f32_e32 v23, v226, v110
	v_fmac_f32_e32 v23, v227, v111
	ds_read_b128 v[32:35], v4 offset:128
	ds_read_b128 v[36:39], v4 offset:4224
	ds_read_b128 v[40:43], v4 offset:8320
	ds_read_b128 v[44:47], v4 offset:12416
	s_waitcnt lgkmcnt(8)
	v_fmac_f32_e32 v24, v48, v108
	v_fmac_f32_e32 v24, v49, v109
	v_fmac_f32_e32 v24, v50, v110
	v_fmac_f32_e32 v24, v51, v111
	v_fmac_f32_e32 v25, v52, v108
	v_fmac_f32_e32 v25, v53, v109
	v_fmac_f32_e32 v25, v54, v110
	v_fmac_f32_e32 v25, v55, v111
	v_fmac_f32_e32 v26, v56, v108
	v_fmac_f32_e32 v26, v57, v109
	v_fmac_f32_e32 v26, v58, v110
	v_fmac_f32_e32 v26, v59, v111
	v_fmac_f32_e32 v27, v60, v108
	v_fmac_f32_e32 v27, v61, v109
	v_fmac_f32_e32 v27, v62, v110
	v_fmac_f32_e32 v27, v63, v111
	ds_read_b128 v[212:215], v4 offset:16512
	ds_read_b128 v[216:219], v4 offset:20608
	ds_read_b128 v[220:223], v4 offset:24704
	ds_read_b128 v[224:227], v4 offset:28800
	s_waitcnt lgkmcnt(8)
	v_fmac_f32_e32 v28, v64, v108
	v_fmac_f32_e32 v28, v65, v109
	v_fmac_f32_e32 v28, v66, v110
	v_fmac_f32_e32 v28, v67, v111
	v_fmac_f32_e32 v29, v68, v108
	v_fmac_f32_e32 v29, v69, v109
	v_fmac_f32_e32 v29, v70, v110
	v_fmac_f32_e32 v29, v71, v111
	v_fmac_f32_e32 v30, v72, v108
	v_fmac_f32_e32 v30, v73, v109
	v_fmac_f32_e32 v30, v74, v110
	v_fmac_f32_e32 v30, v75, v111
	v_fmac_f32_e32 v31, v76, v108
	v_fmac_f32_e32 v31, v77, v109
	v_fmac_f32_e32 v31, v78, v110
	v_fmac_f32_e32 v31, v79, v111
	ds_read_b128 v[48:51], v4 offset:32896
	ds_read_b128 v[52:55], v4 offset:36992
	ds_read_b128 v[56:59], v4 offset:41088
	ds_read_b128 v[60:63], v4 offset:45184
	s_waitcnt vmcnt(31)
	global_load_dword v144, v3, s[42:43] nt
	s_add_u32 s42, s42, 0x6000
	s_addc_u32 s43, s43, 0
	global_load_dword v145, v3, s[42:43] nt
	s_add_u32 s42, s42, 0x6000
	s_addc_u32 s43, s43, 0
	global_load_dword v146, v3, s[42:43] nt
	s_add_u32 s42, s42, 0x6000
	s_addc_u32 s43, s43, 0
	global_load_dword v147, v3, s[42:43] nt
	s_add_u32 s42, s42, 0x6000
	s_addc_u32 s43, s43, 0
	global_load_dword v148, v3, s[42:43] nt
	s_add_u32 s42, s42, 0x6000
	s_addc_u32 s43, s43, 0
	global_load_dword v149, v3, s[42:43] nt
	s_add_u32 s42, s42, 0x6000
	s_addc_u32 s43, s43, 0
	global_load_dword v150, v3, s[42:43] nt
	s_add_u32 s42, s42, 0x6000
	s_addc_u32 s43, s43, 0
	global_load_dword v151, v3, s[42:43] nt
	s_add_u32 s42, s42, 0x6000
	s_addc_u32 s43, s43, 0
	global_load_dword v152, v3, s[42:43] nt
	s_add_u32 s42, s42, 0x6000
	s_addc_u32 s43, s43, 0
	global_load_dword v153, v3, s[42:43] nt
	s_add_u32 s42, s42, 0x6000
	s_addc_u32 s43, s43, 0
	global_load_dword v154, v3, s[42:43] nt
	s_add_u32 s42, s42, 0x6000
	s_addc_u32 s43, s43, 0
	global_load_dword v155, v3, s[42:43] nt
	s_add_u32 s42, s42, 0x6000
	s_addc_u32 s43, s43, 0
	global_load_dword v156, v3, s[42:43] nt
	s_add_u32 s42, s42, 0x6000
	s_addc_u32 s43, s43, 0
	global_load_dword v157, v3, s[42:43] nt
	s_add_u32 s42, s42, 0x6000
	s_addc_u32 s43, s43, 0
	global_load_dword v158, v3, s[42:43] nt
	s_add_u32 s42, s42, 0x6000
	s_addc_u32 s43, s43, 0
	global_load_dword v159, v3, s[42:43] nt
	s_add_u32 s42, s42, 0x6000
	s_addc_u32 s43, s43, 0
	global_load_dword v160, v3, s[42:43] nt
	s_add_u32 s42, s42, 0x6000
	s_addc_u32 s43, s43, 0
	global_load_dword v161, v3, s[42:43] nt
	s_add_u32 s42, s42, 0x6000
	s_addc_u32 s43, s43, 0
	global_load_dword v162, v3, s[42:43] nt
	s_add_u32 s42, s42, 0x6000
	s_addc_u32 s43, s43, 0
	global_load_dword v163, v3, s[42:43] nt
	s_add_u32 s42, s42, 0x6000
	s_addc_u32 s43, s43, 0
	global_load_dword v164, v3, s[42:43] nt
	s_add_u32 s42, s42, 0x6000
	s_addc_u32 s43, s43, 0
	global_load_dword v165, v3, s[42:43] nt
	s_add_u32 s42, s42, 0x6000
	s_addc_u32 s43, s43, 0
	global_load_dword v166, v3, s[42:43] nt
	s_add_u32 s42, s42, 0x6000
	s_addc_u32 s43, s43, 0
	global_load_dword v167, v3, s[42:43] nt
	s_add_u32 s42, s42, 0x6000
	s_addc_u32 s43, s43, 0
	global_load_dword v168, v3, s[42:43] nt
	s_add_u32 s42, s42, 0x6000
	s_addc_u32 s43, s43, 0
	global_load_dword v169, v3, s[42:43] nt
	s_add_u32 s42, s42, 0x6000
	s_addc_u32 s43, s43, 0
	global_load_dword v170, v3, s[42:43] nt
	s_add_u32 s42, s42, 0x6000
	s_addc_u32 s43, s43, 0
	global_load_dword v171, v3, s[42:43] nt
	s_add_u32 s42, s42, 0x6000
	s_addc_u32 s43, s43, 0
	global_load_dword v172, v3, s[42:43] nt
	s_add_u32 s42, s42, 0x6000
	s_addc_u32 s43, s43, 0
	global_load_dword v173, v3, s[42:43] nt
	s_add_u32 s42, s42, 0x6000
	s_addc_u32 s43, s43, 0
	global_load_dword v175, v3, s[42:43] nt
	s_add_u32 s42, s42, 0x6000
	s_addc_u32 s43, s43, 0
	global_load_dword v176, v3, s[42:43] nt
	s_add_u32 s42, s42, 0x6000
	s_addc_u32 s43, s43, 0
	s_waitcnt vmcnt(32)
; #define LAS __attribute__((address_space(3)))
; __global__ void __launch_bounds__(512, 2) mega_fwd(Args a) {
;     ...
;             for (int k = 0; k < 128; k += 16) {
;                 float wv[16];
; #pragma unroll
;                 for (int j = 0; j < 16; ++j) wv[j] = __builtin_nontemporal_load(wp + (size_t)(k + j) * 6144);
; #pragma unroll
;                 for (int jj = 0; jj < 4; ++jj)
; #pragma unroll
;                     for (int r = 0; r < 16; ++r) { const f32x4 s4 = *(const LAS f32x4*)(sl + r * 1024 + wid * 128 + k + 4 * jj);
;                         acc[r] += (s4[0] * wv[4 * jj] + s4[1] * wv[4 * jj + 1]) + (s4[2] * wv[4 * jj + 2] + s4[3] * wv[4 * jj + 3]); }
	s_waitcnt lgkmcnt(8)
	v_fmac_f32_e32 v16, v32, v112
	v_fmac_f32_e32 v16, v33, v113
	v_fmac_f32_e32 v16, v34, v114
	v_fmac_f32_e32 v16, v35, v115
	v_fmac_f32_e32 v17, v36, v112
	v_fmac_f32_e32 v17, v37, v113
	v_fmac_f32_e32 v17, v38, v114
	v_fmac_f32_e32 v17, v39, v115
	v_fmac_f32_e32 v18, v40, v112
	v_fmac_f32_e32 v18, v41, v113
	v_fmac_f32_e32 v18, v42, v114
	v_fmac_f32_e32 v18, v43, v115
	v_fmac_f32_e32 v19, v44, v112
	v_fmac_f32_e32 v19, v45, v113
	v_fmac_f32_e32 v19, v46, v114
	v_fmac_f32_e32 v19, v47, v115
	ds_read_b128 v[64:67], v4 offset:49280
	ds_read_b128 v[68:71], v4 offset:53376
	ds_read_b128 v[72:75], v4 offset:57472
	ds_read_b128 v[76:79], v4 offset:61568
	s_waitcnt lgkmcnt(8)
	v_fmac_f32_e32 v20, v212, v112
	v_fmac_f32_e32 v20, v213, v113
	v_fmac_f32_e32 v20, v214, v114
	v_fmac_f32_e32 v20, v215, v115
	v_fmac_f32_e32 v21, v216, v112
	v_fmac_f32_e32 v21, v217, v113
	v_fmac_f32_e32 v21, v218, v114
	v_fmac_f32_e32 v21, v219, v115
	v_fmac_f32_e32 v22, v220, v112
	v_fmac_f32_e32 v22, v221, v113
	v_fmac_f32_e32 v22, v222, v114
	v_fmac_f32_e32 v22, v223, v115
	v_fmac_f32_e32 v23, v224, v112
	v_fmac_f32_e32 v23, v225, v113
	v_fmac_f32_e32 v23, v226, v114
	v_fmac_f32_e32 v23, v227, v115
	ds_read_b128 v[32:35], v4 offset:144
	ds_read_b128 v[36:39], v4 offset:4240
	ds_read_b128 v[40:43], v4 offset:8336
	ds_read_b128 v[44:47], v4 offset:12432
	s_waitcnt lgkmcnt(8)
	v_fmac_f32_e32 v24, v48, v112
	v_fmac_f32_e32 v24, v49, v113
	v_fmac_f32_e32 v24, v50, v114
	v_fmac_f32_e32 v24, v51, v115
	v_fmac_f32_e32 v25, v52, v112
	v_fmac_f32_e32 v25, v53, v113
	v_fmac_f32_e32 v25, v54, v114
	v_fmac_f32_e32 v25, v55, v115
	v_fmac_f32_e32 v26, v56, v112
	v_fmac_f32_e32 v26, v57, v113
	v_fmac_f32_e32 v26, v58, v114
	v_fmac_f32_e32 v26, v59, v115
	v_fmac_f32_e32 v27, v60, v112
	v_fmac_f32_e32 v27, v61, v113
	v_fmac_f32_e32 v27, v62, v114
	v_fmac_f32_e32 v27, v63, v115
	ds_read_b128 v[212:215], v4 offset:16528
	ds_read_b128 v[216:219], v4 offset:20624
	ds_read_b128 v[220:223], v4 offset:24720
	ds_read_b128 v[224:227], v4 offset:28816
	s_waitcnt lgkmcnt(8)
	v_fmac_f32_e32 v28, v64, v112
	v_fmac_f32_e32 v28, v65, v113
	v_fmac_f32_e32 v28, v66, v114
	v_fmac_f32_e32 v28, v67, v115
	v_fmac_f32_e32 v29, v68, v112
	v_fmac_f32_e32 v29, v69, v113
	v_fmac_f32_e32 v29, v70, v114
	v_fmac_f32_e32 v29, v71, v115
	v_fmac_f32_e32 v30, v72, v112
	v_fmac_f32_e32 v30, v73, v113
	v_fmac_f32_e32 v30, v74, v114
	v_fmac_f32_e32 v30, v75, v115
	v_fmac_f32_e32 v31, v76, v112
	v_fmac_f32_e32 v31, v77, v113
	v_fmac_f32_e32 v31, v78, v114
	v_fmac_f32_e32 v31, v79, v115
	ds_read_b128 v[48:51], v4 offset:32912
	ds_read_b128 v[52:55], v4 offset:37008
	ds_read_b128 v[56:59], v4 offset:41104
	ds_read_b128 v[60:63], v4 offset:45200
	s_waitcnt lgkmcnt(8)
	v_fmac_f32_e32 v16, v32, v116
	v_fmac_f32_e32 v16, v33, v117
	v_fmac_f32_e32 v16, v34, v118
	v_fmac_f32_e32 v16, v35, v119
	v_fmac_f32_e32 v17, v36, v116
	v_fmac_f32_e32 v17, v37, v117
	v_fmac_f32_e32 v17, v38, v118
	v_fmac_f32_e32 v17, v39, v119
	v_fmac_f32_e32 v18, v40, v116
	v_fmac_f32_e32 v18, v41, v117
	v_fmac_f32_e32 v18, v42, v118
	v_fmac_f32_e32 v18, v43, v119
	v_fmac_f32_e32 v19, v44, v116
	v_fmac_f32_e32 v19, v45, v117
	v_fmac_f32_e32 v19, v46, v118
	v_fmac_f32_e32 v19, v47, v119
	ds_read_b128 v[64:67], v4 offset:49296
	ds_read_b128 v[68:71], v4 offset:53392
	ds_read_b128 v[72:75], v4 offset:57488
	ds_read_b128 v[76:79], v4 offset:61584
	s_waitcnt lgkmcnt(8)
	v_fmac_f32_e32 v20, v212, v116
	v_fmac_f32_e32 v20, v213, v117
	v_fmac_f32_e32 v20, v214, v118
	v_fmac_f32_e32 v20, v215, v119
	v_fmac_f32_e32 v21, v216, v116
	v_fmac_f32_e32 v21, v217, v117
	v_fmac_f32_e32 v21, v218, v118
	v_fmac_f32_e32 v21, v219, v119
	v_fmac_f32_e32 v22, v220, v116
	v_fmac_f32_e32 v22, v221, v117
	v_fmac_f32_e32 v22, v222, v118
	v_fmac_f32_e32 v22, v223, v119
	v_fmac_f32_e32 v23, v224, v116
	v_fmac_f32_e32 v23, v225, v117
	v_fmac_f32_e32 v23, v226, v118
	v_fmac_f32_e32 v23, v227, v119
	ds_read_b128 v[32:35], v4 offset:160
	ds_read_b128 v[36:39], v4 offset:4256
	ds_read_b128 v[40:43], v4 offset:8352
	ds_read_b128 v[44:47], v4 offset:12448
	s_waitcnt lgkmcnt(8)
	v_fmac_f32_e32 v24, v48, v116
	v_fmac_f32_e32 v24, v49, v117
	v_fmac_f32_e32 v24, v50, v118
	v_fmac_f32_e32 v24, v51, v119
	v_fmac_f32_e32 v25, v52, v116
	v_fmac_f32_e32 v25, v53, v117
	v_fmac_f32_e32 v25, v54, v118
	v_fmac_f32_e32 v25, v55, v119
	v_fmac_f32_e32 v26, v56, v116
	v_fmac_f32_e32 v26, v57, v117
	v_fmac_f32_e32 v26, v58, v118
	v_fmac_f32_e32 v26, v59, v119
	v_fmac_f32_e32 v27, v60, v116
	v_fmac_f32_e32 v27, v61, v117
	v_fmac_f32_e32 v27, v62, v118
	v_fmac_f32_e32 v27, v63, v119
	ds_read_b128 v[212:215], v4 offset:16544
	ds_read_b128 v[216:219], v4 offset:20640
	ds_read_b128 v[220:223], v4 offset:24736
	ds_read_b128 v[224:227], v4 offset:28832
	s_waitcnt lgkmcnt(8)
	v_fmac_f32_e32 v28, v64, v116
	v_fmac_f32_e32 v28, v65, v117
	v_fmac_f32_e32 v28, v66, v118
	v_fmac_f32_e32 v28, v67, v119
	v_fmac_f32_e32 v29, v68, v116
	v_fmac_f32_e32 v29, v69, v117
	v_fmac_f32_e32 v29, v70, v118
	v_fmac_f32_e32 v29, v71, v119
	v_fmac_f32_e32 v30, v72, v116
	v_fmac_f32_e32 v30, v73, v117
	v_fmac_f32_e32 v30, v74, v118
	v_fmac_f32_e32 v30, v75, v119
	v_fmac_f32_e32 v31, v76, v116
	v_fmac_f32_e32 v31, v77, v117
	v_fmac_f32_e32 v31, v78, v118
	v_fmac_f32_e32 v31, v79, v119
	ds_read_b128 v[48:51], v4 offset:32928
	ds_read_b128 v[52:55], v4 offset:37024
	ds_read_b128 v[56:59], v4 offset:41120
	ds_read_b128 v[60:63], v4 offset:45216
	s_waitcnt lgkmcnt(8)
; #define LAS __attribute__((address_space(3)))
; __global__ void __launch_bounds__(512, 2) mega_fwd(Args a) {
;     ...
;             for (int k = 0; k < 128; k += 16) {
;                 float wv[16];
; #pragma unroll
;                 for (int j = 0; j < 16; ++j) wv[j] = __builtin_nontemporal_load(wp + (size_t)(k + j) * 6144);
; #pragma unroll
;                 for (int jj = 0; jj < 4; ++jj)
; #pragma unroll
;                     for (int r = 0; r < 16; ++r) { const f32x4 s4 = *(const LAS f32x4*)(sl + r * 1024 + wid * 128 + k + 4 * jj);
;                         acc[r] += (s4[0] * wv[4 * jj] + s4[1] * wv[4 * jj + 1]) + (s4[2] * wv[4 * jj + 2] + s4[3] * wv[4 * jj + 3]); }
	v_fmac_f32_e32 v16, v32, v120
	v_fmac_f32_e32 v16, v33, v121
	v_fmac_f32_e32 v16, v34, v122
	v_fmac_f32_e32 v16, v35, v123
	v_fmac_f32_e32 v17, v36, v120
	v_fmac_f32_e32 v17, v37, v121
	v_fmac_f32_e32 v17, v38, v122
	v_fmac_f32_e32 v17, v39, v123
	v_fmac_f32_e32 v18, v40, v120
	v_fmac_f32_e32 v18, v41, v121
	v_fmac_f32_e32 v18, v42, v122
	v_fmac_f32_e32 v18, v43, v123
	v_fmac_f32_e32 v19, v44, v120
	v_fmac_f32_e32 v19, v45, v121
	v_fmac_f32_e32 v19, v46, v122
	v_fmac_f32_e32 v19, v47, v123
	ds_read_b128 v[64:67], v4 offset:49312
	ds_read_b128 v[68:71], v4 offset:53408
	ds_read_b128 v[72:75], v4 offset:57504
	ds_read_b128 v[76:79], v4 offset:61600
	s_waitcnt lgkmcnt(8)
	v_fmac_f32_e32 v20, v212, v120
	v_fmac_f32_e32 v20, v213, v121
	v_fmac_f32_e32 v20, v214, v122
	v_fmac_f32_e32 v20, v215, v123
	v_fmac_f32_e32 v21, v216, v120
	v_fmac_f32_e32 v21, v217, v121
	v_fmac_f32_e32 v21, v218, v122
	v_fmac_f32_e32 v21, v219, v123
	v_fmac_f32_e32 v22, v220, v120
	v_fmac_f32_e32 v22, v221, v121
	v_fmac_f32_e32 v22, v222, v122
	v_fmac_f32_e32 v22, v223, v123
	v_fmac_f32_e32 v23, v224, v120
	v_fmac_f32_e32 v23, v225, v121
	v_fmac_f32_e32 v23, v226, v122
	v_fmac_f32_e32 v23, v227, v123
	ds_read_b128 v[32:35], v4 offset:176
	ds_read_b128 v[36:39], v4 offset:4272
	ds_read_b128 v[40:43], v4 offset:8368
	ds_read_b128 v[44:47], v4 offset:12464
	s_waitcnt lgkmcnt(8)
	v_fmac_f32_e32 v24, v48, v120
	v_fmac_f32_e32 v24, v49, v121
	v_fmac_f32_e32 v24, v50, v122
	v_fmac_f32_e32 v24, v51, v123
	v_fmac_f32_e32 v25, v52, v120
	v_fmac_f32_e32 v25, v53, v121
	v_fmac_f32_e32 v25, v54, v122
	v_fmac_f32_e32 v25, v55, v123
	v_fmac_f32_e32 v26, v56, v120
	v_fmac_f32_e32 v26, v57, v121
	v_fmac_f32_e32 v26, v58, v122
	v_fmac_f32_e32 v26, v59, v123
	v_fmac_f32_e32 v27, v60, v120
	v_fmac_f32_e32 v27, v61, v121
	v_fmac_f32_e32 v27, v62, v122
	v_fmac_f32_e32 v27, v63, v123
	ds_read_b128 v[212:215], v4 offset:16560
	ds_read_b128 v[216:219], v4 offset:20656
	ds_read_b128 v[220:223], v4 offset:24752
	ds_read_b128 v[224:227], v4 offset:28848
	s_waitcnt lgkmcnt(8)
	v_fmac_f32_e32 v28, v64, v120
	v_fmac_f32_e32 v28, v65, v121
	v_fmac_f32_e32 v28, v66, v122
	v_fmac_f32_e32 v28, v67, v123
	v_fmac_f32_e32 v29, v68, v120
	v_fmac_f32_e32 v29, v69, v121
	v_fmac_f32_e32 v29, v70, v122
	v_fmac_f32_e32 v29, v71, v123
	v_fmac_f32_e32 v30, v72, v120
	v_fmac_f32_e32 v30, v73, v121
	v_fmac_f32_e32 v30, v74, v122
	v_fmac_f32_e32 v30, v75, v123
	v_fmac_f32_e32 v31, v76, v120
	v_fmac_f32_e32 v31, v77, v121
	v_fmac_f32_e32 v31, v78, v122
	v_fmac_f32_e32 v31, v79, v123
	ds_read_b128 v[48:51], v4 offset:32944
	ds_read_b128 v[52:55], v4 offset:37040
	ds_read_b128 v[56:59], v4 offset:41136
	ds_read_b128 v[60:63], v4 offset:45232
	s_waitcnt lgkmcnt(8)
	v_fmac_f32_e32 v16, v32, v124
	v_fmac_f32_e32 v16, v33, v125
	v_fmac_f32_e32 v16, v34, v126
	v_fmac_f32_e32 v16, v35, v127
	v_fmac_f32_e32 v17, v36, v124
	v_fmac_f32_e32 v17, v37, v125
	v_fmac_f32_e32 v17, v38, v126
	v_fmac_f32_e32 v17, v39, v127
	v_fmac_f32_e32 v18, v40, v124
	v_fmac_f32_e32 v18, v41, v125
	v_fmac_f32_e32 v18, v42, v126
	v_fmac_f32_e32 v18, v43, v127
	v_fmac_f32_e32 v19, v44, v124
	v_fmac_f32_e32 v19, v45, v125
	v_fmac_f32_e32 v19, v46, v126
	v_fmac_f32_e32 v19, v47, v127
	ds_read_b128 v[64:67], v4 offset:49328
	ds_read_b128 v[68:71], v4 offset:53424
	ds_read_b128 v[72:75], v4 offset:57520
	ds_read_b128 v[76:79], v4 offset:61616
	s_waitcnt lgkmcnt(8)
	v_fmac_f32_e32 v20, v212, v124
	v_fmac_f32_e32 v20, v213, v125
	v_fmac_f32_e32 v20, v214, v126
	v_fmac_f32_e32 v20, v215, v127
	v_fmac_f32_e32 v21, v216, v124
	v_fmac_f32_e32 v21, v217, v125
	v_fmac_f32_e32 v21, v218, v126
	v_fmac_f32_e32 v21, v219, v127
	v_fmac_f32_e32 v22, v220, v124
	v_fmac_f32_e32 v22, v221, v125
	v_fmac_f32_e32 v22, v222, v126
	v_fmac_f32_e32 v22, v223, v127
	v_fmac_f32_e32 v23, v224, v124
	v_fmac_f32_e32 v23, v225, v125
	v_fmac_f32_e32 v23, v226, v126
	v_fmac_f32_e32 v23, v227, v127
	ds_read_b128 v[32:35], v4 offset:192
	ds_read_b128 v[36:39], v4 offset:4288
	ds_read_b128 v[40:43], v4 offset:8384
	ds_read_b128 v[44:47], v4 offset:12480
	s_waitcnt lgkmcnt(8)
	v_fmac_f32_e32 v24, v48, v124
	v_fmac_f32_e32 v24, v49, v125
	v_fmac_f32_e32 v24, v50, v126
	v_fmac_f32_e32 v24, v51, v127
	v_fmac_f32_e32 v25, v52, v124
	v_fmac_f32_e32 v25, v53, v125
	v_fmac_f32_e32 v25, v54, v126
	v_fmac_f32_e32 v25, v55, v127
	v_fmac_f32_e32 v26, v56, v124
	v_fmac_f32_e32 v26, v57, v125
	v_fmac_f32_e32 v26, v58, v126
	v_fmac_f32_e32 v26, v59, v127
	v_fmac_f32_e32 v27, v60, v124
	v_fmac_f32_e32 v27, v61, v125
	v_fmac_f32_e32 v27, v62, v126
	v_fmac_f32_e32 v27, v63, v127
	ds_read_b128 v[212:215], v4 offset:16576
	ds_read_b128 v[216:219], v4 offset:20672
	ds_read_b128 v[220:223], v4 offset:24768
	ds_read_b128 v[224:227], v4 offset:28864
	s_waitcnt lgkmcnt(8)
	v_fmac_f32_e32 v28, v64, v124
	v_fmac_f32_e32 v28, v65, v125
	v_fmac_f32_e32 v28, v66, v126
	v_fmac_f32_e32 v28, v67, v127
	v_fmac_f32_e32 v29, v68, v124
	v_fmac_f32_e32 v29, v69, v125
	v_fmac_f32_e32 v29, v70, v126
	v_fmac_f32_e32 v29, v71, v127
	v_fmac_f32_e32 v30, v72, v124
	v_fmac_f32_e32 v30, v73, v125
	v_fmac_f32_e32 v30, v74, v126
	v_fmac_f32_e32 v30, v75, v127
	v_fmac_f32_e32 v31, v76, v124
	v_fmac_f32_e32 v31, v77, v125
	v_fmac_f32_e32 v31, v78, v126
	v_fmac_f32_e32 v31, v79, v127
	ds_read_b128 v[48:51], v4 offset:32960
	ds_read_b128 v[52:55], v4 offset:37056
	ds_read_b128 v[56:59], v4 offset:41152
	ds_read_b128 v[60:63], v4 offset:45248
	s_waitcnt lgkmcnt(8)
; #define LAS __attribute__((address_space(3)))
; __global__ void __launch_bounds__(512, 2) mega_fwd(Args a) {
;     ...
;             for (int k = 0; k < 128; k += 16) {
;                 float wv[16];
; #pragma unroll
;                 for (int j = 0; j < 16; ++j) wv[j] = __builtin_nontemporal_load(wp + (size_t)(k + j) * 6144);
; #pragma unroll
;                 for (int jj = 0; jj < 4; ++jj)
; #pragma unroll
;                     for (int r = 0; r < 16; ++r) { const f32x4 s4 = *(const LAS f32x4*)(sl + r * 1024 + wid * 128 + k + 4 * jj);
;                         acc[r] += (s4[0] * wv[4 * jj] + s4[1] * wv[4 * jj + 1]) + (s4[2] * wv[4 * jj + 2] + s4[3] * wv[4 * jj + 3]); }
	v_fmac_f32_e32 v16, v32, v128
	v_fmac_f32_e32 v16, v33, v129
	v_fmac_f32_e32 v16, v34, v130
	v_fmac_f32_e32 v16, v35, v131
	v_fmac_f32_e32 v17, v36, v128
	v_fmac_f32_e32 v17, v37, v129
	v_fmac_f32_e32 v17, v38, v130
	v_fmac_f32_e32 v17, v39, v131
	v_fmac_f32_e32 v18, v40, v128
	v_fmac_f32_e32 v18, v41, v129
	v_fmac_f32_e32 v18, v42, v130
	v_fmac_f32_e32 v18, v43, v131
	v_fmac_f32_e32 v19, v44, v128
	v_fmac_f32_e32 v19, v45, v129
	v_fmac_f32_e32 v19, v46, v130
	v_fmac_f32_e32 v19, v47, v131
	ds_read_b128 v[64:67], v4 offset:49344
	ds_read_b128 v[68:71], v4 offset:53440
	ds_read_b128 v[72:75], v4 offset:57536
	ds_read_b128 v[76:79], v4 offset:61632
	s_waitcnt lgkmcnt(8)
	v_fmac_f32_e32 v20, v212, v128
	v_fmac_f32_e32 v20, v213, v129
	v_fmac_f32_e32 v20, v214, v130
	v_fmac_f32_e32 v20, v215, v131
	v_fmac_f32_e32 v21, v216, v128
	v_fmac_f32_e32 v21, v217, v129
	v_fmac_f32_e32 v21, v218, v130
	v_fmac_f32_e32 v21, v219, v131
	v_fmac_f32_e32 v22, v220, v128
	v_fmac_f32_e32 v22, v221, v129
	v_fmac_f32_e32 v22, v222, v130
	v_fmac_f32_e32 v22, v223, v131
	v_fmac_f32_e32 v23, v224, v128
	v_fmac_f32_e32 v23, v225, v129
	v_fmac_f32_e32 v23, v226, v130
	v_fmac_f32_e32 v23, v227, v131
	ds_read_b128 v[32:35], v4 offset:208
	ds_read_b128 v[36:39], v4 offset:4304
	ds_read_b128 v[40:43], v4 offset:8400
	ds_read_b128 v[44:47], v4 offset:12496
	s_waitcnt lgkmcnt(8)
	v_fmac_f32_e32 v24, v48, v128
	v_fmac_f32_e32 v24, v49, v129
	v_fmac_f32_e32 v24, v50, v130
	v_fmac_f32_e32 v24, v51, v131
	v_fmac_f32_e32 v25, v52, v128
	v_fmac_f32_e32 v25, v53, v129
	v_fmac_f32_e32 v25, v54, v130
	v_fmac_f32_e32 v25, v55, v131
	v_fmac_f32_e32 v26, v56, v128
	v_fmac_f32_e32 v26, v57, v129
	v_fmac_f32_e32 v26, v58, v130
	v_fmac_f32_e32 v26, v59, v131
	v_fmac_f32_e32 v27, v60, v128
	v_fmac_f32_e32 v27, v61, v129
	v_fmac_f32_e32 v27, v62, v130
	v_fmac_f32_e32 v27, v63, v131
	ds_read_b128 v[212:215], v4 offset:16592
	ds_read_b128 v[216:219], v4 offset:20688
	ds_read_b128 v[220:223], v4 offset:24784
	ds_read_b128 v[224:227], v4 offset:28880
	s_waitcnt lgkmcnt(8)
	v_fmac_f32_e32 v28, v64, v128
	v_fmac_f32_e32 v28, v65, v129
	v_fmac_f32_e32 v28, v66, v130
	v_fmac_f32_e32 v28, v67, v131
	v_fmac_f32_e32 v29, v68, v128
	v_fmac_f32_e32 v29, v69, v129
	v_fmac_f32_e32 v29, v70, v130
	v_fmac_f32_e32 v29, v71, v131
	v_fmac_f32_e32 v30, v72, v128
	v_fmac_f32_e32 v30, v73, v129
	v_fmac_f32_e32 v30, v74, v130
	v_fmac_f32_e32 v30, v75, v131
	v_fmac_f32_e32 v31, v76, v128
	v_fmac_f32_e32 v31, v77, v129
	v_fmac_f32_e32 v31, v78, v130
	v_fmac_f32_e32 v31, v79, v131
	ds_read_b128 v[48:51], v4 offset:32976
	ds_read_b128 v[52:55], v4 offset:37072
	ds_read_b128 v[56:59], v4 offset:41168
	ds_read_b128 v[60:63], v4 offset:45264
	s_waitcnt lgkmcnt(8)
	v_fmac_f32_e32 v16, v32, v132
	v_fmac_f32_e32 v16, v33, v133
	v_fmac_f32_e32 v16, v34, v134
	v_fmac_f32_e32 v16, v35, v135
	v_fmac_f32_e32 v17, v36, v132
	v_fmac_f32_e32 v17, v37, v133
	v_fmac_f32_e32 v17, v38, v134
	v_fmac_f32_e32 v17, v39, v135
	v_fmac_f32_e32 v18, v40, v132
	v_fmac_f32_e32 v18, v41, v133
	v_fmac_f32_e32 v18, v42, v134
	v_fmac_f32_e32 v18, v43, v135
	v_fmac_f32_e32 v19, v44, v132
	v_fmac_f32_e32 v19, v45, v133
	v_fmac_f32_e32 v19, v46, v134
	v_fmac_f32_e32 v19, v47, v135
	ds_read_b128 v[64:67], v4 offset:49360
	ds_read_b128 v[68:71], v4 offset:53456
	ds_read_b128 v[72:75], v4 offset:57552
	ds_read_b128 v[76:79], v4 offset:61648
	s_waitcnt lgkmcnt(8)
	v_fmac_f32_e32 v20, v212, v132
	v_fmac_f32_e32 v20, v213, v133
	v_fmac_f32_e32 v20, v214, v134
	v_fmac_f32_e32 v20, v215, v135
	v_fmac_f32_e32 v21, v216, v132
	v_fmac_f32_e32 v21, v217, v133
	v_fmac_f32_e32 v21, v218, v134
	v_fmac_f32_e32 v21, v219, v135
	v_fmac_f32_e32 v22, v220, v132
	v_fmac_f32_e32 v22, v221, v133
	v_fmac_f32_e32 v22, v222, v134
	v_fmac_f32_e32 v22, v223, v135
	v_fmac_f32_e32 v23, v224, v132
	v_fmac_f32_e32 v23, v225, v133
	v_fmac_f32_e32 v23, v226, v134
	v_fmac_f32_e32 v23, v227, v135
	ds_read_b128 v[32:35], v4 offset:224
	ds_read_b128 v[36:39], v4 offset:4320
	ds_read_b128 v[40:43], v4 offset:8416
	ds_read_b128 v[44:47], v4 offset:12512
	s_waitcnt lgkmcnt(8)
	v_fmac_f32_e32 v24, v48, v132
	v_fmac_f32_e32 v24, v49, v133
	v_fmac_f32_e32 v24, v50, v134
	v_fmac_f32_e32 v24, v51, v135
	v_fmac_f32_e32 v25, v52, v132
	v_fmac_f32_e32 v25, v53, v133
	v_fmac_f32_e32 v25, v54, v134
	v_fmac_f32_e32 v25, v55, v135
	v_fmac_f32_e32 v26, v56, v132
	v_fmac_f32_e32 v26, v57, v133
	v_fmac_f32_e32 v26, v58, v134
	v_fmac_f32_e32 v26, v59, v135
	v_fmac_f32_e32 v27, v60, v132
	v_fmac_f32_e32 v27, v61, v133
	v_fmac_f32_e32 v27, v62, v134
	v_fmac_f32_e32 v27, v63, v135
	ds_read_b128 v[212:215], v4 offset:16608
	ds_read_b128 v[216:219], v4 offset:20704
	ds_read_b128 v[220:223], v4 offset:24800
	ds_read_b128 v[224:227], v4 offset:28896
	s_waitcnt lgkmcnt(8)
	v_fmac_f32_e32 v28, v64, v132
	v_fmac_f32_e32 v28, v65, v133
	v_fmac_f32_e32 v28, v66, v134
	v_fmac_f32_e32 v28, v67, v135
	v_fmac_f32_e32 v29, v68, v132
	v_fmac_f32_e32 v29, v69, v133
	v_fmac_f32_e32 v29, v70, v134
	v_fmac_f32_e32 v29, v71, v135
	v_fmac_f32_e32 v30, v72, v132
	v_fmac_f32_e32 v30, v73, v133
	v_fmac_f32_e32 v30, v74, v134
	v_fmac_f32_e32 v30, v75, v135
	v_fmac_f32_e32 v31, v76, v132
	v_fmac_f32_e32 v31, v77, v133
	v_fmac_f32_e32 v31, v78, v134
	v_fmac_f32_e32 v31, v79, v135
	ds_read_b128 v[48:51], v4 offset:32992
	ds_read_b128 v[52:55], v4 offset:37088
	ds_read_b128 v[56:59], v4 offset:41184
	ds_read_b128 v[60:63], v4 offset:45280
	s_waitcnt lgkmcnt(8)
; #define LAS __attribute__((address_space(3)))
; __global__ void __launch_bounds__(512, 2) mega_fwd(Args a) {
;     ...
;             for (int k = 0; k < 128; k += 16) {
;                 float wv[16];
; #pragma unroll
;                 for (int j = 0; j < 16; ++j) wv[j] = __builtin_nontemporal_load(wp + (size_t)(k + j) * 6144);
; #pragma unroll
;                 for (int jj = 0; jj < 4; ++jj)
; #pragma unroll
;                     for (int r = 0; r < 16; ++r) { const f32x4 s4 = *(const LAS f32x4*)(sl + r * 1024 + wid * 128 + k + 4 * jj);
;                         acc[r] += (s4[0] * wv[4 * jj] + s4[1] * wv[4 * jj + 1]) + (s4[2] * wv[4 * jj + 2] + s4[3] * wv[4 * jj + 3]); }
	v_fmac_f32_e32 v16, v32, v136
	v_fmac_f32_e32 v16, v33, v137
	v_fmac_f32_e32 v16, v34, v138
	v_fmac_f32_e32 v16, v35, v139
	v_fmac_f32_e32 v17, v36, v136
	v_fmac_f32_e32 v17, v37, v137
	v_fmac_f32_e32 v17, v38, v138
	v_fmac_f32_e32 v17, v39, v139
	v_fmac_f32_e32 v18, v40, v136
	v_fmac_f32_e32 v18, v41, v137
	v_fmac_f32_e32 v18, v42, v138
	v_fmac_f32_e32 v18, v43, v139
	v_fmac_f32_e32 v19, v44, v136
	v_fmac_f32_e32 v19, v45, v137
	v_fmac_f32_e32 v19, v46, v138
	v_fmac_f32_e32 v19, v47, v139
	ds_read_b128 v[64:67], v4 offset:49376
	ds_read_b128 v[68:71], v4 offset:53472
	ds_read_b128 v[72:75], v4 offset:57568
	ds_read_b128 v[76:79], v4 offset:61664
	s_waitcnt lgkmcnt(8)
	v_fmac_f32_e32 v20, v212, v136
	v_fmac_f32_e32 v20, v213, v137
	v_fmac_f32_e32 v20, v214, v138
	v_fmac_f32_e32 v20, v215, v139
	v_fmac_f32_e32 v21, v216, v136
	v_fmac_f32_e32 v21, v217, v137
	v_fmac_f32_e32 v21, v218, v138
	v_fmac_f32_e32 v21, v219, v139
	v_fmac_f32_e32 v22, v220, v136
	v_fmac_f32_e32 v22, v221, v137
	v_fmac_f32_e32 v22, v222, v138
	v_fmac_f32_e32 v22, v223, v139
	v_fmac_f32_e32 v23, v224, v136
	v_fmac_f32_e32 v23, v225, v137
	v_fmac_f32_e32 v23, v226, v138
	v_fmac_f32_e32 v23, v227, v139
	ds_read_b128 v[32:35], v4 offset:240
	ds_read_b128 v[36:39], v4 offset:4336
	ds_read_b128 v[40:43], v4 offset:8432
	ds_read_b128 v[44:47], v4 offset:12528
	s_waitcnt lgkmcnt(8)
	v_fmac_f32_e32 v24, v48, v136
	v_fmac_f32_e32 v24, v49, v137
	v_fmac_f32_e32 v24, v50, v138
	v_fmac_f32_e32 v24, v51, v139
	v_fmac_f32_e32 v25, v52, v136
	v_fmac_f32_e32 v25, v53, v137
	v_fmac_f32_e32 v25, v54, v138
	v_fmac_f32_e32 v25, v55, v139
	v_fmac_f32_e32 v26, v56, v136
	v_fmac_f32_e32 v26, v57, v137
	v_fmac_f32_e32 v26, v58, v138
	v_fmac_f32_e32 v26, v59, v139
	v_fmac_f32_e32 v27, v60, v136
	v_fmac_f32_e32 v27, v61, v137
	v_fmac_f32_e32 v27, v62, v138
	v_fmac_f32_e32 v27, v63, v139
	ds_read_b128 v[212:215], v4 offset:16624
	ds_read_b128 v[216:219], v4 offset:20720
	ds_read_b128 v[220:223], v4 offset:24816
	ds_read_b128 v[224:227], v4 offset:28912
	s_waitcnt lgkmcnt(8)
	v_fmac_f32_e32 v28, v64, v136
	v_fmac_f32_e32 v28, v65, v137
	v_fmac_f32_e32 v28, v66, v138
	v_fmac_f32_e32 v28, v67, v139
	v_fmac_f32_e32 v29, v68, v136
	v_fmac_f32_e32 v29, v69, v137
	v_fmac_f32_e32 v29, v70, v138
	v_fmac_f32_e32 v29, v71, v139
	v_fmac_f32_e32 v30, v72, v136
	v_fmac_f32_e32 v30, v73, v137
	v_fmac_f32_e32 v30, v74, v138
	v_fmac_f32_e32 v30, v75, v139
	v_fmac_f32_e32 v31, v76, v136
	v_fmac_f32_e32 v31, v77, v137
	v_fmac_f32_e32 v31, v78, v138
	v_fmac_f32_e32 v31, v79, v139
	ds_read_b128 v[48:51], v4 offset:33008
	ds_read_b128 v[52:55], v4 offset:37104
	ds_read_b128 v[56:59], v4 offset:41200
	ds_read_b128 v[60:63], v4 offset:45296
	s_waitcnt lgkmcnt(8)
	v_fmac_f32_e32 v16, v32, v140
	v_fmac_f32_e32 v16, v33, v141
	v_fmac_f32_e32 v16, v34, v142
	v_fmac_f32_e32 v16, v35, v143
	v_fmac_f32_e32 v17, v36, v140
	v_fmac_f32_e32 v17, v37, v141
	v_fmac_f32_e32 v17, v38, v142
	v_fmac_f32_e32 v17, v39, v143
	v_fmac_f32_e32 v18, v40, v140
	v_fmac_f32_e32 v18, v41, v141
	v_fmac_f32_e32 v18, v42, v142
	v_fmac_f32_e32 v18, v43, v143
	v_fmac_f32_e32 v19, v44, v140
	v_fmac_f32_e32 v19, v45, v141
	v_fmac_f32_e32 v19, v46, v142
	v_fmac_f32_e32 v19, v47, v143
	ds_read_b128 v[64:67], v4 offset:49392
	ds_read_b128 v[68:71], v4 offset:53488
	ds_read_b128 v[72:75], v4 offset:57584
	ds_read_b128 v[76:79], v4 offset:61680
	s_waitcnt lgkmcnt(8)
	v_fmac_f32_e32 v20, v212, v140
	v_fmac_f32_e32 v20, v213, v141
	v_fmac_f32_e32 v20, v214, v142
	v_fmac_f32_e32 v20, v215, v143
	v_fmac_f32_e32 v21, v216, v140
	v_fmac_f32_e32 v21, v217, v141
	v_fmac_f32_e32 v21, v218, v142
	v_fmac_f32_e32 v21, v219, v143
	v_fmac_f32_e32 v22, v220, v140
	v_fmac_f32_e32 v22, v221, v141
	v_fmac_f32_e32 v22, v222, v142
	v_fmac_f32_e32 v22, v223, v143
	v_fmac_f32_e32 v23, v224, v140
	v_fmac_f32_e32 v23, v225, v141
	v_fmac_f32_e32 v23, v226, v142
	v_fmac_f32_e32 v23, v227, v143
	ds_read_b128 v[32:35], v4 offset:256
	ds_read_b128 v[36:39], v4 offset:4352
	ds_read_b128 v[40:43], v4 offset:8448
	ds_read_b128 v[44:47], v4 offset:12544
	s_waitcnt lgkmcnt(8)
	v_fmac_f32_e32 v24, v48, v140
	v_fmac_f32_e32 v24, v49, v141
	v_fmac_f32_e32 v24, v50, v142
	v_fmac_f32_e32 v24, v51, v143
	v_fmac_f32_e32 v25, v52, v140
	v_fmac_f32_e32 v25, v53, v141
	v_fmac_f32_e32 v25, v54, v142
	v_fmac_f32_e32 v25, v55, v143
	v_fmac_f32_e32 v26, v56, v140
	v_fmac_f32_e32 v26, v57, v141
	v_fmac_f32_e32 v26, v58, v142
	v_fmac_f32_e32 v26, v59, v143
	v_fmac_f32_e32 v27, v60, v140
	v_fmac_f32_e32 v27, v61, v141
	v_fmac_f32_e32 v27, v62, v142
	v_fmac_f32_e32 v27, v63, v143
	ds_read_b128 v[212:215], v4 offset:16640
	ds_read_b128 v[216:219], v4 offset:20736
	ds_read_b128 v[220:223], v4 offset:24832
	ds_read_b128 v[224:227], v4 offset:28928
	s_waitcnt lgkmcnt(8)
	v_fmac_f32_e32 v28, v64, v140
	v_fmac_f32_e32 v28, v65, v141
	v_fmac_f32_e32 v28, v66, v142
	v_fmac_f32_e32 v28, v67, v143
	v_fmac_f32_e32 v29, v68, v140
	v_fmac_f32_e32 v29, v69, v141
	v_fmac_f32_e32 v29, v70, v142
	v_fmac_f32_e32 v29, v71, v143
	v_fmac_f32_e32 v30, v72, v140
	v_fmac_f32_e32 v30, v73, v141
	v_fmac_f32_e32 v30, v74, v142
	v_fmac_f32_e32 v30, v75, v143
	v_fmac_f32_e32 v31, v76, v140
	v_fmac_f32_e32 v31, v77, v141
	v_fmac_f32_e32 v31, v78, v142
	v_fmac_f32_e32 v31, v79, v143
	ds_read_b128 v[48:51], v4 offset:33024
	ds_read_b128 v[52:55], v4 offset:37120
	ds_read_b128 v[56:59], v4 offset:41216
	ds_read_b128 v[60:63], v4 offset:45312
	s_waitcnt vmcnt(31)
; #define LAS __attribute__((address_space(3)))
; __global__ void __launch_bounds__(512, 2) mega_fwd(Args a) {
;     ...
;             for (int k = 0; k < 128; k += 16) {
;                 float wv[16];
; #pragma unroll
;                 for (int j = 0; j < 16; ++j) wv[j] = __builtin_nontemporal_load(wp + (size_t)(k + j) * 6144);
; #pragma unroll
;                 for (int jj = 0; jj < 4; ++jj)
; #pragma unroll
;                     for (int r = 0; r < 16; ++r) { const f32x4 s4 = *(const LAS f32x4*)(sl + r * 1024 + wid * 128 + k + 4 * jj);
;                         acc[r] += (s4[0] * wv[4 * jj] + s4[1] * wv[4 * jj + 1]) + (s4[2] * wv[4 * jj + 2] + s4[3] * wv[4 * jj + 3]); }
	global_load_dword v177, v3, s[42:43] nt
	s_add_u32 s42, s42, 0x6000
	s_addc_u32 s43, s43, 0
	global_load_dword v178, v3, s[42:43] nt
	s_add_u32 s42, s42, 0x6000
	s_addc_u32 s43, s43, 0
	global_load_dword v179, v3, s[42:43] nt
	s_add_u32 s42, s42, 0x6000
	s_addc_u32 s43, s43, 0
	global_load_dword v180, v3, s[42:43] nt
	s_add_u32 s42, s42, 0x6000
	s_addc_u32 s43, s43, 0
	global_load_dword v181, v3, s[42:43] nt
	s_add_u32 s42, s42, 0x6000
	s_addc_u32 s43, s43, 0
	global_load_dword v182, v3, s[42:43] nt
	s_add_u32 s42, s42, 0x6000
	s_addc_u32 s43, s43, 0
	global_load_dword v183, v3, s[42:43] nt
	s_add_u32 s42, s42, 0x6000
	s_addc_u32 s43, s43, 0
	global_load_dword v184, v3, s[42:43] nt
	s_add_u32 s42, s42, 0x6000
	s_addc_u32 s43, s43, 0
	global_load_dword v185, v3, s[42:43] nt
	s_add_u32 s42, s42, 0x6000
	s_addc_u32 s43, s43, 0
	global_load_dword v186, v3, s[42:43] nt
	s_add_u32 s42, s42, 0x6000
	s_addc_u32 s43, s43, 0
	global_load_dword v187, v3, s[42:43] nt
	s_add_u32 s42, s42, 0x6000
	s_addc_u32 s43, s43, 0
	global_load_dword v188, v3, s[42:43] nt
	s_add_u32 s42, s42, 0x6000
	s_addc_u32 s43, s43, 0
	global_load_dword v189, v3, s[42:43] nt
	s_add_u32 s42, s42, 0x6000
	s_addc_u32 s43, s43, 0
	global_load_dword v190, v3, s[42:43] nt
	s_add_u32 s42, s42, 0x6000
	s_addc_u32 s43, s43, 0
	global_load_dword v191, v3, s[42:43] nt
	s_add_u32 s42, s42, 0x6000
	s_addc_u32 s43, s43, 0
	global_load_dword v192, v3, s[42:43] nt
	s_add_u32 s42, s42, 0x6000
	s_addc_u32 s43, s43, 0
	global_load_dword v193, v3, s[42:43] nt
	s_add_u32 s42, s42, 0x6000
	s_addc_u32 s43, s43, 0
	global_load_dword v194, v3, s[42:43] nt
	s_add_u32 s42, s42, 0x6000
	s_addc_u32 s43, s43, 0
	global_load_dword v195, v3, s[42:43] nt
	s_add_u32 s42, s42, 0x6000
	s_addc_u32 s43, s43, 0
	global_load_dword v196, v3, s[42:43] nt
	s_add_u32 s42, s42, 0x6000
	s_addc_u32 s43, s43, 0
	global_load_dword v197, v3, s[42:43] nt
	s_add_u32 s42, s42, 0x6000
	s_addc_u32 s43, s43, 0
	global_load_dword v198, v3, s[42:43] nt
	s_add_u32 s42, s42, 0x6000
	s_addc_u32 s43, s43, 0
	global_load_dword v199, v3, s[42:43] nt
	s_add_u32 s42, s42, 0x6000
	s_addc_u32 s43, s43, 0
	global_load_dword v200, v3, s[42:43] nt
	s_add_u32 s42, s42, 0x6000
	s_addc_u32 s43, s43, 0
	global_load_dword v201, v3, s[42:43] nt
	s_add_u32 s42, s42, 0x6000
	s_addc_u32 s43, s43, 0
	global_load_dword v202, v3, s[42:43] nt
	s_add_u32 s42, s42, 0x6000
	s_addc_u32 s43, s43, 0
	global_load_dword v203, v3, s[42:43] nt
	s_add_u32 s42, s42, 0x6000
	s_addc_u32 s43, s43, 0
	global_load_dword v204, v3, s[42:43] nt
	s_add_u32 s42, s42, 0x6000
	s_addc_u32 s43, s43, 0
	global_load_dword v205, v3, s[42:43] nt
	s_add_u32 s42, s42, 0x6000
	s_addc_u32 s43, s43, 0
	global_load_dword v206, v3, s[42:43] nt
	s_add_u32 s42, s42, 0x6000
	s_addc_u32 s43, s43, 0
	global_load_dword v207, v3, s[42:43] nt
	s_add_u32 s42, s42, 0x6000
	s_addc_u32 s43, s43, 0
	global_load_dword v208, v3, s[42:43] nt
	s_add_u32 s42, s42, 0x6000
	s_addc_u32 s43, s43, 0
	s_waitcnt vmcnt(32)
	s_waitcnt lgkmcnt(8)
	v_fmac_f32_e32 v16, v32, v144
	v_fmac_f32_e32 v16, v33, v145
	v_fmac_f32_e32 v16, v34, v146
	v_fmac_f32_e32 v16, v35, v147
	v_fmac_f32_e32 v17, v36, v144
	v_fmac_f32_e32 v17, v37, v145
	v_fmac_f32_e32 v17, v38, v146
	v_fmac_f32_e32 v17, v39, v147
	v_fmac_f32_e32 v18, v40, v144
	v_fmac_f32_e32 v18, v41, v145
	v_fmac_f32_e32 v18, v42, v146
	v_fmac_f32_e32 v18, v43, v147
	v_fmac_f32_e32 v19, v44, v144
	v_fmac_f32_e32 v19, v45, v145
	v_fmac_f32_e32 v19, v46, v146
	v_fmac_f32_e32 v19, v47, v147
	ds_read_b128 v[64:67], v4 offset:49408
	ds_read_b128 v[68:71], v4 offset:53504
	ds_read_b128 v[72:75], v4 offset:57600
	ds_read_b128 v[76:79], v4 offset:61696
	s_waitcnt lgkmcnt(8)
	v_fmac_f32_e32 v20, v212, v144
	v_fmac_f32_e32 v20, v213, v145
	v_fmac_f32_e32 v20, v214, v146
	v_fmac_f32_e32 v20, v215, v147
	v_fmac_f32_e32 v21, v216, v144
	v_fmac_f32_e32 v21, v217, v145
	v_fmac_f32_e32 v21, v218, v146
	v_fmac_f32_e32 v21, v219, v147
	v_fmac_f32_e32 v22, v220, v144
	v_fmac_f32_e32 v22, v221, v145
	v_fmac_f32_e32 v22, v222, v146
	v_fmac_f32_e32 v22, v223, v147
	v_fmac_f32_e32 v23, v224, v144
	v_fmac_f32_e32 v23, v225, v145
	v_fmac_f32_e32 v23, v226, v146
	v_fmac_f32_e32 v23, v227, v147
	ds_read_b128 v[32:35], v4 offset:272
	ds_read_b128 v[36:39], v4 offset:4368
	ds_read_b128 v[40:43], v4 offset:8464
	ds_read_b128 v[44:47], v4 offset:12560
	s_waitcnt lgkmcnt(8)
	v_fmac_f32_e32 v24, v48, v144
	v_fmac_f32_e32 v24, v49, v145
	v_fmac_f32_e32 v24, v50, v146
	v_fmac_f32_e32 v24, v51, v147
	v_fmac_f32_e32 v25, v52, v144
	v_fmac_f32_e32 v25, v53, v145
	v_fmac_f32_e32 v25, v54, v146
	v_fmac_f32_e32 v25, v55, v147
	v_fmac_f32_e32 v26, v56, v144
	v_fmac_f32_e32 v26, v57, v145
	v_fmac_f32_e32 v26, v58, v146
	v_fmac_f32_e32 v26, v59, v147
	v_fmac_f32_e32 v27, v60, v144
	v_fmac_f32_e32 v27, v61, v145
	v_fmac_f32_e32 v27, v62, v146
	v_fmac_f32_e32 v27, v63, v147
	ds_read_b128 v[212:215], v4 offset:16656
	ds_read_b128 v[216:219], v4 offset:20752
	ds_read_b128 v[220:223], v4 offset:24848
	ds_read_b128 v[224:227], v4 offset:28944
	s_waitcnt lgkmcnt(8)
	v_fmac_f32_e32 v28, v64, v144
	v_fmac_f32_e32 v28, v65, v145
	v_fmac_f32_e32 v28, v66, v146
	v_fmac_f32_e32 v28, v67, v147
	v_fmac_f32_e32 v29, v68, v144
	v_fmac_f32_e32 v29, v69, v145
	v_fmac_f32_e32 v29, v70, v146
	v_fmac_f32_e32 v29, v71, v147
	v_fmac_f32_e32 v30, v72, v144
	v_fmac_f32_e32 v30, v73, v145
	v_fmac_f32_e32 v30, v74, v146
	v_fmac_f32_e32 v30, v75, v147
	v_fmac_f32_e32 v31, v76, v144
	v_fmac_f32_e32 v31, v77, v145
	v_fmac_f32_e32 v31, v78, v146
	v_fmac_f32_e32 v31, v79, v147
	ds_read_b128 v[48:51], v4 offset:33040
	ds_read_b128 v[52:55], v4 offset:37136
	ds_read_b128 v[56:59], v4 offset:41232
	ds_read_b128 v[60:63], v4 offset:45328
	s_waitcnt lgkmcnt(8)
; #define LAS __attribute__((address_space(3)))
; __global__ void __launch_bounds__(512, 2) mega_fwd(Args a) {
;     ...
;             for (int k = 0; k < 128; k += 16) {
;                 float wv[16];
; #pragma unroll
;                 for (int j = 0; j < 16; ++j) wv[j] = __builtin_nontemporal_load(wp + (size_t)(k + j) * 6144);
; #pragma unroll
;                 for (int jj = 0; jj < 4; ++jj)
; #pragma unroll
;                     for (int r = 0; r < 16; ++r) { const f32x4 s4 = *(const LAS f32x4*)(sl + r * 1024 + wid * 128 + k + 4 * jj);
;                         acc[r] += (s4[0] * wv[4 * jj] + s4[1] * wv[4 * jj + 1]) + (s4[2] * wv[4 * jj + 2] + s4[3] * wv[4 * jj + 3]); }
	v_fmac_f32_e32 v16, v32, v148
	v_fmac_f32_e32 v16, v33, v149
	v_fmac_f32_e32 v16, v34, v150
	v_fmac_f32_e32 v16, v35, v151
	v_fmac_f32_e32 v17, v36, v148
	v_fmac_f32_e32 v17, v37, v149
	v_fmac_f32_e32 v17, v38, v150
	v_fmac_f32_e32 v17, v39, v151
	v_fmac_f32_e32 v18, v40, v148
	v_fmac_f32_e32 v18, v41, v149
	v_fmac_f32_e32 v18, v42, v150
	v_fmac_f32_e32 v18, v43, v151
	v_fmac_f32_e32 v19, v44, v148
	v_fmac_f32_e32 v19, v45, v149
	v_fmac_f32_e32 v19, v46, v150
	v_fmac_f32_e32 v19, v47, v151
	ds_read_b128 v[64:67], v4 offset:49424
	ds_read_b128 v[68:71], v4 offset:53520
	ds_read_b128 v[72:75], v4 offset:57616
	ds_read_b128 v[76:79], v4 offset:61712
	s_waitcnt lgkmcnt(8)
	v_fmac_f32_e32 v20, v212, v148
	v_fmac_f32_e32 v20, v213, v149
	v_fmac_f32_e32 v20, v214, v150
	v_fmac_f32_e32 v20, v215, v151
	v_fmac_f32_e32 v21, v216, v148
	v_fmac_f32_e32 v21, v217, v149
	v_fmac_f32_e32 v21, v218, v150
	v_fmac_f32_e32 v21, v219, v151
	v_fmac_f32_e32 v22, v220, v148
	v_fmac_f32_e32 v22, v221, v149
	v_fmac_f32_e32 v22, v222, v150
	v_fmac_f32_e32 v22, v223, v151
	v_fmac_f32_e32 v23, v224, v148
	v_fmac_f32_e32 v23, v225, v149
	v_fmac_f32_e32 v23, v226, v150
	v_fmac_f32_e32 v23, v227, v151
	ds_read_b128 v[32:35], v4 offset:288
	ds_read_b128 v[36:39], v4 offset:4384
	ds_read_b128 v[40:43], v4 offset:8480
	ds_read_b128 v[44:47], v4 offset:12576
	s_waitcnt lgkmcnt(8)
	v_fmac_f32_e32 v24, v48, v148
	v_fmac_f32_e32 v24, v49, v149
	v_fmac_f32_e32 v24, v50, v150
	v_fmac_f32_e32 v24, v51, v151
	v_fmac_f32_e32 v25, v52, v148
	v_fmac_f32_e32 v25, v53, v149
	v_fmac_f32_e32 v25, v54, v150
	v_fmac_f32_e32 v25, v55, v151
	v_fmac_f32_e32 v26, v56, v148
	v_fmac_f32_e32 v26, v57, v149
	v_fmac_f32_e32 v26, v58, v150
	v_fmac_f32_e32 v26, v59, v151
	v_fmac_f32_e32 v27, v60, v148
	v_fmac_f32_e32 v27, v61, v149
	v_fmac_f32_e32 v27, v62, v150
	v_fmac_f32_e32 v27, v63, v151
	ds_read_b128 v[212:215], v4 offset:16672
	ds_read_b128 v[216:219], v4 offset:20768
	ds_read_b128 v[220:223], v4 offset:24864
	ds_read_b128 v[224:227], v4 offset:28960
	s_waitcnt lgkmcnt(8)
	v_fmac_f32_e32 v28, v64, v148
	v_fmac_f32_e32 v28, v65, v149
	v_fmac_f32_e32 v28, v66, v150
	v_fmac_f32_e32 v28, v67, v151
	v_fmac_f32_e32 v29, v68, v148
	v_fmac_f32_e32 v29, v69, v149
	v_fmac_f32_e32 v29, v70, v150
	v_fmac_f32_e32 v29, v71, v151
	v_fmac_f32_e32 v30, v72, v148
	v_fmac_f32_e32 v30, v73, v149
	v_fmac_f32_e32 v30, v74, v150
	v_fmac_f32_e32 v30, v75, v151
	v_fmac_f32_e32 v31, v76, v148
	v_fmac_f32_e32 v31, v77, v149
	v_fmac_f32_e32 v31, v78, v150
	v_fmac_f32_e32 v31, v79, v151
	ds_read_b128 v[48:51], v4 offset:33056
	ds_read_b128 v[52:55], v4 offset:37152
	ds_read_b128 v[56:59], v4 offset:41248
	ds_read_b128 v[60:63], v4 offset:45344
	s_waitcnt lgkmcnt(8)
	v_fmac_f32_e32 v16, v32, v152
	v_fmac_f32_e32 v16, v33, v153
	v_fmac_f32_e32 v16, v34, v154
	v_fmac_f32_e32 v16, v35, v155
	v_fmac_f32_e32 v17, v36, v152
	v_fmac_f32_e32 v17, v37, v153
	v_fmac_f32_e32 v17, v38, v154
	v_fmac_f32_e32 v17, v39, v155
	v_fmac_f32_e32 v18, v40, v152
	v_fmac_f32_e32 v18, v41, v153
	v_fmac_f32_e32 v18, v42, v154
	v_fmac_f32_e32 v18, v43, v155
	v_fmac_f32_e32 v19, v44, v152
	v_fmac_f32_e32 v19, v45, v153
	v_fmac_f32_e32 v19, v46, v154
	v_fmac_f32_e32 v19, v47, v155
	ds_read_b128 v[64:67], v4 offset:49440
	ds_read_b128 v[68:71], v4 offset:53536
	ds_read_b128 v[72:75], v4 offset:57632
	ds_read_b128 v[76:79], v4 offset:61728
	s_waitcnt lgkmcnt(8)
	v_fmac_f32_e32 v20, v212, v152
	v_fmac_f32_e32 v20, v213, v153
	v_fmac_f32_e32 v20, v214, v154
	v_fmac_f32_e32 v20, v215, v155
	v_fmac_f32_e32 v21, v216, v152
	v_fmac_f32_e32 v21, v217, v153
	v_fmac_f32_e32 v21, v218, v154
	v_fmac_f32_e32 v21, v219, v155
	v_fmac_f32_e32 v22, v220, v152
	v_fmac_f32_e32 v22, v221, v153
	v_fmac_f32_e32 v22, v222, v154
	v_fmac_f32_e32 v22, v223, v155
	v_fmac_f32_e32 v23, v224, v152
	v_fmac_f32_e32 v23, v225, v153
	v_fmac_f32_e32 v23, v226, v154
	v_fmac_f32_e32 v23, v227, v155
	ds_read_b128 v[32:35], v4 offset:304
	ds_read_b128 v[36:39], v4 offset:4400
	ds_read_b128 v[40:43], v4 offset:8496
	ds_read_b128 v[44:47], v4 offset:12592
	s_waitcnt lgkmcnt(8)
	v_fmac_f32_e32 v24, v48, v152
	v_fmac_f32_e32 v24, v49, v153
	v_fmac_f32_e32 v24, v50, v154
	v_fmac_f32_e32 v24, v51, v155
	v_fmac_f32_e32 v25, v52, v152
	v_fmac_f32_e32 v25, v53, v153
	v_fmac_f32_e32 v25, v54, v154
	v_fmac_f32_e32 v25, v55, v155
	v_fmac_f32_e32 v26, v56, v152
	v_fmac_f32_e32 v26, v57, v153
	v_fmac_f32_e32 v26, v58, v154
	v_fmac_f32_e32 v26, v59, v155
	v_fmac_f32_e32 v27, v60, v152
	v_fmac_f32_e32 v27, v61, v153
	v_fmac_f32_e32 v27, v62, v154
	v_fmac_f32_e32 v27, v63, v155
	ds_read_b128 v[212:215], v4 offset:16688
	ds_read_b128 v[216:219], v4 offset:20784
	ds_read_b128 v[220:223], v4 offset:24880
	ds_read_b128 v[224:227], v4 offset:28976
	s_waitcnt lgkmcnt(8)
	v_fmac_f32_e32 v28, v64, v152
	v_fmac_f32_e32 v28, v65, v153
	v_fmac_f32_e32 v28, v66, v154
	v_fmac_f32_e32 v28, v67, v155
	v_fmac_f32_e32 v29, v68, v152
	v_fmac_f32_e32 v29, v69, v153
	v_fmac_f32_e32 v29, v70, v154
	v_fmac_f32_e32 v29, v71, v155
	v_fmac_f32_e32 v30, v72, v152
	v_fmac_f32_e32 v30, v73, v153
	v_fmac_f32_e32 v30, v74, v154
	v_fmac_f32_e32 v30, v75, v155
	v_fmac_f32_e32 v31, v76, v152
	v_fmac_f32_e32 v31, v77, v153
	v_fmac_f32_e32 v31, v78, v154
	v_fmac_f32_e32 v31, v79, v155
	ds_read_b128 v[48:51], v4 offset:33072
	ds_read_b128 v[52:55], v4 offset:37168
	ds_read_b128 v[56:59], v4 offset:41264
	ds_read_b128 v[60:63], v4 offset:45360
	s_waitcnt lgkmcnt(8)
; #define LAS __attribute__((address_space(3)))
; __global__ void __launch_bounds__(512, 2) mega_fwd(Args a) {
;     ...
;             for (int k = 0; k < 128; k += 16) {
;                 float wv[16];
; #pragma unroll
;                 for (int j = 0; j < 16; ++j) wv[j] = __builtin_nontemporal_load(wp + (size_t)(k + j) * 6144);
; #pragma unroll
;                 for (int jj = 0; jj < 4; ++jj)
; #pragma unroll
;                     for (int r = 0; r < 16; ++r) { const f32x4 s4 = *(const LAS f32x4*)(sl + r * 1024 + wid * 128 + k + 4 * jj);
;                         acc[r] += (s4[0] * wv[4 * jj] + s4[1] * wv[4 * jj + 1]) + (s4[2] * wv[4 * jj + 2] + s4[3] * wv[4 * jj + 3]); }
	v_fmac_f32_e32 v16, v32, v156
	v_fmac_f32_e32 v16, v33, v157
	v_fmac_f32_e32 v16, v34, v158
	v_fmac_f32_e32 v16, v35, v159
	v_fmac_f32_e32 v17, v36, v156
	v_fmac_f32_e32 v17, v37, v157
	v_fmac_f32_e32 v17, v38, v158
	v_fmac_f32_e32 v17, v39, v159
	v_fmac_f32_e32 v18, v40, v156
	v_fmac_f32_e32 v18, v41, v157
	v_fmac_f32_e32 v18, v42, v158
	v_fmac_f32_e32 v18, v43, v159
	v_fmac_f32_e32 v19, v44, v156
	v_fmac_f32_e32 v19, v45, v157
	v_fmac_f32_e32 v19, v46, v158
	v_fmac_f32_e32 v19, v47, v159
	ds_read_b128 v[64:67], v4 offset:49456
	ds_read_b128 v[68:71], v4 offset:53552
	ds_read_b128 v[72:75], v4 offset:57648
	ds_read_b128 v[76:79], v4 offset:61744
	s_waitcnt lgkmcnt(8)
	v_fmac_f32_e32 v20, v212, v156
	v_fmac_f32_e32 v20, v213, v157
	v_fmac_f32_e32 v20, v214, v158
	v_fmac_f32_e32 v20, v215, v159
	v_fmac_f32_e32 v21, v216, v156
	v_fmac_f32_e32 v21, v217, v157
	v_fmac_f32_e32 v21, v218, v158
	v_fmac_f32_e32 v21, v219, v159
	v_fmac_f32_e32 v22, v220, v156
	v_fmac_f32_e32 v22, v221, v157
	v_fmac_f32_e32 v22, v222, v158
	v_fmac_f32_e32 v22, v223, v159
	v_fmac_f32_e32 v23, v224, v156
	v_fmac_f32_e32 v23, v225, v157
	v_fmac_f32_e32 v23, v226, v158
	v_fmac_f32_e32 v23, v227, v159
	ds_read_b128 v[32:35], v4 offset:320
	ds_read_b128 v[36:39], v4 offset:4416
	ds_read_b128 v[40:43], v4 offset:8512
	ds_read_b128 v[44:47], v4 offset:12608
	s_waitcnt lgkmcnt(8)
	v_fmac_f32_e32 v24, v48, v156
	v_fmac_f32_e32 v24, v49, v157
	v_fmac_f32_e32 v24, v50, v158
	v_fmac_f32_e32 v24, v51, v159
	v_fmac_f32_e32 v25, v52, v156
	v_fmac_f32_e32 v25, v53, v157
	v_fmac_f32_e32 v25, v54, v158
	v_fmac_f32_e32 v25, v55, v159
	v_fmac_f32_e32 v26, v56, v156
	v_fmac_f32_e32 v26, v57, v157
	v_fmac_f32_e32 v26, v58, v158
	v_fmac_f32_e32 v26, v59, v159
	v_fmac_f32_e32 v27, v60, v156
	v_fmac_f32_e32 v27, v61, v157
	v_fmac_f32_e32 v27, v62, v158
	v_fmac_f32_e32 v27, v63, v159
	ds_read_b128 v[212:215], v4 offset:16704
	ds_read_b128 v[216:219], v4 offset:20800
	ds_read_b128 v[220:223], v4 offset:24896
	ds_read_b128 v[224:227], v4 offset:28992
	s_waitcnt lgkmcnt(8)
	v_fmac_f32_e32 v28, v64, v156
	v_fmac_f32_e32 v28, v65, v157
	v_fmac_f32_e32 v28, v66, v158
	v_fmac_f32_e32 v28, v67, v159
	v_fmac_f32_e32 v29, v68, v156
	v_fmac_f32_e32 v29, v69, v157
	v_fmac_f32_e32 v29, v70, v158
	v_fmac_f32_e32 v29, v71, v159
	v_fmac_f32_e32 v30, v72, v156
	v_fmac_f32_e32 v30, v73, v157
	v_fmac_f32_e32 v30, v74, v158
	v_fmac_f32_e32 v30, v75, v159
	v_fmac_f32_e32 v31, v76, v156
	v_fmac_f32_e32 v31, v77, v157
	v_fmac_f32_e32 v31, v78, v158
	v_fmac_f32_e32 v31, v79, v159
	ds_read_b128 v[48:51], v4 offset:33088
	ds_read_b128 v[52:55], v4 offset:37184
	ds_read_b128 v[56:59], v4 offset:41280
	ds_read_b128 v[60:63], v4 offset:45376
	s_waitcnt lgkmcnt(8)
	v_fmac_f32_e32 v16, v32, v160
	v_fmac_f32_e32 v16, v33, v161
	v_fmac_f32_e32 v16, v34, v162
	v_fmac_f32_e32 v16, v35, v163
	v_fmac_f32_e32 v17, v36, v160
	v_fmac_f32_e32 v17, v37, v161
	v_fmac_f32_e32 v17, v38, v162
	v_fmac_f32_e32 v17, v39, v163
	v_fmac_f32_e32 v18, v40, v160
	v_fmac_f32_e32 v18, v41, v161
	v_fmac_f32_e32 v18, v42, v162
	v_fmac_f32_e32 v18, v43, v163
	v_fmac_f32_e32 v19, v44, v160
	v_fmac_f32_e32 v19, v45, v161
	v_fmac_f32_e32 v19, v46, v162
	v_fmac_f32_e32 v19, v47, v163
	ds_read_b128 v[64:67], v4 offset:49472
	ds_read_b128 v[68:71], v4 offset:53568
	ds_read_b128 v[72:75], v4 offset:57664
	ds_read_b128 v[76:79], v4 offset:61760
	s_waitcnt lgkmcnt(8)
	v_fmac_f32_e32 v20, v212, v160
	v_fmac_f32_e32 v20, v213, v161
	v_fmac_f32_e32 v20, v214, v162
	v_fmac_f32_e32 v20, v215, v163
	v_fmac_f32_e32 v21, v216, v160
	v_fmac_f32_e32 v21, v217, v161
	v_fmac_f32_e32 v21, v218, v162
	v_fmac_f32_e32 v21, v219, v163
	v_fmac_f32_e32 v22, v220, v160
	v_fmac_f32_e32 v22, v221, v161
	v_fmac_f32_e32 v22, v222, v162
	v_fmac_f32_e32 v22, v223, v163
	v_fmac_f32_e32 v23, v224, v160
	v_fmac_f32_e32 v23, v225, v161
	v_fmac_f32_e32 v23, v226, v162
	v_fmac_f32_e32 v23, v227, v163
	ds_read_b128 v[32:35], v4 offset:336
	ds_read_b128 v[36:39], v4 offset:4432
	ds_read_b128 v[40:43], v4 offset:8528
	ds_read_b128 v[44:47], v4 offset:12624
	s_waitcnt lgkmcnt(8)
	v_fmac_f32_e32 v24, v48, v160
	v_fmac_f32_e32 v24, v49, v161
	v_fmac_f32_e32 v24, v50, v162
	v_fmac_f32_e32 v24, v51, v163
	v_fmac_f32_e32 v25, v52, v160
	v_fmac_f32_e32 v25, v53, v161
	v_fmac_f32_e32 v25, v54, v162
	v_fmac_f32_e32 v25, v55, v163
	v_fmac_f32_e32 v26, v56, v160
	v_fmac_f32_e32 v26, v57, v161
	v_fmac_f32_e32 v26, v58, v162
	v_fmac_f32_e32 v26, v59, v163
	v_fmac_f32_e32 v27, v60, v160
	v_fmac_f32_e32 v27, v61, v161
	v_fmac_f32_e32 v27, v62, v162
	v_fmac_f32_e32 v27, v63, v163
	ds_read_b128 v[212:215], v4 offset:16720
	ds_read_b128 v[216:219], v4 offset:20816
	ds_read_b128 v[220:223], v4 offset:24912
	ds_read_b128 v[224:227], v4 offset:29008
	s_waitcnt lgkmcnt(8)
	v_fmac_f32_e32 v28, v64, v160
	v_fmac_f32_e32 v28, v65, v161
	v_fmac_f32_e32 v28, v66, v162
	v_fmac_f32_e32 v28, v67, v163
	v_fmac_f32_e32 v29, v68, v160
	v_fmac_f32_e32 v29, v69, v161
	v_fmac_f32_e32 v29, v70, v162
	v_fmac_f32_e32 v29, v71, v163
	v_fmac_f32_e32 v30, v72, v160
	v_fmac_f32_e32 v30, v73, v161
	v_fmac_f32_e32 v30, v74, v162
	v_fmac_f32_e32 v30, v75, v163
	v_fmac_f32_e32 v31, v76, v160
	v_fmac_f32_e32 v31, v77, v161
	v_fmac_f32_e32 v31, v78, v162
	v_fmac_f32_e32 v31, v79, v163
	ds_read_b128 v[48:51], v4 offset:33104
	ds_read_b128 v[52:55], v4 offset:37200
	ds_read_b128 v[56:59], v4 offset:41296
	ds_read_b128 v[60:63], v4 offset:45392
	s_waitcnt lgkmcnt(8)
; #define LAS __attribute__((address_space(3)))
; __global__ void __launch_bounds__(512, 2) mega_fwd(Args a) {
;     ...
;             for (int k = 0; k < 128; k += 16) {
;                 float wv[16];
; #pragma unroll
;                 for (int j = 0; j < 16; ++j) wv[j] = __builtin_nontemporal_load(wp + (size_t)(k + j) * 6144);
; #pragma unroll
;                 for (int jj = 0; jj < 4; ++jj)
; #pragma unroll
;                     for (int r = 0; r < 16; ++r) { const f32x4 s4 = *(const LAS f32x4*)(sl + r * 1024 + wid * 128 + k + 4 * jj);
;                         acc[r] += (s4[0] * wv[4 * jj] + s4[1] * wv[4 * jj + 1]) + (s4[2] * wv[4 * jj + 2] + s4[3] * wv[4 * jj + 3]); }
	v_fmac_f32_e32 v16, v32, v164
	v_fmac_f32_e32 v16, v33, v165
	v_fmac_f32_e32 v16, v34, v166
	v_fmac_f32_e32 v16, v35, v167
	v_fmac_f32_e32 v17, v36, v164
	v_fmac_f32_e32 v17, v37, v165
	v_fmac_f32_e32 v17, v38, v166
	v_fmac_f32_e32 v17, v39, v167
	v_fmac_f32_e32 v18, v40, v164
	v_fmac_f32_e32 v18, v41, v165
	v_fmac_f32_e32 v18, v42, v166
	v_fmac_f32_e32 v18, v43, v167
	v_fmac_f32_e32 v19, v44, v164
	v_fmac_f32_e32 v19, v45, v165
	v_fmac_f32_e32 v19, v46, v166
	v_fmac_f32_e32 v19, v47, v167
	ds_read_b128 v[64:67], v4 offset:49488
	ds_read_b128 v[68:71], v4 offset:53584
	ds_read_b128 v[72:75], v4 offset:57680
	ds_read_b128 v[76:79], v4 offset:61776
	s_waitcnt lgkmcnt(8)
	v_fmac_f32_e32 v20, v212, v164
	v_fmac_f32_e32 v20, v213, v165
	v_fmac_f32_e32 v20, v214, v166
	v_fmac_f32_e32 v20, v215, v167
	v_fmac_f32_e32 v21, v216, v164
	v_fmac_f32_e32 v21, v217, v165
	v_fmac_f32_e32 v21, v218, v166
	v_fmac_f32_e32 v21, v219, v167
	v_fmac_f32_e32 v22, v220, v164
	v_fmac_f32_e32 v22, v221, v165
	v_fmac_f32_e32 v22, v222, v166
	v_fmac_f32_e32 v22, v223, v167
	v_fmac_f32_e32 v23, v224, v164
	v_fmac_f32_e32 v23, v225, v165
	v_fmac_f32_e32 v23, v226, v166
	v_fmac_f32_e32 v23, v227, v167
	ds_read_b128 v[32:35], v4 offset:352
	ds_read_b128 v[36:39], v4 offset:4448
	ds_read_b128 v[40:43], v4 offset:8544
	ds_read_b128 v[44:47], v4 offset:12640
	s_waitcnt lgkmcnt(8)
	v_fmac_f32_e32 v24, v48, v164
	v_fmac_f32_e32 v24, v49, v165
	v_fmac_f32_e32 v24, v50, v166
	v_fmac_f32_e32 v24, v51, v167
	v_fmac_f32_e32 v25, v52, v164
	v_fmac_f32_e32 v25, v53, v165
	v_fmac_f32_e32 v25, v54, v166
	v_fmac_f32_e32 v25, v55, v167
	v_fmac_f32_e32 v26, v56, v164
	v_fmac_f32_e32 v26, v57, v165
	v_fmac_f32_e32 v26, v58, v166
	v_fmac_f32_e32 v26, v59, v167
	v_fmac_f32_e32 v27, v60, v164
	v_fmac_f32_e32 v27, v61, v165
	v_fmac_f32_e32 v27, v62, v166
	v_fmac_f32_e32 v27, v63, v167
	ds_read_b128 v[212:215], v4 offset:16736
	ds_read_b128 v[216:219], v4 offset:20832
	ds_read_b128 v[220:223], v4 offset:24928
	ds_read_b128 v[224:227], v4 offset:29024
	s_waitcnt lgkmcnt(8)
	v_fmac_f32_e32 v28, v64, v164
	v_fmac_f32_e32 v28, v65, v165
	v_fmac_f32_e32 v28, v66, v166
	v_fmac_f32_e32 v28, v67, v167
	v_fmac_f32_e32 v29, v68, v164
	v_fmac_f32_e32 v29, v69, v165
	v_fmac_f32_e32 v29, v70, v166
	v_fmac_f32_e32 v29, v71, v167
	v_fmac_f32_e32 v30, v72, v164
	v_fmac_f32_e32 v30, v73, v165
	v_fmac_f32_e32 v30, v74, v166
	v_fmac_f32_e32 v30, v75, v167
	v_fmac_f32_e32 v31, v76, v164
	v_fmac_f32_e32 v31, v77, v165
	v_fmac_f32_e32 v31, v78, v166
	v_fmac_f32_e32 v31, v79, v167
	ds_read_b128 v[48:51], v4 offset:33120
	ds_read_b128 v[52:55], v4 offset:37216
	ds_read_b128 v[56:59], v4 offset:41312
	ds_read_b128 v[60:63], v4 offset:45408
	s_waitcnt lgkmcnt(8)
	v_fmac_f32_e32 v16, v32, v168
	v_fmac_f32_e32 v16, v33, v169
	v_fmac_f32_e32 v16, v34, v170
	v_fmac_f32_e32 v16, v35, v171
	v_fmac_f32_e32 v17, v36, v168
	v_fmac_f32_e32 v17, v37, v169
	v_fmac_f32_e32 v17, v38, v170
	v_fmac_f32_e32 v17, v39, v171
	v_fmac_f32_e32 v18, v40, v168
	v_fmac_f32_e32 v18, v41, v169
	v_fmac_f32_e32 v18, v42, v170
	v_fmac_f32_e32 v18, v43, v171
	v_fmac_f32_e32 v19, v44, v168
	v_fmac_f32_e32 v19, v45, v169
	v_fmac_f32_e32 v19, v46, v170
	v_fmac_f32_e32 v19, v47, v171
	ds_read_b128 v[64:67], v4 offset:49504
	ds_read_b128 v[68:71], v4 offset:53600
	ds_read_b128 v[72:75], v4 offset:57696
	ds_read_b128 v[76:79], v4 offset:61792
	s_waitcnt lgkmcnt(8)
	v_fmac_f32_e32 v20, v212, v168
	v_fmac_f32_e32 v20, v213, v169
	v_fmac_f32_e32 v20, v214, v170
	v_fmac_f32_e32 v20, v215, v171
	v_fmac_f32_e32 v21, v216, v168
	v_fmac_f32_e32 v21, v217, v169
	v_fmac_f32_e32 v21, v218, v170
	v_fmac_f32_e32 v21, v219, v171
	v_fmac_f32_e32 v22, v220, v168
	v_fmac_f32_e32 v22, v221, v169
	v_fmac_f32_e32 v22, v222, v170
	v_fmac_f32_e32 v22, v223, v171
	v_fmac_f32_e32 v23, v224, v168
	v_fmac_f32_e32 v23, v225, v169
	v_fmac_f32_e32 v23, v226, v170
	v_fmac_f32_e32 v23, v227, v171
	ds_read_b128 v[32:35], v4 offset:368
	ds_read_b128 v[36:39], v4 offset:4464
	ds_read_b128 v[40:43], v4 offset:8560
	ds_read_b128 v[44:47], v4 offset:12656
	s_waitcnt lgkmcnt(8)
	v_fmac_f32_e32 v24, v48, v168
	v_fmac_f32_e32 v24, v49, v169
	v_fmac_f32_e32 v24, v50, v170
	v_fmac_f32_e32 v24, v51, v171
	v_fmac_f32_e32 v25, v52, v168
	v_fmac_f32_e32 v25, v53, v169
	v_fmac_f32_e32 v25, v54, v170
	v_fmac_f32_e32 v25, v55, v171
	v_fmac_f32_e32 v26, v56, v168
	v_fmac_f32_e32 v26, v57, v169
	v_fmac_f32_e32 v26, v58, v170
	v_fmac_f32_e32 v26, v59, v171
	v_fmac_f32_e32 v27, v60, v168
	v_fmac_f32_e32 v27, v61, v169
	v_fmac_f32_e32 v27, v62, v170
	v_fmac_f32_e32 v27, v63, v171
	ds_read_b128 v[212:215], v4 offset:16752
	ds_read_b128 v[216:219], v4 offset:20848
	ds_read_b128 v[220:223], v4 offset:24944
	ds_read_b128 v[224:227], v4 offset:29040
	s_waitcnt lgkmcnt(8)
	v_fmac_f32_e32 v28, v64, v168
	v_fmac_f32_e32 v28, v65, v169
	v_fmac_f32_e32 v28, v66, v170
	v_fmac_f32_e32 v28, v67, v171
	v_fmac_f32_e32 v29, v68, v168
	v_fmac_f32_e32 v29, v69, v169
	v_fmac_f32_e32 v29, v70, v170
	v_fmac_f32_e32 v29, v71, v171
	v_fmac_f32_e32 v30, v72, v168
	v_fmac_f32_e32 v30, v73, v169
	v_fmac_f32_e32 v30, v74, v170
	v_fmac_f32_e32 v30, v75, v171
	v_fmac_f32_e32 v31, v76, v168
	v_fmac_f32_e32 v31, v77, v169
	v_fmac_f32_e32 v31, v78, v170
	v_fmac_f32_e32 v31, v79, v171
	ds_read_b128 v[48:51], v4 offset:33136
	ds_read_b128 v[52:55], v4 offset:37232
	ds_read_b128 v[56:59], v4 offset:41328
	ds_read_b128 v[60:63], v4 offset:45424
	s_waitcnt lgkmcnt(8)
; #define LAS __attribute__((address_space(3)))
; __global__ void __launch_bounds__(512, 2) mega_fwd(Args a) {
;     ...
;             for (int k = 0; k < 128; k += 16) {
;                 float wv[16];
; #pragma unroll
;                 for (int j = 0; j < 16; ++j) wv[j] = __builtin_nontemporal_load(wp + (size_t)(k + j) * 6144);
; #pragma unroll
;                 for (int jj = 0; jj < 4; ++jj)
; #pragma unroll
;                     for (int r = 0; r < 16; ++r) { const f32x4 s4 = *(const LAS f32x4*)(sl + r * 1024 + wid * 128 + k + 4 * jj);
;                         acc[r] += (s4[0] * wv[4 * jj] + s4[1] * wv[4 * jj + 1]) + (s4[2] * wv[4 * jj + 2] + s4[3] * wv[4 * jj + 3]); }
	v_fmac_f32_e32 v16, v32, v172
	v_fmac_f32_e32 v16, v33, v173
	v_fmac_f32_e32 v16, v34, v175
	v_fmac_f32_e32 v16, v35, v176
	v_fmac_f32_e32 v17, v36, v172
	v_fmac_f32_e32 v17, v37, v173
	v_fmac_f32_e32 v17, v38, v175
	v_fmac_f32_e32 v17, v39, v176
	v_fmac_f32_e32 v18, v40, v172
	v_fmac_f32_e32 v18, v41, v173
	v_fmac_f32_e32 v18, v42, v175
	v_fmac_f32_e32 v18, v43, v176
	v_fmac_f32_e32 v19, v44, v172
	v_fmac_f32_e32 v19, v45, v173
	v_fmac_f32_e32 v19, v46, v175
	v_fmac_f32_e32 v19, v47, v176
	ds_read_b128 v[64:67], v4 offset:49520
	ds_read_b128 v[68:71], v4 offset:53616
	ds_read_b128 v[72:75], v4 offset:57712
	ds_read_b128 v[76:79], v4 offset:61808
	s_waitcnt lgkmcnt(8)
	v_fmac_f32_e32 v20, v212, v172
	v_fmac_f32_e32 v20, v213, v173
	v_fmac_f32_e32 v20, v214, v175
	v_fmac_f32_e32 v20, v215, v176
	v_fmac_f32_e32 v21, v216, v172
	v_fmac_f32_e32 v21, v217, v173
	v_fmac_f32_e32 v21, v218, v175
	v_fmac_f32_e32 v21, v219, v176
	v_fmac_f32_e32 v22, v220, v172
	v_fmac_f32_e32 v22, v221, v173
	v_fmac_f32_e32 v22, v222, v175
	v_fmac_f32_e32 v22, v223, v176
	v_fmac_f32_e32 v23, v224, v172
	v_fmac_f32_e32 v23, v225, v173
	v_fmac_f32_e32 v23, v226, v175
	v_fmac_f32_e32 v23, v227, v176
	ds_read_b128 v[32:35], v4 offset:384
	ds_read_b128 v[36:39], v4 offset:4480
	ds_read_b128 v[40:43], v4 offset:8576
	ds_read_b128 v[44:47], v4 offset:12672
	s_waitcnt lgkmcnt(8)
	v_fmac_f32_e32 v24, v48, v172
	v_fmac_f32_e32 v24, v49, v173
	v_fmac_f32_e32 v24, v50, v175
	v_fmac_f32_e32 v24, v51, v176
	v_fmac_f32_e32 v25, v52, v172
	v_fmac_f32_e32 v25, v53, v173
	v_fmac_f32_e32 v25, v54, v175
	v_fmac_f32_e32 v25, v55, v176
	v_fmac_f32_e32 v26, v56, v172
	v_fmac_f32_e32 v26, v57, v173
	v_fmac_f32_e32 v26, v58, v175
	v_fmac_f32_e32 v26, v59, v176
	v_fmac_f32_e32 v27, v60, v172
	v_fmac_f32_e32 v27, v61, v173
	v_fmac_f32_e32 v27, v62, v175
	v_fmac_f32_e32 v27, v63, v176
	ds_read_b128 v[212:215], v4 offset:16768
	ds_read_b128 v[216:219], v4 offset:20864
	ds_read_b128 v[220:223], v4 offset:24960
	ds_read_b128 v[224:227], v4 offset:29056
	s_waitcnt lgkmcnt(8)
	v_fmac_f32_e32 v28, v64, v172
	v_fmac_f32_e32 v28, v65, v173
	v_fmac_f32_e32 v28, v66, v175
	v_fmac_f32_e32 v28, v67, v176
	v_fmac_f32_e32 v29, v68, v172
	v_fmac_f32_e32 v29, v69, v173
	v_fmac_f32_e32 v29, v70, v175
	v_fmac_f32_e32 v29, v71, v176
	v_fmac_f32_e32 v30, v72, v172
	v_fmac_f32_e32 v30, v73, v173
	v_fmac_f32_e32 v30, v74, v175
	v_fmac_f32_e32 v30, v75, v176
	v_fmac_f32_e32 v31, v76, v172
	v_fmac_f32_e32 v31, v77, v173
	v_fmac_f32_e32 v31, v78, v175
	v_fmac_f32_e32 v31, v79, v176
	ds_read_b128 v[48:51], v4 offset:33152
	ds_read_b128 v[52:55], v4 offset:37248
	ds_read_b128 v[56:59], v4 offset:41344
	ds_read_b128 v[60:63], v4 offset:45440
	s_waitcnt vmcnt(0)
	s_waitcnt lgkmcnt(8)
	v_fmac_f32_e32 v16, v32, v177
	v_fmac_f32_e32 v16, v33, v178
	v_fmac_f32_e32 v16, v34, v179
	v_fmac_f32_e32 v16, v35, v180
	v_fmac_f32_e32 v17, v36, v177
	v_fmac_f32_e32 v17, v37, v178
	v_fmac_f32_e32 v17, v38, v179
	v_fmac_f32_e32 v17, v39, v180
	v_fmac_f32_e32 v18, v40, v177
	v_fmac_f32_e32 v18, v41, v178
	v_fmac_f32_e32 v18, v42, v179
	v_fmac_f32_e32 v18, v43, v180
	v_fmac_f32_e32 v19, v44, v177
	v_fmac_f32_e32 v19, v45, v178
	v_fmac_f32_e32 v19, v46, v179
	v_fmac_f32_e32 v19, v47, v180
	ds_read_b128 v[64:67], v4 offset:49536
	ds_read_b128 v[68:71], v4 offset:53632
	ds_read_b128 v[72:75], v4 offset:57728
	ds_read_b128 v[76:79], v4 offset:61824
	s_waitcnt lgkmcnt(8)
	v_fmac_f32_e32 v20, v212, v177
	v_fmac_f32_e32 v20, v213, v178
	v_fmac_f32_e32 v20, v214, v179
	v_fmac_f32_e32 v20, v215, v180
	v_fmac_f32_e32 v21, v216, v177
	v_fmac_f32_e32 v21, v217, v178
	v_fmac_f32_e32 v21, v218, v179
	v_fmac_f32_e32 v21, v219, v180
	v_fmac_f32_e32 v22, v220, v177
	v_fmac_f32_e32 v22, v221, v178
	v_fmac_f32_e32 v22, v222, v179
	v_fmac_f32_e32 v22, v223, v180
	v_fmac_f32_e32 v23, v224, v177
	v_fmac_f32_e32 v23, v225, v178
	v_fmac_f32_e32 v23, v226, v179
	v_fmac_f32_e32 v23, v227, v180
	ds_read_b128 v[32:35], v4 offset:400
	ds_read_b128 v[36:39], v4 offset:4496
	ds_read_b128 v[40:43], v4 offset:8592
	ds_read_b128 v[44:47], v4 offset:12688
	s_waitcnt lgkmcnt(8)
	v_fmac_f32_e32 v24, v48, v177
	v_fmac_f32_e32 v24, v49, v178
	v_fmac_f32_e32 v24, v50, v179
	v_fmac_f32_e32 v24, v51, v180
	v_fmac_f32_e32 v25, v52, v177
	v_fmac_f32_e32 v25, v53, v178
	v_fmac_f32_e32 v25, v54, v179
	v_fmac_f32_e32 v25, v55, v180
	v_fmac_f32_e32 v26, v56, v177
	v_fmac_f32_e32 v26, v57, v178
	v_fmac_f32_e32 v26, v58, v179
	v_fmac_f32_e32 v26, v59, v180
	v_fmac_f32_e32 v27, v60, v177
	v_fmac_f32_e32 v27, v61, v178
	v_fmac_f32_e32 v27, v62, v179
	v_fmac_f32_e32 v27, v63, v180
	ds_read_b128 v[212:215], v4 offset:16784
	ds_read_b128 v[216:219], v4 offset:20880
	ds_read_b128 v[220:223], v4 offset:24976
	ds_read_b128 v[224:227], v4 offset:29072
	s_waitcnt lgkmcnt(8)
	v_fmac_f32_e32 v28, v64, v177
	v_fmac_f32_e32 v28, v65, v178
	v_fmac_f32_e32 v28, v66, v179
	v_fmac_f32_e32 v28, v67, v180
	v_fmac_f32_e32 v29, v68, v177
	v_fmac_f32_e32 v29, v69, v178
	v_fmac_f32_e32 v29, v70, v179
	v_fmac_f32_e32 v29, v71, v180
	v_fmac_f32_e32 v30, v72, v177
	v_fmac_f32_e32 v30, v73, v178
	v_fmac_f32_e32 v30, v74, v179
	v_fmac_f32_e32 v30, v75, v180
	v_fmac_f32_e32 v31, v76, v177
	v_fmac_f32_e32 v31, v77, v178
	v_fmac_f32_e32 v31, v78, v179
	v_fmac_f32_e32 v31, v79, v180
	ds_read_b128 v[48:51], v4 offset:33168
	ds_read_b128 v[52:55], v4 offset:37264
	ds_read_b128 v[56:59], v4 offset:41360
	ds_read_b128 v[60:63], v4 offset:45456
	s_waitcnt lgkmcnt(8)
; #define LAS __attribute__((address_space(3)))
; __global__ void __launch_bounds__(512, 2) mega_fwd(Args a) {
;     ...
;             for (int k = 0; k < 128; k += 16) {
;                 float wv[16];
; #pragma unroll
;                 for (int j = 0; j < 16; ++j) wv[j] = __builtin_nontemporal_load(wp + (size_t)(k + j) * 6144);
; #pragma unroll
;                 for (int jj = 0; jj < 4; ++jj)
; #pragma unroll
;                     for (int r = 0; r < 16; ++r) { const f32x4 s4 = *(const LAS f32x4*)(sl + r * 1024 + wid * 128 + k + 4 * jj);
;                         acc[r] += (s4[0] * wv[4 * jj] + s4[1] * wv[4 * jj + 1]) + (s4[2] * wv[4 * jj + 2] + s4[3] * wv[4 * jj + 3]); }
	v_fmac_f32_e32 v16, v32, v181
	v_fmac_f32_e32 v16, v33, v182
	v_fmac_f32_e32 v16, v34, v183
	v_fmac_f32_e32 v16, v35, v184
	v_fmac_f32_e32 v17, v36, v181
	v_fmac_f32_e32 v17, v37, v182
	v_fmac_f32_e32 v17, v38, v183
	v_fmac_f32_e32 v17, v39, v184
	v_fmac_f32_e32 v18, v40, v181
	v_fmac_f32_e32 v18, v41, v182
	v_fmac_f32_e32 v18, v42, v183
	v_fmac_f32_e32 v18, v43, v184
	v_fmac_f32_e32 v19, v44, v181
	v_fmac_f32_e32 v19, v45, v182
	v_fmac_f32_e32 v19, v46, v183
	v_fmac_f32_e32 v19, v47, v184
	ds_read_b128 v[64:67], v4 offset:49552
	ds_read_b128 v[68:71], v4 offset:53648
	ds_read_b128 v[72:75], v4 offset:57744
	ds_read_b128 v[76:79], v4 offset:61840
	s_waitcnt lgkmcnt(8)
	v_fmac_f32_e32 v20, v212, v181
	v_fmac_f32_e32 v20, v213, v182
	v_fmac_f32_e32 v20, v214, v183
	v_fmac_f32_e32 v20, v215, v184
	v_fmac_f32_e32 v21, v216, v181
	v_fmac_f32_e32 v21, v217, v182
	v_fmac_f32_e32 v21, v218, v183
	v_fmac_f32_e32 v21, v219, v184
	v_fmac_f32_e32 v22, v220, v181
	v_fmac_f32_e32 v22, v221, v182
	v_fmac_f32_e32 v22, v222, v183
	v_fmac_f32_e32 v22, v223, v184
	v_fmac_f32_e32 v23, v224, v181
	v_fmac_f32_e32 v23, v225, v182
	v_fmac_f32_e32 v23, v226, v183
	v_fmac_f32_e32 v23, v227, v184
	ds_read_b128 v[32:35], v4 offset:416
	ds_read_b128 v[36:39], v4 offset:4512
	ds_read_b128 v[40:43], v4 offset:8608
	ds_read_b128 v[44:47], v4 offset:12704
	s_waitcnt lgkmcnt(8)
	v_fmac_f32_e32 v24, v48, v181
	v_fmac_f32_e32 v24, v49, v182
	v_fmac_f32_e32 v24, v50, v183
	v_fmac_f32_e32 v24, v51, v184
	v_fmac_f32_e32 v25, v52, v181
	v_fmac_f32_e32 v25, v53, v182
	v_fmac_f32_e32 v25, v54, v183
	v_fmac_f32_e32 v25, v55, v184
	v_fmac_f32_e32 v26, v56, v181
	v_fmac_f32_e32 v26, v57, v182
	v_fmac_f32_e32 v26, v58, v183
	v_fmac_f32_e32 v26, v59, v184
	v_fmac_f32_e32 v27, v60, v181
	v_fmac_f32_e32 v27, v61, v182
	v_fmac_f32_e32 v27, v62, v183
	v_fmac_f32_e32 v27, v63, v184
	ds_read_b128 v[212:215], v4 offset:16800
	ds_read_b128 v[216:219], v4 offset:20896
	ds_read_b128 v[220:223], v4 offset:24992
	ds_read_b128 v[224:227], v4 offset:29088
	s_waitcnt lgkmcnt(8)
	v_fmac_f32_e32 v28, v64, v181
	v_fmac_f32_e32 v28, v65, v182
	v_fmac_f32_e32 v28, v66, v183
	v_fmac_f32_e32 v28, v67, v184
	v_fmac_f32_e32 v29, v68, v181
	v_fmac_f32_e32 v29, v69, v182
	v_fmac_f32_e32 v29, v70, v183
	v_fmac_f32_e32 v29, v71, v184
	v_fmac_f32_e32 v30, v72, v181
	v_fmac_f32_e32 v30, v73, v182
	v_fmac_f32_e32 v30, v74, v183
	v_fmac_f32_e32 v30, v75, v184
	v_fmac_f32_e32 v31, v76, v181
	v_fmac_f32_e32 v31, v77, v182
	v_fmac_f32_e32 v31, v78, v183
	v_fmac_f32_e32 v31, v79, v184
	ds_read_b128 v[48:51], v4 offset:33184
	ds_read_b128 v[52:55], v4 offset:37280
	ds_read_b128 v[56:59], v4 offset:41376
	ds_read_b128 v[60:63], v4 offset:45472
	s_waitcnt lgkmcnt(8)
	v_fmac_f32_e32 v16, v32, v185
	v_fmac_f32_e32 v16, v33, v186
	v_fmac_f32_e32 v16, v34, v187
	v_fmac_f32_e32 v16, v35, v188
	v_fmac_f32_e32 v17, v36, v185
	v_fmac_f32_e32 v17, v37, v186
	v_fmac_f32_e32 v17, v38, v187
	v_fmac_f32_e32 v17, v39, v188
	v_fmac_f32_e32 v18, v40, v185
	v_fmac_f32_e32 v18, v41, v186
	v_fmac_f32_e32 v18, v42, v187
	v_fmac_f32_e32 v18, v43, v188
	v_fmac_f32_e32 v19, v44, v185
	v_fmac_f32_e32 v19, v45, v186
	v_fmac_f32_e32 v19, v46, v187
	v_fmac_f32_e32 v19, v47, v188
	ds_read_b128 v[64:67], v4 offset:49568
	ds_read_b128 v[68:71], v4 offset:53664
	ds_read_b128 v[72:75], v4 offset:57760
	ds_read_b128 v[76:79], v4 offset:61856
	s_waitcnt lgkmcnt(8)
	v_fmac_f32_e32 v20, v212, v185
	v_fmac_f32_e32 v20, v213, v186
	v_fmac_f32_e32 v20, v214, v187
	v_fmac_f32_e32 v20, v215, v188
	v_fmac_f32_e32 v21, v216, v185
	v_fmac_f32_e32 v21, v217, v186
	v_fmac_f32_e32 v21, v218, v187
	v_fmac_f32_e32 v21, v219, v188
	v_fmac_f32_e32 v22, v220, v185
	v_fmac_f32_e32 v22, v221, v186
	v_fmac_f32_e32 v22, v222, v187
	v_fmac_f32_e32 v22, v223, v188
	v_fmac_f32_e32 v23, v224, v185
	v_fmac_f32_e32 v23, v225, v186
	v_fmac_f32_e32 v23, v226, v187
	v_fmac_f32_e32 v23, v227, v188
	ds_read_b128 v[32:35], v4 offset:432
	ds_read_b128 v[36:39], v4 offset:4528
	ds_read_b128 v[40:43], v4 offset:8624
	ds_read_b128 v[44:47], v4 offset:12720
	s_waitcnt lgkmcnt(8)
	v_fmac_f32_e32 v24, v48, v185
	v_fmac_f32_e32 v24, v49, v186
	v_fmac_f32_e32 v24, v50, v187
	v_fmac_f32_e32 v24, v51, v188
	v_fmac_f32_e32 v25, v52, v185
	v_fmac_f32_e32 v25, v53, v186
	v_fmac_f32_e32 v25, v54, v187
	v_fmac_f32_e32 v25, v55, v188
	v_fmac_f32_e32 v26, v56, v185
	v_fmac_f32_e32 v26, v57, v186
	v_fmac_f32_e32 v26, v58, v187
	v_fmac_f32_e32 v26, v59, v188
	v_fmac_f32_e32 v27, v60, v185
	v_fmac_f32_e32 v27, v61, v186
	v_fmac_f32_e32 v27, v62, v187
	v_fmac_f32_e32 v27, v63, v188
	ds_read_b128 v[212:215], v4 offset:16816
	ds_read_b128 v[216:219], v4 offset:20912
	ds_read_b128 v[220:223], v4 offset:25008
	ds_read_b128 v[224:227], v4 offset:29104
	s_waitcnt lgkmcnt(8)
	v_fmac_f32_e32 v28, v64, v185
	v_fmac_f32_e32 v28, v65, v186
	v_fmac_f32_e32 v28, v66, v187
	v_fmac_f32_e32 v28, v67, v188
	v_fmac_f32_e32 v29, v68, v185
	v_fmac_f32_e32 v29, v69, v186
	v_fmac_f32_e32 v29, v70, v187
	v_fmac_f32_e32 v29, v71, v188
	v_fmac_f32_e32 v30, v72, v185
	v_fmac_f32_e32 v30, v73, v186
	v_fmac_f32_e32 v30, v74, v187
	v_fmac_f32_e32 v30, v75, v188
	v_fmac_f32_e32 v31, v76, v185
	v_fmac_f32_e32 v31, v77, v186
	v_fmac_f32_e32 v31, v78, v187
	v_fmac_f32_e32 v31, v79, v188
	ds_read_b128 v[48:51], v4 offset:33200
	ds_read_b128 v[52:55], v4 offset:37296
	ds_read_b128 v[56:59], v4 offset:41392
	ds_read_b128 v[60:63], v4 offset:45488
	s_waitcnt lgkmcnt(8)
; #define LAS __attribute__((address_space(3)))
; __global__ void __launch_bounds__(512, 2) mega_fwd(Args a) {
;     ...
;             for (int k = 0; k < 128; k += 16) {
;                 float wv[16];
; #pragma unroll
;                 for (int j = 0; j < 16; ++j) wv[j] = __builtin_nontemporal_load(wp + (size_t)(k + j) * 6144);
; #pragma unroll
;                 for (int jj = 0; jj < 4; ++jj)
; #pragma unroll
;                     for (int r = 0; r < 16; ++r) { const f32x4 s4 = *(const LAS f32x4*)(sl + r * 1024 + wid * 128 + k + 4 * jj);
;                         acc[r] += (s4[0] * wv[4 * jj] + s4[1] * wv[4 * jj + 1]) + (s4[2] * wv[4 * jj + 2] + s4[3] * wv[4 * jj + 3]); }
	v_fmac_f32_e32 v16, v32, v189
	v_fmac_f32_e32 v16, v33, v190
	v_fmac_f32_e32 v16, v34, v191
	v_fmac_f32_e32 v16, v35, v192
	v_fmac_f32_e32 v17, v36, v189
	v_fmac_f32_e32 v17, v37, v190
	v_fmac_f32_e32 v17, v38, v191
	v_fmac_f32_e32 v17, v39, v192
	v_fmac_f32_e32 v18, v40, v189
	v_fmac_f32_e32 v18, v41, v190
	v_fmac_f32_e32 v18, v42, v191
	v_fmac_f32_e32 v18, v43, v192
	v_fmac_f32_e32 v19, v44, v189
	v_fmac_f32_e32 v19, v45, v190
	v_fmac_f32_e32 v19, v46, v191
	v_fmac_f32_e32 v19, v47, v192
	ds_read_b128 v[64:67], v4 offset:49584
	ds_read_b128 v[68:71], v4 offset:53680
	ds_read_b128 v[72:75], v4 offset:57776
	ds_read_b128 v[76:79], v4 offset:61872
	s_waitcnt lgkmcnt(8)
	v_fmac_f32_e32 v20, v212, v189
	v_fmac_f32_e32 v20, v213, v190
	v_fmac_f32_e32 v20, v214, v191
	v_fmac_f32_e32 v20, v215, v192
	v_fmac_f32_e32 v21, v216, v189
	v_fmac_f32_e32 v21, v217, v190
	v_fmac_f32_e32 v21, v218, v191
	v_fmac_f32_e32 v21, v219, v192
	v_fmac_f32_e32 v22, v220, v189
	v_fmac_f32_e32 v22, v221, v190
	v_fmac_f32_e32 v22, v222, v191
	v_fmac_f32_e32 v22, v223, v192
	v_fmac_f32_e32 v23, v224, v189
	v_fmac_f32_e32 v23, v225, v190
	v_fmac_f32_e32 v23, v226, v191
	v_fmac_f32_e32 v23, v227, v192
	ds_read_b128 v[32:35], v4 offset:448
	ds_read_b128 v[36:39], v4 offset:4544
	ds_read_b128 v[40:43], v4 offset:8640
	ds_read_b128 v[44:47], v4 offset:12736
	s_waitcnt lgkmcnt(8)
	v_fmac_f32_e32 v24, v48, v189
	v_fmac_f32_e32 v24, v49, v190
	v_fmac_f32_e32 v24, v50, v191
	v_fmac_f32_e32 v24, v51, v192
	v_fmac_f32_e32 v25, v52, v189
	v_fmac_f32_e32 v25, v53, v190
	v_fmac_f32_e32 v25, v54, v191
	v_fmac_f32_e32 v25, v55, v192
	v_fmac_f32_e32 v26, v56, v189
	v_fmac_f32_e32 v26, v57, v190
	v_fmac_f32_e32 v26, v58, v191
	v_fmac_f32_e32 v26, v59, v192
	v_fmac_f32_e32 v27, v60, v189
	v_fmac_f32_e32 v27, v61, v190
	v_fmac_f32_e32 v27, v62, v191
	v_fmac_f32_e32 v27, v63, v192
	ds_read_b128 v[212:215], v4 offset:16832
	ds_read_b128 v[216:219], v4 offset:20928
	ds_read_b128 v[220:223], v4 offset:25024
	ds_read_b128 v[224:227], v4 offset:29120
	s_waitcnt lgkmcnt(8)
	v_fmac_f32_e32 v28, v64, v189
	v_fmac_f32_e32 v28, v65, v190
	v_fmac_f32_e32 v28, v66, v191
	v_fmac_f32_e32 v28, v67, v192
	v_fmac_f32_e32 v29, v68, v189
	v_fmac_f32_e32 v29, v69, v190
	v_fmac_f32_e32 v29, v70, v191
	v_fmac_f32_e32 v29, v71, v192
	v_fmac_f32_e32 v30, v72, v189
	v_fmac_f32_e32 v30, v73, v190
	v_fmac_f32_e32 v30, v74, v191
	v_fmac_f32_e32 v30, v75, v192
	v_fmac_f32_e32 v31, v76, v189
	v_fmac_f32_e32 v31, v77, v190
	v_fmac_f32_e32 v31, v78, v191
	v_fmac_f32_e32 v31, v79, v192
	ds_read_b128 v[48:51], v4 offset:33216
	ds_read_b128 v[52:55], v4 offset:37312
	ds_read_b128 v[56:59], v4 offset:41408
	ds_read_b128 v[60:63], v4 offset:45504
	s_waitcnt lgkmcnt(8)
	v_fmac_f32_e32 v16, v32, v193
	v_fmac_f32_e32 v16, v33, v194
	v_fmac_f32_e32 v16, v34, v195
	v_fmac_f32_e32 v16, v35, v196
	v_fmac_f32_e32 v17, v36, v193
	v_fmac_f32_e32 v17, v37, v194
	v_fmac_f32_e32 v17, v38, v195
	v_fmac_f32_e32 v17, v39, v196
	v_fmac_f32_e32 v18, v40, v193
	v_fmac_f32_e32 v18, v41, v194
	v_fmac_f32_e32 v18, v42, v195
	v_fmac_f32_e32 v18, v43, v196
	v_fmac_f32_e32 v19, v44, v193
	v_fmac_f32_e32 v19, v45, v194
	v_fmac_f32_e32 v19, v46, v195
	v_fmac_f32_e32 v19, v47, v196
	ds_read_b128 v[64:67], v4 offset:49600
	ds_read_b128 v[68:71], v4 offset:53696
	ds_read_b128 v[72:75], v4 offset:57792
	ds_read_b128 v[76:79], v4 offset:61888
	s_waitcnt lgkmcnt(8)
	v_fmac_f32_e32 v20, v212, v193
	v_fmac_f32_e32 v20, v213, v194
	v_fmac_f32_e32 v20, v214, v195
	v_fmac_f32_e32 v20, v215, v196
	v_fmac_f32_e32 v21, v216, v193
	v_fmac_f32_e32 v21, v217, v194
	v_fmac_f32_e32 v21, v218, v195
	v_fmac_f32_e32 v21, v219, v196
	v_fmac_f32_e32 v22, v220, v193
	v_fmac_f32_e32 v22, v221, v194
	v_fmac_f32_e32 v22, v222, v195
	v_fmac_f32_e32 v22, v223, v196
	v_fmac_f32_e32 v23, v224, v193
	v_fmac_f32_e32 v23, v225, v194
	v_fmac_f32_e32 v23, v226, v195
	v_fmac_f32_e32 v23, v227, v196
	ds_read_b128 v[32:35], v4 offset:464
	ds_read_b128 v[36:39], v4 offset:4560
	ds_read_b128 v[40:43], v4 offset:8656
	ds_read_b128 v[44:47], v4 offset:12752
	s_waitcnt lgkmcnt(8)
	v_fmac_f32_e32 v24, v48, v193
	v_fmac_f32_e32 v24, v49, v194
	v_fmac_f32_e32 v24, v50, v195
	v_fmac_f32_e32 v24, v51, v196
	v_fmac_f32_e32 v25, v52, v193
	v_fmac_f32_e32 v25, v53, v194
	v_fmac_f32_e32 v25, v54, v195
	v_fmac_f32_e32 v25, v55, v196
	v_fmac_f32_e32 v26, v56, v193
	v_fmac_f32_e32 v26, v57, v194
	v_fmac_f32_e32 v26, v58, v195
	v_fmac_f32_e32 v26, v59, v196
	v_fmac_f32_e32 v27, v60, v193
	v_fmac_f32_e32 v27, v61, v194
	v_fmac_f32_e32 v27, v62, v195
	v_fmac_f32_e32 v27, v63, v196
	ds_read_b128 v[212:215], v4 offset:16848
	ds_read_b128 v[216:219], v4 offset:20944
	ds_read_b128 v[220:223], v4 offset:25040
	ds_read_b128 v[224:227], v4 offset:29136
	s_waitcnt lgkmcnt(8)
	v_fmac_f32_e32 v28, v64, v193
	v_fmac_f32_e32 v28, v65, v194
	v_fmac_f32_e32 v28, v66, v195
	v_fmac_f32_e32 v28, v67, v196
	v_fmac_f32_e32 v29, v68, v193
	v_fmac_f32_e32 v29, v69, v194
	v_fmac_f32_e32 v29, v70, v195
	v_fmac_f32_e32 v29, v71, v196
	v_fmac_f32_e32 v30, v72, v193
	v_fmac_f32_e32 v30, v73, v194
	v_fmac_f32_e32 v30, v74, v195
	v_fmac_f32_e32 v30, v75, v196
	v_fmac_f32_e32 v31, v76, v193
	v_fmac_f32_e32 v31, v77, v194
	v_fmac_f32_e32 v31, v78, v195
	v_fmac_f32_e32 v31, v79, v196
	ds_read_b128 v[48:51], v4 offset:33232
	ds_read_b128 v[52:55], v4 offset:37328
	ds_read_b128 v[56:59], v4 offset:41424
	ds_read_b128 v[60:63], v4 offset:45520
	s_waitcnt lgkmcnt(8)
; #define LAS __attribute__((address_space(3)))
; __global__ void __launch_bounds__(512, 2) mega_fwd(Args a) {
;     ...
;             for (int k = 0; k < 128; k += 16) {
;                 float wv[16];
; #pragma unroll
;                 for (int j = 0; j < 16; ++j) wv[j] = __builtin_nontemporal_load(wp + (size_t)(k + j) * 6144);
; #pragma unroll
;                 for (int jj = 0; jj < 4; ++jj)
; #pragma unroll
;                     for (int r = 0; r < 16; ++r) { const f32x4 s4 = *(const LAS f32x4*)(sl + r * 1024 + wid * 128 + k + 4 * jj);
;                         acc[r] += (s4[0] * wv[4 * jj] + s4[1] * wv[4 * jj + 1]) + (s4[2] * wv[4 * jj + 2] + s4[3] * wv[4 * jj + 3]); }
;             }
	v_fmac_f32_e32 v16, v32, v197
	v_fmac_f32_e32 v16, v33, v198
	v_fmac_f32_e32 v16, v34, v199
	v_fmac_f32_e32 v16, v35, v200
	v_fmac_f32_e32 v17, v36, v197
	v_fmac_f32_e32 v17, v37, v198
	v_fmac_f32_e32 v17, v38, v199
	v_fmac_f32_e32 v17, v39, v200
	v_fmac_f32_e32 v18, v40, v197
	v_fmac_f32_e32 v18, v41, v198
	v_fmac_f32_e32 v18, v42, v199
	v_fmac_f32_e32 v18, v43, v200
	v_fmac_f32_e32 v19, v44, v197
	v_fmac_f32_e32 v19, v45, v198
	v_fmac_f32_e32 v19, v46, v199
	v_fmac_f32_e32 v19, v47, v200
	ds_read_b128 v[64:67], v4 offset:49616
	ds_read_b128 v[68:71], v4 offset:53712
	ds_read_b128 v[72:75], v4 offset:57808
	ds_read_b128 v[76:79], v4 offset:61904
	s_waitcnt lgkmcnt(8)
	v_fmac_f32_e32 v20, v212, v197
	v_fmac_f32_e32 v20, v213, v198
	v_fmac_f32_e32 v20, v214, v199
	v_fmac_f32_e32 v20, v215, v200
	v_fmac_f32_e32 v21, v216, v197
	v_fmac_f32_e32 v21, v217, v198
	v_fmac_f32_e32 v21, v218, v199
	v_fmac_f32_e32 v21, v219, v200
	v_fmac_f32_e32 v22, v220, v197
	v_fmac_f32_e32 v22, v221, v198
	v_fmac_f32_e32 v22, v222, v199
	v_fmac_f32_e32 v22, v223, v200
	v_fmac_f32_e32 v23, v224, v197
	v_fmac_f32_e32 v23, v225, v198
	v_fmac_f32_e32 v23, v226, v199
	v_fmac_f32_e32 v23, v227, v200
	ds_read_b128 v[32:35], v4 offset:480
	ds_read_b128 v[36:39], v4 offset:4576
	ds_read_b128 v[40:43], v4 offset:8672
	ds_read_b128 v[44:47], v4 offset:12768
	s_waitcnt lgkmcnt(8)
	v_fmac_f32_e32 v24, v48, v197
	v_fmac_f32_e32 v24, v49, v198
	v_fmac_f32_e32 v24, v50, v199
	v_fmac_f32_e32 v24, v51, v200
	v_fmac_f32_e32 v25, v52, v197
	v_fmac_f32_e32 v25, v53, v198
	v_fmac_f32_e32 v25, v54, v199
	v_fmac_f32_e32 v25, v55, v200
	v_fmac_f32_e32 v26, v56, v197
	v_fmac_f32_e32 v26, v57, v198
	v_fmac_f32_e32 v26, v58, v199
	v_fmac_f32_e32 v26, v59, v200
	v_fmac_f32_e32 v27, v60, v197
	v_fmac_f32_e32 v27, v61, v198
	v_fmac_f32_e32 v27, v62, v199
	v_fmac_f32_e32 v27, v63, v200
	ds_read_b128 v[212:215], v4 offset:16864
	ds_read_b128 v[216:219], v4 offset:20960
	ds_read_b128 v[220:223], v4 offset:25056
	ds_read_b128 v[224:227], v4 offset:29152
	s_waitcnt lgkmcnt(8)
	v_fmac_f32_e32 v28, v64, v197
	v_fmac_f32_e32 v28, v65, v198
	v_fmac_f32_e32 v28, v66, v199
	v_fmac_f32_e32 v28, v67, v200
	v_fmac_f32_e32 v29, v68, v197
	v_fmac_f32_e32 v29, v69, v198
	v_fmac_f32_e32 v29, v70, v199
	v_fmac_f32_e32 v29, v71, v200
	v_fmac_f32_e32 v30, v72, v197
	v_fmac_f32_e32 v30, v73, v198
	v_fmac_f32_e32 v30, v74, v199
	v_fmac_f32_e32 v30, v75, v200
	v_fmac_f32_e32 v31, v76, v197
	v_fmac_f32_e32 v31, v77, v198
	v_fmac_f32_e32 v31, v78, v199
	v_fmac_f32_e32 v31, v79, v200
	ds_read_b128 v[48:51], v4 offset:33248
	ds_read_b128 v[52:55], v4 offset:37344
	ds_read_b128 v[56:59], v4 offset:41440
	ds_read_b128 v[60:63], v4 offset:45536
	s_waitcnt lgkmcnt(8)
	v_fmac_f32_e32 v16, v32, v201
	v_fmac_f32_e32 v16, v33, v202
	v_fmac_f32_e32 v16, v34, v203
	v_fmac_f32_e32 v16, v35, v204
	v_fmac_f32_e32 v17, v36, v201
	v_fmac_f32_e32 v17, v37, v202
	v_fmac_f32_e32 v17, v38, v203
	v_fmac_f32_e32 v17, v39, v204
	v_fmac_f32_e32 v18, v40, v201
	v_fmac_f32_e32 v18, v41, v202
	v_fmac_f32_e32 v18, v42, v203
	v_fmac_f32_e32 v18, v43, v204
	v_fmac_f32_e32 v19, v44, v201
	v_fmac_f32_e32 v19, v45, v202
	v_fmac_f32_e32 v19, v46, v203
	v_fmac_f32_e32 v19, v47, v204
	ds_read_b128 v[64:67], v4 offset:49632
	ds_read_b128 v[68:71], v4 offset:53728
	ds_read_b128 v[72:75], v4 offset:57824
	ds_read_b128 v[76:79], v4 offset:61920
	s_waitcnt lgkmcnt(8)
	v_fmac_f32_e32 v20, v212, v201
	v_fmac_f32_e32 v20, v213, v202
	v_fmac_f32_e32 v20, v214, v203
	v_fmac_f32_e32 v20, v215, v204
	v_fmac_f32_e32 v21, v216, v201
	v_fmac_f32_e32 v21, v217, v202
	v_fmac_f32_e32 v21, v218, v203
	v_fmac_f32_e32 v21, v219, v204
	v_fmac_f32_e32 v22, v220, v201
	v_fmac_f32_e32 v22, v221, v202
	v_fmac_f32_e32 v22, v222, v203
	v_fmac_f32_e32 v22, v223, v204
	v_fmac_f32_e32 v23, v224, v201
	v_fmac_f32_e32 v23, v225, v202
	v_fmac_f32_e32 v23, v226, v203
	v_fmac_f32_e32 v23, v227, v204
	ds_read_b128 v[32:35], v4 offset:496
	ds_read_b128 v[36:39], v4 offset:4592
	ds_read_b128 v[40:43], v4 offset:8688
	ds_read_b128 v[44:47], v4 offset:12784
	s_waitcnt lgkmcnt(8)
	v_fmac_f32_e32 v24, v48, v201
	v_fmac_f32_e32 v24, v49, v202
	v_fmac_f32_e32 v24, v50, v203
	v_fmac_f32_e32 v24, v51, v204
	v_fmac_f32_e32 v25, v52, v201
	v_fmac_f32_e32 v25, v53, v202
	v_fmac_f32_e32 v25, v54, v203
	v_fmac_f32_e32 v25, v55, v204
	v_fmac_f32_e32 v26, v56, v201
	v_fmac_f32_e32 v26, v57, v202
	v_fmac_f32_e32 v26, v58, v203
	v_fmac_f32_e32 v26, v59, v204
	v_fmac_f32_e32 v27, v60, v201
	v_fmac_f32_e32 v27, v61, v202
	v_fmac_f32_e32 v27, v62, v203
	v_fmac_f32_e32 v27, v63, v204
	ds_read_b128 v[212:215], v4 offset:16880
	ds_read_b128 v[216:219], v4 offset:20976
	ds_read_b128 v[220:223], v4 offset:25072
	ds_read_b128 v[224:227], v4 offset:29168
	s_waitcnt lgkmcnt(8)
; #define LAS __attribute__((address_space(3)))
; __global__ void __launch_bounds__(512, 2) mega_fwd(Args a) {
;     ...
;             for (int k = 0; k < 128; k += 16) {
;                 float wv[16];
; #pragma unroll
;                 for (int j = 0; j < 16; ++j) wv[j] = __builtin_nontemporal_load(wp + (size_t)(k + j) * 6144);
; #pragma unroll
;                 for (int jj = 0; jj < 4; ++jj)
; #pragma unroll
;                     for (int r = 0; r < 16; ++r) { const f32x4 s4 = *(const LAS f32x4*)(sl + r * 1024 + wid * 128 + k + 4 * jj);
;                         acc[r] += (s4[0] * wv[4 * jj] + s4[1] * wv[4 * jj + 1]) + (s4[2] * wv[4 * jj + 2] + s4[3] * wv[4 * jj + 3]); }
;             }
; #pragma unroll
;             for (int r = 0; r < 16; ++r) red[(wid * 16 + r) * 64 + lane] = acc[r];
;             __syncthreads();
;             for (int e = tid; e < 1024; e += 512) { const int r = e >> 6, col = e & 63; float s = b_ada[it * 64 + col];
; #pragma unroll
;                 for (int w = 0; w < 8; ++w) s += red[(w * 16 + r) * 64 + col];
;                 MOD[(size_t)r * 6144 + it * 64 + col] = s; }
;             __syncthreads();
	v_fmac_f32_e32 v28, v64, v201
	v_fmac_f32_e32 v28, v65, v202
	v_fmac_f32_e32 v28, v66, v203
	v_fmac_f32_e32 v28, v67, v204
	v_fmac_f32_e32 v29, v68, v201
	v_fmac_f32_e32 v29, v69, v202
	v_fmac_f32_e32 v29, v70, v203
	v_fmac_f32_e32 v29, v71, v204
	v_fmac_f32_e32 v30, v72, v201
	v_fmac_f32_e32 v30, v73, v202
	v_fmac_f32_e32 v30, v74, v203
	v_fmac_f32_e32 v30, v75, v204
	v_fmac_f32_e32 v31, v76, v201
	v_fmac_f32_e32 v31, v77, v202
	v_fmac_f32_e32 v31, v78, v203
	v_fmac_f32_e32 v31, v79, v204
	ds_read_b128 v[48:51], v4 offset:33264
	ds_read_b128 v[52:55], v4 offset:37360
	ds_read_b128 v[56:59], v4 offset:41456
	ds_read_b128 v[60:63], v4 offset:45552
	s_waitcnt lgkmcnt(8)
	v_fmac_f32_e32 v16, v32, v205
	v_fmac_f32_e32 v16, v33, v206
	v_fmac_f32_e32 v16, v34, v207
	v_fmac_f32_e32 v16, v35, v208
	v_fmac_f32_e32 v17, v36, v205
	v_fmac_f32_e32 v17, v37, v206
	v_fmac_f32_e32 v17, v38, v207
	v_fmac_f32_e32 v17, v39, v208
	v_fmac_f32_e32 v18, v40, v205
	v_fmac_f32_e32 v18, v41, v206
	v_fmac_f32_e32 v18, v42, v207
	v_fmac_f32_e32 v18, v43, v208
	v_fmac_f32_e32 v19, v44, v205
	v_fmac_f32_e32 v19, v45, v206
	v_fmac_f32_e32 v19, v46, v207
	v_fmac_f32_e32 v19, v47, v208
	ds_read_b128 v[64:67], v4 offset:49648
	ds_read_b128 v[68:71], v4 offset:53744
	ds_read_b128 v[72:75], v4 offset:57840
	ds_read_b128 v[76:79], v4 offset:61936
	s_waitcnt lgkmcnt(8)
	v_fmac_f32_e32 v20, v212, v205
	v_fmac_f32_e32 v20, v213, v206
	v_fmac_f32_e32 v20, v214, v207
	v_fmac_f32_e32 v20, v215, v208
	v_fmac_f32_e32 v21, v216, v205
	v_fmac_f32_e32 v21, v217, v206
	v_fmac_f32_e32 v21, v218, v207
	v_fmac_f32_e32 v21, v219, v208
	v_fmac_f32_e32 v22, v220, v205
	v_fmac_f32_e32 v22, v221, v206
	v_fmac_f32_e32 v22, v222, v207
	v_fmac_f32_e32 v22, v223, v208
	v_fmac_f32_e32 v23, v224, v205
	v_fmac_f32_e32 v23, v225, v206
	v_fmac_f32_e32 v23, v226, v207
	v_fmac_f32_e32 v23, v227, v208
	s_waitcnt lgkmcnt(4)
	v_fmac_f32_e32 v24, v48, v205
	v_fmac_f32_e32 v24, v49, v206
	v_fmac_f32_e32 v24, v50, v207
	v_fmac_f32_e32 v24, v51, v208
	v_fmac_f32_e32 v25, v52, v205
	v_fmac_f32_e32 v25, v53, v206
	v_fmac_f32_e32 v25, v54, v207
	v_fmac_f32_e32 v25, v55, v208
	v_fmac_f32_e32 v26, v56, v205
	v_fmac_f32_e32 v26, v57, v206
	v_fmac_f32_e32 v26, v58, v207
	v_fmac_f32_e32 v26, v59, v208
	v_fmac_f32_e32 v27, v60, v205
	v_fmac_f32_e32 v27, v61, v206
	v_fmac_f32_e32 v27, v62, v207
	v_fmac_f32_e32 v27, v63, v208
	s_waitcnt lgkmcnt(0)
	v_fmac_f32_e32 v28, v64, v205
	v_fmac_f32_e32 v28, v65, v206
	v_fmac_f32_e32 v28, v66, v207
	v_fmac_f32_e32 v28, v67, v208
	v_fmac_f32_e32 v29, v68, v205
	v_fmac_f32_e32 v29, v69, v206
	v_fmac_f32_e32 v29, v70, v207
	v_fmac_f32_e32 v29, v71, v208
	v_fmac_f32_e32 v30, v72, v205
	v_fmac_f32_e32 v30, v73, v206
	v_fmac_f32_e32 v30, v74, v207
	v_fmac_f32_e32 v30, v75, v208
	v_fmac_f32_e32 v31, v76, v205
	v_fmac_f32_e32 v31, v77, v206
	v_fmac_f32_e32 v31, v78, v207
	v_fmac_f32_e32 v31, v79, v208
	s_lshl_b32 s3, s7, 12
	s_add_i32 s3, s3, 0x10000
	v_add_u32_e32 v5, s3, v3
	ds_write_b32 v5, v16
	ds_write_b32 v5, v17 offset:256
	ds_write_b32 v5, v18 offset:512
	ds_write_b32 v5, v19 offset:768
	ds_write_b32 v5, v20 offset:1024
	ds_write_b32 v5, v21 offset:1280
	ds_write_b32 v5, v22 offset:1536
	ds_write_b32 v5, v23 offset:1792
	ds_write_b32 v5, v24 offset:2048
	ds_write_b32 v5, v25 offset:2304
	ds_write_b32 v5, v26 offset:2560
	ds_write_b32 v5, v27 offset:2816
	ds_write_b32 v5, v28 offset:3072
	ds_write_b32 v5, v29 offset:3328
	ds_write_b32 v5, v30 offset:3584
	ds_write_b32 v5, v31 offset:3840
	s_waitcnt lgkmcnt(0)
	s_barrier
	v_add_u32_e32 v6, 0x10000, v2
	ds_read_b32 v8, v6
	ds_read_b32 v9, v6 offset:4096
	ds_read_b32 v10, v6 offset:8192
	ds_read_b32 v11, v6 offset:12288
	ds_read_b32 v12, v6 offset:16384
	ds_read_b32 v13, v6 offset:20480
	ds_read_b32 v14, v6 offset:24576
	ds_read_b32 v15, v6 offset:28672
	ds_read_b32 v24, v6 offset:2048
	ds_read_b32 v25, v6 offset:6144
	ds_read_b32 v26, v6 offset:10240
	ds_read_b32 v27, v6 offset:14336
	ds_read_b32 v28, v6 offset:18432
	ds_read_b32 v29, v6 offset:22528
	ds_read_b32 v30, v6 offset:26624
	ds_read_b32 v31, v6 offset:30720
	s_lshl_b32 s3, s61, 8
	s_add_u32 s44, s22, s3
	s_addc_u32 s45, s23, 0
	global_load_dword v7, v3, s[44:45]
	v_lshrrev_b32_e32 v32, 6, v174
	v_mul_u32_u24_e32 v32, 0x6000, v32
	v_add_u32_e32 v32, v32, v3
	s_add_u32 s44, s30, s3
	s_addc_u32 s45, s31, 0
	s_waitcnt vmcnt(0)
	s_waitcnt lgkmcnt(8)
	v_mov_b32_e32 v33, v7
	v_add_f32_e32 v33, v33, v8
	v_add_f32_e32 v33, v33, v9
	v_add_f32_e32 v33, v33, v10
	v_add_f32_e32 v33, v33, v11
	v_add_f32_e32 v33, v33, v12
	v_add_f32_e32 v33, v33, v13
	v_add_f32_e32 v33, v33, v14
	v_add_f32_e32 v33, v33, v15
	s_waitcnt lgkmcnt(0)
	v_mov_b32_e32 v34, v7
	v_add_f32_e32 v34, v34, v24
	v_add_f32_e32 v34, v34, v25
	v_add_f32_e32 v34, v34, v26
	v_add_f32_e32 v34, v34, v27
	v_add_f32_e32 v34, v34, v28
	v_add_f32_e32 v34, v34, v29
	v_add_f32_e32 v34, v34, v30
	v_add_f32_e32 v34, v34, v31
	global_store_dword v32, v33, s[44:45]
	s_add_u32 s44, s44, 0x30000
	s_addc_u32 s45, s45, 0
	global_store_dword v32, v34, s[44:45]
	s_add_i32 s61, s61, s34
	s_cmpk_gt_i32 s61, 0x5f
	s_barrier
	s_cbranch_scc0 .Lada_it

; #define LAS __attribute__((address_space(3)))
; __device__ __forceinline__ float max3f(float a, float b, float c) { float r; asm("v_max3_f32 %0, %1, %2, %3" : "=v"(r) : "v"(a), "v"(b), "v"(c)); return r; }
; template <bool QK, bool SM>
; __device__ __forceinline__ void attn_step(const LAS unsigned char* kb, const LAS unsigned char* vbp, const bf16x8 (&qr)[6],
;                                           f32x16& s0, f32x16& s1, f32x16& o0, f32x16& o1, float& mrow, float& lsum) {
;     ...
;         for (int s = 0; s < 6; ++s) { const bf16x8 ka = *(const LAS bf16x8*)(kb + s * 32), kc = *(const LAS bf16x8*)(kb + 32 * KPITCH + s * 32);
;             n0 = __builtin_amdgcn_mfma_f32_32x32x16_bf16(ka, qr[s], n0, 0, 0, 0); n1 = __builtin_amdgcn_mfma_f32_32x32x16_bf16(kc, qr[s], n1, 0, 0, 0); }
;     }
;     if constexpr (SM) {
;         float mx = max3f(s0[0], s1[0], s0[1]); mx = max3f(mx, s1[1], s0[2]); float my = max3f(s1[2], s0[3], s1[3]);
; #pragma unroll
;         for (int r = 4; r < 16; r += 4) { mx = max3f(mx, s0[r], s1[r]); my = max3f(my, s0[r + 1], s1[r + 1]); mx = max3f(mx, s0[r + 2], s1[r + 2]); my = max3f(my, s0[r + 3], s1[r + 3]); }
;         mx = fmaxf(mx, my);
;         { const auto rr = __builtin_amdgcn_permlane32_swap(__float_as_uint(mx), __float_as_uint(mx), false, false); mx = fmaxf(__uint_as_float(rr[0]), __uint_as_float(rr[1])); }
;         const float mnew = fmaxf(mrow, mx), alpha = __builtin_amdgcn_exp2f(mrow - mnew); mrow = mnew;
;         const f32x2 m2 = (f32x2){mnew, mnew}; f32x2 ps2 = (f32x2){0.f, 0.f};
; #pragma unroll
;         for (int r = 0; r < 16; r += 2) { f32x2 a = (f32x2){s0[r], s0[r + 1]} - m2, b = (f32x2){s1[r], s1[r + 1]} - m2;
;             a.x = __builtin_amdgcn_exp2f(a.x); a.y = __builtin_amdgcn_exp2f(a.y); b.x = __builtin_amdgcn_exp2f(b.x); b.y = __builtin_amdgcn_exp2f(b.y);
;             s0[r] = a.x; s0[r + 1] = a.y; s1[r] = b.x; s1[r + 1] = b.y; ps2 += a + b; }
;         const float ps = ps2.x + ps2.y;
;         lsum = lsum * alpha + ps;
.LBB0_952:
	ds_read_b128 v[2:5], v213 offset:13312
	ds_read_b128 v[10:13], v213 offset:13344
	ds_read_b128 v[80:83], v213 offset:19968
	ds_read_b128 v[96:99], v213 offset:20000
	ds_read_b128 v[84:87], v213 offset:13376
	ds_read_b128 v[88:91], v213 offset:13408
	s_waitcnt lgkmcnt(5)
	v_mfma_f32_32x32x16_bf16 v[112:127], v[2:5], v[164:167], v[218:233]
	ds_read_b128 v[100:103], v213 offset:20032
	ds_read_b128 v[104:107], v213 offset:20064
	ds_read_b128 v[92:95], v213 offset:13440
	ds_read_b128 v[108:111], v213 offset:13472
	ds_read_b128 v[6:9], v213 offset:20096
	ds_read_b128 v[2:5], v213 offset:20128
	v_max3_f32 v0, v48, v16, v49
	v_max3_f32 v0, v0, v17, v50
	v_max3_f32 v0, v0, v52, v20
	s_waitcnt lgkmcnt(10)
	v_mfma_f32_32x32x16_bf16 v[112:127], v[10:13], v[160:163], v[112:127]
	v_max3_f32 v10, v18, v51, v19
	v_max3_f32 v0, v0, v54, v22
	v_max3_f32 v10, v10, v53, v21
	v_max3_f32 v0, v0, v56, v24
	v_max3_f32 v10, v10, v55, v23
	s_waitcnt lgkmcnt(7)
	v_mfma_f32_32x32x16_bf16 v[112:127], v[84:87], v[156:159], v[112:127]
	v_max3_f32 v10, v10, v57, v25
	v_max3_f32 v0, v0, v58, v26
	v_max3_f32 v10, v10, v59, v27
	v_max3_f32 v0, v0, v60, v28
	v_max3_f32 v10, v10, v61, v29
	s_waitcnt lgkmcnt(6)
	v_mfma_f32_32x32x16_bf16 v[112:127], v[88:91], v[152:155], v[112:127]
	v_max3_f32 v10, v10, v63, v31
	v_max3_f32 v0, v0, v62, v30
	v_max_f32_e32 v10, v10, v10
	v_max_f32_e32 v0, v0, v0
	v_max_f32_e32 v0, v0, v10
	v_mov_b32_e32 v10, v0
	s_waitcnt lgkmcnt(3)
	v_mfma_f32_32x32x16_bf16 v[112:127], v[92:95], v[148:151], v[112:127]
	v_permlane32_swap_b32_e32 v0, v10
	v_max_f32_e32 v0, v0, v10
	v_sub_f32_e32 v10, v0, v206
	v_cmp_lt_f32_e32 vcc, 0x41000000, v10
	v_mov_b32_e32 v208, v206
	s_nop 0
	s_cbranch_vccnz .Latt_slowA
.Latt_contA:
	v_mfma_f32_32x32x16_bf16 v[80:95], v[80:83], v[164:167], v[218:233]
	v_exp_f32_e32 v128, v48
	v_exp_f32_e32 v129, v49
	v_exp_f32_e32 v48, v16
	v_exp_f32_e32 v49, v17
	v_exp_f32_e32 v130, v50
	v_mfma_f32_32x32x16_bf16 v[80:95], v[96:99], v[160:163], v[80:95]
	v_exp_f32_e32 v131, v51
	v_exp_f32_e32 v50, v18
	v_exp_f32_e32 v51, v19
	v_add_f32_e32 v10, v128, v48
	v_add_f32_e32 v11, v129, v49
	v_add_f32_e32 v12, v130, v50
	v_add_f32_e32 v13, v131, v51
	v_mfma_f32_32x32x16_bf16 v[80:95], v[100:103], v[156:159], v[80:95]
	v_add_u32_e32 v100, v214, v204
	v_add_f32_e32 v10, v12, v10
	v_add_f32_e32 v11, v13, v11
	v_mfma_f32_32x32x16_bf16 v[80:95], v[104:107], v[152:155], v[80:95]
	v_exp_f32_e32 v12, v52
	v_exp_f32_e32 v13, v53
	v_exp_f32_e32 v16, v54
	v_exp_f32_e32 v17, v55

; __device__ __forceinline__ unsigned cvt_pk_bf16(float lo, float hi) { unsigned r; asm("v_cvt_pk_bf16_f32 %0, %1, %2" : "=v"(r) : "v"(lo), "v"(hi)); return r; }
; template <bool QK, bool SM>
; __device__ __forceinline__ void attn_step(const LAS unsigned char* kb, const LAS unsigned char* vbp, const bf16x8 (&qr)[6],
;                                           f32x16& s0, f32x16& s1, f32x16& o0, f32x16& o1, float& mrow, float& lsum) {
;     ...
;         for (int S = 0; S < 4; ++S) { u32x4 w;
;             if (S < 2) { w.x = cvt_pk_bf16(s0[8 * S + 0], s0[8 * S + 1]); w.y = cvt_pk_bf16(s0[8 * S + 2], s0[8 * S + 3]); w.z = cvt_pk_bf16(s0[8 * S + 4], s0[8 * S + 5]); w.w = cvt_pk_bf16(s0[8 * S + 6], s0[8 * S + 7]); }
;             else { w.x = cvt_pk_bf16(s1[8 * S - 16], s1[8 * S - 15]); w.y = cvt_pk_bf16(s1[8 * S - 14], s1[8 * S - 13]); w.z = cvt_pk_bf16(s1[8 * S - 12], s1[8 * S - 11]); w.w = cvt_pk_bf16(s1[8 * S - 10], s1[8 * S - 9]); }
;             pb[S] = __builtin_bit_cast(bf16x8, w); }
	v_cvt_pk_bf16_f32 v96, v128, v129

; #define LAS __attribute__((address_space(3)))
; template <bool QK, bool SM>
; __device__ __forceinline__ void attn_step(const LAS unsigned char* kb, const LAS unsigned char* vbp, const bf16x8 (&qr)[6],
;                                           f32x16& s0, f32x16& s1, f32x16& o0, f32x16& o1, float& mrow, float& lsum) {
;     ...
;         for (int s = 0; s < 6; ++s) { const bf16x8 ka = *(const LAS bf16x8*)(kb + s * 32), kc = *(const LAS bf16x8*)(kb + 32 * KPITCH + s * 32);
;             n0 = __builtin_amdgcn_mfma_f32_32x32x16_bf16(ka, qr[s], n0, 0, 0, 0); n1 = __builtin_amdgcn_mfma_f32_32x32x16_bf16(kc, qr[s], n1, 0, 0, 0); }
;     ...
;             const u32x2 a0 = *(const LAS u32x2*)(vbp + S * 32), a1 = *(const LAS u32x2*)(vbp + S * 32 + 16);
;             const u32x2 c0 = *(const LAS u32x2*)(vbp + 32 * VPITCH + S * 32), c1 = *(const LAS u32x2*)(vbp + 32 * VPITCH + S * 32 + 16);
	s_waitcnt lgkmcnt(2)
	v_mfma_f32_32x32x16_bf16 v[112:127], v[108:111], v[144:147], v[112:127]
	v_add_u32_e32 v110, 0x6800, v100
	v_add_u32_e32 v111, 0x7800, v100
	ds_read2_b64 v[100:103], v111 offset0:32 offset1:34

; __device__ __forceinline__ unsigned cvt_pk_bf16(float lo, float hi) { unsigned r; asm("v_cvt_pk_bf16_f32 %0, %1, %2" : "=v"(r) : "v"(lo), "v"(hi)); return r; }
; template <bool QK, bool SM>
; __device__ __forceinline__ void attn_step(const LAS unsigned char* kb, const LAS unsigned char* vbp, const bf16x8 (&qr)[6],
;                                           f32x16& s0, f32x16& s1, f32x16& o0, f32x16& o1, float& mrow, float& lsum) {
;     ...
;         for (int S = 0; S < 4; ++S) { u32x4 w;
;             if (S < 2) { w.x = cvt_pk_bf16(s0[8 * S + 0], s0[8 * S + 1]); w.y = cvt_pk_bf16(s0[8 * S + 2], s0[8 * S + 3]); w.z = cvt_pk_bf16(s0[8 * S + 4], s0[8 * S + 5]); w.w = cvt_pk_bf16(s0[8 * S + 6], s0[8 * S + 7]); }
;             else { w.x = cvt_pk_bf16(s1[8 * S - 16], s1[8 * S - 15]); w.y = cvt_pk_bf16(s1[8 * S - 14], s1[8 * S - 13]); w.z = cvt_pk_bf16(s1[8 * S - 12], s1[8 * S - 11]); w.w = cvt_pk_bf16(s1[8 * S - 10], s1[8 * S - 9]); }
;             pb[S] = __builtin_bit_cast(bf16x8, w); }
	v_cvt_pk_bf16_f32 v97, v130, v131


; __device__ __forceinline__ unsigned cvt_pk_bf16(float lo, float hi) { unsigned r; asm("v_cvt_pk_bf16_f32 %0, %1, %2" : "=v"(r) : "v"(lo), "v"(hi)); return r; }
; template <bool QK, bool SM>
; __device__ __forceinline__ void attn_step(const LAS unsigned char* kb, const LAS unsigned char* vbp, const bf16x8 (&qr)[6],
;                                           f32x16& s0, f32x16& s1, f32x16& o0, f32x16& o1, float& mrow, float& lsum) {
;     ...
;         for (int S = 0; S < 4; ++S) { u32x4 w;
;             if (S < 2) { w.x = cvt_pk_bf16(s0[8 * S + 0], s0[8 * S + 1]); w.y = cvt_pk_bf16(s0[8 * S + 2], s0[8 * S + 3]); w.z = cvt_pk_bf16(s0[8 * S + 4], s0[8 * S + 5]); w.w = cvt_pk_bf16(s0[8 * S + 6], s0[8 * S + 7]); }
;             else { w.x = cvt_pk_bf16(s1[8 * S - 16], s1[8 * S - 15]); w.y = cvt_pk_bf16(s1[8 * S - 14], s1[8 * S - 13]); w.z = cvt_pk_bf16(s1[8 * S - 12], s1[8 * S - 11]); w.w = cvt_pk_bf16(s1[8 * S - 10], s1[8 * S - 9]); }
;             pb[S] = __builtin_bit_cast(bf16x8, w); }
	v_cvt_pk_bf16_f32 v98, v12, v13

; #define LAS __attribute__((address_space(3)))
; template <bool QK, bool SM>
; __device__ __forceinline__ void attn_step(const LAS unsigned char* kb, const LAS unsigned char* vbp, const bf16x8 (&qr)[6],
;                                           f32x16& s0, f32x16& s1, f32x16& o0, f32x16& o1, float& mrow, float& lsum) {
;     ...
;         for (int s = 0; s < 6; ++s) { const bf16x8 ka = *(const LAS bf16x8*)(kb + s * 32), kc = *(const LAS bf16x8*)(kb + 32 * KPITCH + s * 32);
;             n0 = __builtin_amdgcn_mfma_f32_32x32x16_bf16(ka, qr[s], n0, 0, 0, 0); n1 = __builtin_amdgcn_mfma_f32_32x32x16_bf16(kc, qr[s], n1, 0, 0, 0); }
;     ...
;             const u32x2 a0 = *(const LAS u32x2*)(vbp + S * 32), a1 = *(const LAS u32x2*)(vbp + S * 32 + 16);
;             const u32x2 c0 = *(const LAS u32x2*)(vbp + 32 * VPITCH + S * 32), c1 = *(const LAS u32x2*)(vbp + 32 * VPITCH + S * 32 + 16);
	s_waitcnt lgkmcnt(2)
	v_mfma_f32_32x32x16_bf16 v[80:95], v[6:9], v[148:151], v[80:95]
	ds_read2_b64 v[6:9], v110 offset1:2

; __device__ __forceinline__ unsigned cvt_pk_bf16(float lo, float hi) { unsigned r; asm("v_cvt_pk_bf16_f32 %0, %1, %2" : "=v"(r) : "v"(lo), "v"(hi)); return r; }
; template <bool QK, bool SM>
; __device__ __forceinline__ void attn_step(const LAS unsigned char* kb, const LAS unsigned char* vbp, const bf16x8 (&qr)[6],
;                                           f32x16& s0, f32x16& s1, f32x16& o0, f32x16& o1, float& mrow, float& lsum) {
;     ...
;         for (int S = 0; S < 4; ++S) { u32x4 w;
;             if (S < 2) { w.x = cvt_pk_bf16(s0[8 * S + 0], s0[8 * S + 1]); w.y = cvt_pk_bf16(s0[8 * S + 2], s0[8 * S + 3]); w.z = cvt_pk_bf16(s0[8 * S + 4], s0[8 * S + 5]); w.w = cvt_pk_bf16(s0[8 * S + 6], s0[8 * S + 7]); }
;             else { w.x = cvt_pk_bf16(s1[8 * S - 16], s1[8 * S - 15]); w.y = cvt_pk_bf16(s1[8 * S - 14], s1[8 * S - 13]); w.z = cvt_pk_bf16(s1[8 * S - 12], s1[8 * S - 11]); w.w = cvt_pk_bf16(s1[8 * S - 10], s1[8 * S - 9]); }
;             pb[S] = __builtin_bit_cast(bf16x8, w); }
	v_cvt_pk_bf16_f32 v99, v16, v17

; #define LAS __attribute__((address_space(3)))
; template <bool QK, bool SM>
; __device__ __forceinline__ void attn_step(const LAS unsigned char* kb, const LAS unsigned char* vbp, const bf16x8 (&qr)[6],
;                                           f32x16& s0, f32x16& s1, f32x16& o0, f32x16& o1, float& mrow, float& lsum) {
;     ...
;         for (int S = 0; S < 4; ++S) {
;             const u32x2 a0 = *(const LAS u32x2*)(vbp + S * 32), a1 = *(const LAS u32x2*)(vbp + S * 32 + 16);
;             const u32x2 c0 = *(const LAS u32x2*)(vbp + 32 * VPITCH + S * 32), c1 = *(const LAS u32x2*)(vbp + 32 * VPITCH + S * 32 + 16);
;             const bf16x8 va = __builtin_bit_cast(bf16x8, (u32x4){a0.x, a0.y, a1.x, a1.y}), vc = __builtin_bit_cast(bf16x8, (u32x4){c0.x, c0.y, c1.x, c1.y});
;             o0 = __builtin_amdgcn_mfma_f32_32x32x16_bf16(va, pb[S], o0, 0, 0, 0); o1 = __builtin_amdgcn_mfma_f32_32x32x16_bf16(vc, pb[S], o1, 0, 0, 0); }
	s_waitcnt lgkmcnt(0)
	s_nop 0
	s_waitcnt vmcnt(5)
	ds_write_b128 v197, v[168:171]
	s_and_saveexec_b64 s[10:11], s[0:1]
	s_waitcnt vmcnt(4)
	ds_write_b128 v212, v[172:175]
	s_or_b64 exec, exec, s[10:11]
	v_add_u32_e32 v235, 0x8a00, v199
	s_waitcnt vmcnt(3)
	ds_write2_b64 v235, v[176:177], v[178:179] offset1:1
	v_mfma_f32_32x32x16_bf16 v[32:47], v[6:9], v[96:99], v[32:47]
	ds_read2_b64 v[6:9], v110 offset0:4 offset1:6
	v_mov_b32_e32 v14, v20
	v_mov_b32_e32 v15, v21
	v_mfma_f32_32x32x16_bf16 v[64:79], v[100:103], v[96:99], v[64:79]
	ds_read2_b64 v[100:103], v111 offset0:36 offset1:38
	v_exp_f32_e32 v18, v56
	v_exp_f32_e32 v19, v57
	v_exp_f32_e32 v20, v58
	v_exp_f32_e32 v21, v59
	v_exp_f32_e32 v52, v60
	v_exp_f32_e32 v53, v61
	v_exp_f32_e32 v104, v62
	v_exp_f32_e32 v105, v63

; __device__ __forceinline__ unsigned cvt_pk_bf16(float lo, float hi) { unsigned r; asm("v_cvt_pk_bf16_f32 %0, %1, %2" : "=v"(r) : "v"(lo), "v"(hi)); return r; }
; template <bool QK, bool SM>
; __device__ __forceinline__ void attn_step(const LAS unsigned char* kb, const LAS unsigned char* vbp, const bf16x8 (&qr)[6],
;                                           f32x16& s0, f32x16& s1, f32x16& o0, f32x16& o1, float& mrow, float& lsum) {
;     ...
;         for (int S = 0; S < 4; ++S) { u32x4 w;
;             if (S < 2) { w.x = cvt_pk_bf16(s0[8 * S + 0], s0[8 * S + 1]); w.y = cvt_pk_bf16(s0[8 * S + 2], s0[8 * S + 3]); w.z = cvt_pk_bf16(s0[8 * S + 4], s0[8 * S + 5]); w.w = cvt_pk_bf16(s0[8 * S + 6], s0[8 * S + 7]); }
;             else { w.x = cvt_pk_bf16(s1[8 * S - 16], s1[8 * S - 15]); w.y = cvt_pk_bf16(s1[8 * S - 14], s1[8 * S - 13]); w.z = cvt_pk_bf16(s1[8 * S - 12], s1[8 * S - 11]); w.w = cvt_pk_bf16(s1[8 * S - 10], s1[8 * S - 9]); }
;             pb[S] = __builtin_bit_cast(bf16x8, w); }
	v_cvt_pk_bf16_f32 v96, v18, v19


; __device__ __forceinline__ unsigned cvt_pk_bf16(float lo, float hi) { unsigned r; asm("v_cvt_pk_bf16_f32 %0, %1, %2" : "=v"(r) : "v"(lo), "v"(hi)); return r; }
; template <bool QK, bool SM>
; __device__ __forceinline__ void attn_step(const LAS unsigned char* kb, const LAS unsigned char* vbp, const bf16x8 (&qr)[6],
;                                           f32x16& s0, f32x16& s1, f32x16& o0, f32x16& o1, float& mrow, float& lsum) {
;     ...
;         for (int S = 0; S < 4; ++S) { u32x4 w;
;             if (S < 2) { w.x = cvt_pk_bf16(s0[8 * S + 0], s0[8 * S + 1]); w.y = cvt_pk_bf16(s0[8 * S + 2], s0[8 * S + 3]); w.z = cvt_pk_bf16(s0[8 * S + 4], s0[8 * S + 5]); w.w = cvt_pk_bf16(s0[8 * S + 6], s0[8 * S + 7]); }
;             else { w.x = cvt_pk_bf16(s1[8 * S - 16], s1[8 * S - 15]); w.y = cvt_pk_bf16(s1[8 * S - 14], s1[8 * S - 13]); w.z = cvt_pk_bf16(s1[8 * S - 12], s1[8 * S - 11]); w.w = cvt_pk_bf16(s1[8 * S - 10], s1[8 * S - 9]); }
;             pb[S] = __builtin_bit_cast(bf16x8, w); }
	v_cvt_pk_bf16_f32 v97, v20, v21


; __device__ __forceinline__ unsigned cvt_pk_bf16(float lo, float hi) { unsigned r; asm("v_cvt_pk_bf16_f32 %0, %1, %2" : "=v"(r) : "v"(lo), "v"(hi)); return r; }
; template <bool QK, bool SM>
; __device__ __forceinline__ void attn_step(const LAS unsigned char* kb, const LAS unsigned char* vbp, const bf16x8 (&qr)[6],
;                                           f32x16& s0, f32x16& s1, f32x16& o0, f32x16& o1, float& mrow, float& lsum) {
;     ...
;         for (int S = 0; S < 4; ++S) { u32x4 w;
;             if (S < 2) { w.x = cvt_pk_bf16(s0[8 * S + 0], s0[8 * S + 1]); w.y = cvt_pk_bf16(s0[8 * S + 2], s0[8 * S + 3]); w.z = cvt_pk_bf16(s0[8 * S + 4], s0[8 * S + 5]); w.w = cvt_pk_bf16(s0[8 * S + 6], s0[8 * S + 7]); }
;             else { w.x = cvt_pk_bf16(s1[8 * S - 16], s1[8 * S - 15]); w.y = cvt_pk_bf16(s1[8 * S - 14], s1[8 * S - 13]); w.z = cvt_pk_bf16(s1[8 * S - 12], s1[8 * S - 11]); w.w = cvt_pk_bf16(s1[8 * S - 10], s1[8 * S - 9]); }
;             pb[S] = __builtin_bit_cast(bf16x8, w); }
	v_cvt_pk_bf16_f32 v98, v52, v53


; __device__ __forceinline__ unsigned cvt_pk_bf16(float lo, float hi) { unsigned r; asm("v_cvt_pk_bf16_f32 %0, %1, %2" : "=v"(r) : "v"(lo), "v"(hi)); return r; }
; template <bool QK, bool SM>
; __device__ __forceinline__ void attn_step(const LAS unsigned char* kb, const LAS unsigned char* vbp, const bf16x8 (&qr)[6],
;                                           f32x16& s0, f32x16& s1, f32x16& o0, f32x16& o1, float& mrow, float& lsum) {
;     ...
;         for (int S = 0; S < 4; ++S) { u32x4 w;
;             if (S < 2) { w.x = cvt_pk_bf16(s0[8 * S + 0], s0[8 * S + 1]); w.y = cvt_pk_bf16(s0[8 * S + 2], s0[8 * S + 3]); w.z = cvt_pk_bf16(s0[8 * S + 4], s0[8 * S + 5]); w.w = cvt_pk_bf16(s0[8 * S + 6], s0[8 * S + 7]); }
;             else { w.x = cvt_pk_bf16(s1[8 * S - 16], s1[8 * S - 15]); w.y = cvt_pk_bf16(s1[8 * S - 14], s1[8 * S - 13]); w.z = cvt_pk_bf16(s1[8 * S - 12], s1[8 * S - 11]); w.w = cvt_pk_bf16(s1[8 * S - 10], s1[8 * S - 9]); }
;             pb[S] = __builtin_bit_cast(bf16x8, w); }
	v_cvt_pk_bf16_f32 v99, v104, v105

; #define LAS __attribute__((address_space(3)))
; __device__ __forceinline__ unsigned cvt_pk_bf16(float lo, float hi) { unsigned r; asm("v_cvt_pk_bf16_f32 %0, %1, %2" : "=v"(r) : "v"(lo), "v"(hi)); return r; }
; template <bool QK, bool SM>
; __device__ __forceinline__ void attn_step(const LAS unsigned char* kb, const LAS unsigned char* vbp, const bf16x8 (&qr)[6],
;                                           f32x16& s0, f32x16& s1, f32x16& o0, f32x16& o1, float& mrow, float& lsum) {
;     ...
;         for (int r = 0; r < 16; r += 2) { f32x2 a = (f32x2){s0[r], s0[r + 1]} - m2, b = (f32x2){s1[r], s1[r + 1]} - m2;
;             a.x = __builtin_amdgcn_exp2f(a.x); a.y = __builtin_amdgcn_exp2f(a.y); b.x = __builtin_amdgcn_exp2f(b.x); b.y = __builtin_amdgcn_exp2f(b.y);
;             s0[r] = a.x; s0[r + 1] = a.y; s1[r] = b.x; s1[r + 1] = b.y; ps2 += a + b; }
;         const float ps = ps2.x + ps2.y;
;         lsum = lsum * alpha + ps;
; #pragma unroll
;         for (int r = 0; r < 16; ++r) { o0[r] *= alpha; o1[r] *= alpha; }
;         bf16x8 pb[4];
; #pragma unroll
;         for (int S = 0; S < 4; ++S) { u32x4 w;
;             if (S < 2) { w.x = cvt_pk_bf16(s0[8 * S + 0], s0[8 * S + 1]); w.y = cvt_pk_bf16(s0[8 * S + 2], s0[8 * S + 3]); w.z = cvt_pk_bf16(s0[8 * S + 4], s0[8 * S + 5]); w.w = cvt_pk_bf16(s0[8 * S + 6], s0[8 * S + 7]); }
;             else { w.x = cvt_pk_bf16(s1[8 * S - 16], s1[8 * S - 15]); w.y = cvt_pk_bf16(s1[8 * S - 14], s1[8 * S - 13]); w.z = cvt_pk_bf16(s1[8 * S - 12], s1[8 * S - 11]); w.w = cvt_pk_bf16(s1[8 * S - 10], s1[8 * S - 9]); }
;             pb[S] = __builtin_bit_cast(bf16x8, w); }
; #pragma unroll
;         for (int S = 0; S < 4; ++S) {
;             const u32x2 a0 = *(const LAS u32x2*)(vbp + S * 32), a1 = *(const LAS u32x2*)(vbp + S * 32 + 16);
;             const u32x2 c0 = *(const LAS u32x2*)(vbp + 32 * VPITCH + S * 32), c1 = *(const LAS u32x2*)(vbp + 32 * VPITCH + S * 32 + 16);
;             const bf16x8 va = __builtin_bit_cast(bf16x8, (u32x4){a0.x, a0.y, a1.x, a1.y}), vc = __builtin_bit_cast(bf16x8, (u32x4){c0.x, c0.y, c1.x, c1.y});
;             o0 = __builtin_amdgcn_mfma_f32_32x32x16_bf16(va, pb[S], o0, 0, 0, 0); o1 = __builtin_amdgcn_mfma_f32_32x32x16_bf16(vc, pb[S], o1, 0, 0, 0); }
	v_exp_f32_e32 v14, v14
	s_waitcnt lgkmcnt(1)
	v_mfma_f32_32x32x16_bf16 v[32:47], v[6:9], v[96:99], v[32:47]
	v_exp_f32_e32 v106, v22
	v_exp_f32_e32 v107, v23
	ds_read2_b64 v[6:9], v110 offset0:8 offset1:10
	v_exp_f32_e32 v15, v15
	v_exp_f32_e32 v108, v24
	s_waitcnt lgkmcnt(1)
	v_mfma_f32_32x32x16_bf16 v[64:79], v[100:103], v[96:99], v[64:79]
	ds_read2_b64 v[96:99], v111 offset0:40 offset1:42
	v_exp_f32_e32 v109, v25

; __device__ __forceinline__ unsigned cvt_pk_bf16(float lo, float hi) { unsigned r; asm("v_cvt_pk_bf16_f32 %0, %1, %2" : "=v"(r) : "v"(lo), "v"(hi)); return r; }
; template <bool QK, bool SM>
; __device__ __forceinline__ void attn_step(const LAS unsigned char* kb, const LAS unsigned char* vbp, const bf16x8 (&qr)[6],
;                                           f32x16& s0, f32x16& s1, f32x16& o0, f32x16& o1, float& mrow, float& lsum) {
;     ...
;         for (int S = 0; S < 4; ++S) { u32x4 w;
;             if (S < 2) { w.x = cvt_pk_bf16(s0[8 * S + 0], s0[8 * S + 1]); w.y = cvt_pk_bf16(s0[8 * S + 2], s0[8 * S + 3]); w.z = cvt_pk_bf16(s0[8 * S + 4], s0[8 * S + 5]); w.w = cvt_pk_bf16(s0[8 * S + 6], s0[8 * S + 7]); }
;             else { w.x = cvt_pk_bf16(s1[8 * S - 16], s1[8 * S - 15]); w.y = cvt_pk_bf16(s1[8 * S - 14], s1[8 * S - 13]); w.z = cvt_pk_bf16(s1[8 * S - 12], s1[8 * S - 11]); w.w = cvt_pk_bf16(s1[8 * S - 10], s1[8 * S - 9]); }
;             pb[S] = __builtin_bit_cast(bf16x8, w); }
	v_cvt_pk_bf16_f32 v22, v48, v49


; __device__ __forceinline__ unsigned cvt_pk_bf16(float lo, float hi) { unsigned r; asm("v_cvt_pk_bf16_f32 %0, %1, %2" : "=v"(r) : "v"(lo), "v"(hi)); return r; }
; template <bool QK, bool SM>
; __device__ __forceinline__ void attn_step(const LAS unsigned char* kb, const LAS unsigned char* vbp, const bf16x8 (&qr)[6],
;                                           f32x16& s0, f32x16& s1, f32x16& o0, f32x16& o1, float& mrow, float& lsum) {
;     ...
;         for (int S = 0; S < 4; ++S) { u32x4 w;
;             if (S < 2) { w.x = cvt_pk_bf16(s0[8 * S + 0], s0[8 * S + 1]); w.y = cvt_pk_bf16(s0[8 * S + 2], s0[8 * S + 3]); w.z = cvt_pk_bf16(s0[8 * S + 4], s0[8 * S + 5]); w.w = cvt_pk_bf16(s0[8 * S + 6], s0[8 * S + 7]); }
;             else { w.x = cvt_pk_bf16(s1[8 * S - 16], s1[8 * S - 15]); w.y = cvt_pk_bf16(s1[8 * S - 14], s1[8 * S - 13]); w.z = cvt_pk_bf16(s1[8 * S - 12], s1[8 * S - 11]); w.w = cvt_pk_bf16(s1[8 * S - 10], s1[8 * S - 9]); }
;             pb[S] = __builtin_bit_cast(bf16x8, w); }
	v_cvt_pk_bf16_f32 v23, v50, v51


; __device__ __forceinline__ unsigned cvt_pk_bf16(float lo, float hi) { unsigned r; asm("v_cvt_pk_bf16_f32 %0, %1, %2" : "=v"(r) : "v"(lo), "v"(hi)); return r; }
; template <bool QK, bool SM>
; __device__ __forceinline__ void attn_step(const LAS unsigned char* kb, const LAS unsigned char* vbp, const bf16x8 (&qr)[6],
;                                           f32x16& s0, f32x16& s1, f32x16& o0, f32x16& o1, float& mrow, float& lsum) {
;     ...
;         for (int S = 0; S < 4; ++S) { u32x4 w;
;             if (S < 2) { w.x = cvt_pk_bf16(s0[8 * S + 0], s0[8 * S + 1]); w.y = cvt_pk_bf16(s0[8 * S + 2], s0[8 * S + 3]); w.z = cvt_pk_bf16(s0[8 * S + 4], s0[8 * S + 5]); w.w = cvt_pk_bf16(s0[8 * S + 6], s0[8 * S + 7]); }
;             else { w.x = cvt_pk_bf16(s1[8 * S - 16], s1[8 * S - 15]); w.y = cvt_pk_bf16(s1[8 * S - 14], s1[8 * S - 13]); w.z = cvt_pk_bf16(s1[8 * S - 12], s1[8 * S - 11]); w.w = cvt_pk_bf16(s1[8 * S - 10], s1[8 * S - 9]); }
;             pb[S] = __builtin_bit_cast(bf16x8, w); }
	v_cvt_pk_bf16_f32 v24, v14, v15


; __device__ __forceinline__ unsigned cvt_pk_bf16(float lo, float hi) { unsigned r; asm("v_cvt_pk_bf16_f32 %0, %1, %2" : "=v"(r) : "v"(lo), "v"(hi)); return r; }
; template <bool QK, bool SM>
; __device__ __forceinline__ void attn_step(const LAS unsigned char* kb, const LAS unsigned char* vbp, const bf16x8 (&qr)[6],
;                                           f32x16& s0, f32x16& s1, f32x16& o0, f32x16& o1, float& mrow, float& lsum) {
;     ...
;         for (int S = 0; S < 4; ++S) { u32x4 w;
;             if (S < 2) { w.x = cvt_pk_bf16(s0[8 * S + 0], s0[8 * S + 1]); w.y = cvt_pk_bf16(s0[8 * S + 2], s0[8 * S + 3]); w.z = cvt_pk_bf16(s0[8 * S + 4], s0[8 * S + 5]); w.w = cvt_pk_bf16(s0[8 * S + 6], s0[8 * S + 7]); }
;             else { w.x = cvt_pk_bf16(s1[8 * S - 16], s1[8 * S - 15]); w.y = cvt_pk_bf16(s1[8 * S - 14], s1[8 * S - 13]); w.z = cvt_pk_bf16(s1[8 * S - 12], s1[8 * S - 11]); w.w = cvt_pk_bf16(s1[8 * S - 10], s1[8 * S - 9]); }
;             pb[S] = __builtin_bit_cast(bf16x8, w); }
	v_cvt_pk_bf16_f32 v25, v106, v107

; #define LAS __attribute__((address_space(3)))
; template <bool QK, bool SM>
; __device__ __forceinline__ void attn_step(const LAS unsigned char* kb, const LAS unsigned char* vbp, const bf16x8 (&qr)[6],
;                                           f32x16& s0, f32x16& s1, f32x16& o0, f32x16& o1, float& mrow, float& lsum) {
;     ...
;         for (int s = 0; s < 6; ++s) { const bf16x8 ka = *(const LAS bf16x8*)(kb + s * 32), kc = *(const LAS bf16x8*)(kb + 32 * KPITCH + s * 32);
;             n0 = __builtin_amdgcn_mfma_f32_32x32x16_bf16(ka, qr[s], n0, 0, 0, 0); n1 = __builtin_amdgcn_mfma_f32_32x32x16_bf16(kc, qr[s], n1, 0, 0, 0); }
;     }
;     if constexpr (SM) {
;         float mx = max3f(s0[0], s1[0], s0[1]); mx = max3f(mx, s1[1], s0[2]); float my = max3f(s1[2], s0[3], s1[3]);
; #pragma unroll
;         for (int r = 4; r < 16; r += 4) { mx = max3f(mx, s0[r], s1[r]); my = max3f(my, s0[r + 1], s1[r + 1]); mx = max3f(mx, s0[r + 2], s1[r + 2]); my = max3f(my, s0[r + 3], s1[r + 3]); }
;         mx = fmaxf(mx, my);
;         { const auto rr = __builtin_amdgcn_permlane32_swap(__float_as_uint(mx), __float_as_uint(mx), false, false); mx = fmaxf(__uint_as_float(rr[0]), __uint_as_float(rr[1])); }
;         const float mnew = fmaxf(mrow, mx), alpha = __builtin_amdgcn_exp2f(mrow - mnew); mrow = mnew;
;         const f32x2 m2 = (f32x2){mnew, mnew}; f32x2 ps2 = (f32x2){0.f, 0.f};
; #pragma unroll
;         for (int r = 0; r < 16; r += 2) { f32x2 a = (f32x2){s0[r], s0[r + 1]} - m2, b = (f32x2){s1[r], s1[r + 1]} - m2;
;             a.x = __builtin_amdgcn_exp2f(a.x); a.y = __builtin_amdgcn_exp2f(a.y); b.x = __builtin_amdgcn_exp2f(b.x); b.y = __builtin_amdgcn_exp2f(b.y);
;             s0[r] = a.x; s0[r + 1] = a.y; s1[r] = b.x; s1[r + 1] = b.y; ps2 += a + b; }
;         const float ps = ps2.x + ps2.y;
;         lsum = lsum * alpha + ps;
; #pragma unroll
;         for (int r = 0; r < 16; ++r) { o0[r] *= alpha; o1[r] *= alpha; }
;         bf16x8 pb[4];
; #pragma unroll
;         for (int S = 0; S < 4; ++S) { u32x4 w;
;             if (S < 2) { w.x = cvt_pk_bf16(s0[8 * S + 0], s0[8 * S + 1]); w.y = cvt_pk_bf16(s0[8 * S + 2], s0[8 * S + 3]); w.z = cvt_pk_bf16(s0[8 * S + 4], s0[8 * S + 5]); w.w = cvt_pk_bf16(s0[8 * S + 6], s0[8 * S + 7]); }
	v_mfma_f32_32x32x16_bf16 v[80:95], v[2:5], v[144:147], v[80:95]
	v_exp_f32_e32 v100, v26
	v_exp_f32_e32 v101, v27
	s_nop 0
	v_exp_f32_e32 v30, v30
	v_exp_f32_e32 v31, v31
	s_waitcnt lgkmcnt(1)
	v_mfma_f32_32x32x16_bf16 v[32:47], v[6:9], v[22:25], v[32:47]
	v_mov_b32_e32 v6, v28
	v_mov_b32_e32 v7, v29
	ds_read2_b64 v[26:29], v111 offset0:44 offset1:46
	v_exp_f32_e32 v102, v6
	v_exp_f32_e32 v103, v7
	ds_read2_b64 v[6:9], v110 offset0:12 offset1:14
	s_waitcnt lgkmcnt(2)
	v_mfma_f32_32x32x16_bf16 v[64:79], v[96:99], v[22:25], v[64:79]

; __device__ __forceinline__ unsigned cvt_pk_bf16(float lo, float hi) { unsigned r; asm("v_cvt_pk_bf16_f32 %0, %1, %2" : "=v"(r) : "v"(lo), "v"(hi)); return r; }
; template <bool QK, bool SM>
; __device__ __forceinline__ void attn_step(const LAS unsigned char* kb, const LAS unsigned char* vbp, const bf16x8 (&qr)[6],
;                                           f32x16& s0, f32x16& s1, f32x16& o0, f32x16& o1, float& mrow, float& lsum) {
;     ...
;         for (int S = 0; S < 4; ++S) { u32x4 w;
;             if (S < 2) { w.x = cvt_pk_bf16(s0[8 * S + 0], s0[8 * S + 1]); w.y = cvt_pk_bf16(s0[8 * S + 2], s0[8 * S + 3]); w.z = cvt_pk_bf16(s0[8 * S + 4], s0[8 * S + 5]); w.w = cvt_pk_bf16(s0[8 * S + 6], s0[8 * S + 7]); }
;             else { w.x = cvt_pk_bf16(s1[8 * S - 16], s1[8 * S - 15]); w.y = cvt_pk_bf16(s1[8 * S - 14], s1[8 * S - 13]); w.z = cvt_pk_bf16(s1[8 * S - 12], s1[8 * S - 11]); w.w = cvt_pk_bf16(s1[8 * S - 10], s1[8 * S - 9]); }
;             pb[S] = __builtin_bit_cast(bf16x8, w); }
	v_cvt_pk_bf16_f32 v22, v108, v109


; __device__ __forceinline__ unsigned cvt_pk_bf16(float lo, float hi) { unsigned r; asm("v_cvt_pk_bf16_f32 %0, %1, %2" : "=v"(r) : "v"(lo), "v"(hi)); return r; }
; template <bool QK, bool SM>
; __device__ __forceinline__ void attn_step(const LAS unsigned char* kb, const LAS unsigned char* vbp, const bf16x8 (&qr)[6],
;                                           f32x16& s0, f32x16& s1, f32x16& o0, f32x16& o1, float& mrow, float& lsum) {
;     ...
;         for (int S = 0; S < 4; ++S) { u32x4 w;
;             if (S < 2) { w.x = cvt_pk_bf16(s0[8 * S + 0], s0[8 * S + 1]); w.y = cvt_pk_bf16(s0[8 * S + 2], s0[8 * S + 3]); w.z = cvt_pk_bf16(s0[8 * S + 4], s0[8 * S + 5]); w.w = cvt_pk_bf16(s0[8 * S + 6], s0[8 * S + 7]); }
;             else { w.x = cvt_pk_bf16(s1[8 * S - 16], s1[8 * S - 15]); w.y = cvt_pk_bf16(s1[8 * S - 14], s1[8 * S - 13]); w.z = cvt_pk_bf16(s1[8 * S - 12], s1[8 * S - 11]); w.w = cvt_pk_bf16(s1[8 * S - 10], s1[8 * S - 9]); }
;             pb[S] = __builtin_bit_cast(bf16x8, w); }
	v_cvt_pk_bf16_f32 v23, v100, v101


; __device__ __forceinline__ unsigned cvt_pk_bf16(float lo, float hi) { unsigned r; asm("v_cvt_pk_bf16_f32 %0, %1, %2" : "=v"(r) : "v"(lo), "v"(hi)); return r; }
; template <bool QK, bool SM>
; __device__ __forceinline__ void attn_step(const LAS unsigned char* kb, const LAS unsigned char* vbp, const bf16x8 (&qr)[6],
;                                           f32x16& s0, f32x16& s1, f32x16& o0, f32x16& o1, float& mrow, float& lsum) {
;     ...
;         for (int S = 0; S < 4; ++S) { u32x4 w;
;             if (S < 2) { w.x = cvt_pk_bf16(s0[8 * S + 0], s0[8 * S + 1]); w.y = cvt_pk_bf16(s0[8 * S + 2], s0[8 * S + 3]); w.z = cvt_pk_bf16(s0[8 * S + 4], s0[8 * S + 5]); w.w = cvt_pk_bf16(s0[8 * S + 6], s0[8 * S + 7]); }
;             else { w.x = cvt_pk_bf16(s1[8 * S - 16], s1[8 * S - 15]); w.y = cvt_pk_bf16(s1[8 * S - 14], s1[8 * S - 13]); w.z = cvt_pk_bf16(s1[8 * S - 12], s1[8 * S - 11]); w.w = cvt_pk_bf16(s1[8 * S - 10], s1[8 * S - 9]); }
;             pb[S] = __builtin_bit_cast(bf16x8, w); }
	v_cvt_pk_bf16_f32 v24, v102, v103


; __device__ __forceinline__ unsigned cvt_pk_bf16(float lo, float hi) { unsigned r; asm("v_cvt_pk_bf16_f32 %0, %1, %2" : "=v"(r) : "v"(lo), "v"(hi)); return r; }
; template <bool QK, bool SM>
; __device__ __forceinline__ void attn_step(const LAS unsigned char* kb, const LAS unsigned char* vbp, const bf16x8 (&qr)[6],
;                                           f32x16& s0, f32x16& s1, f32x16& o0, f32x16& o1, float& mrow, float& lsum) {
;     ...
;         for (int S = 0; S < 4; ++S) { u32x4 w;
;             if (S < 2) { w.x = cvt_pk_bf16(s0[8 * S + 0], s0[8 * S + 1]); w.y = cvt_pk_bf16(s0[8 * S + 2], s0[8 * S + 3]); w.z = cvt_pk_bf16(s0[8 * S + 4], s0[8 * S + 5]); w.w = cvt_pk_bf16(s0[8 * S + 6], s0[8 * S + 7]); }
;             else { w.x = cvt_pk_bf16(s1[8 * S - 16], s1[8 * S - 15]); w.y = cvt_pk_bf16(s1[8 * S - 14], s1[8 * S - 13]); w.z = cvt_pk_bf16(s1[8 * S - 12], s1[8 * S - 11]); w.w = cvt_pk_bf16(s1[8 * S - 10], s1[8 * S - 9]); }
;             pb[S] = __builtin_bit_cast(bf16x8, w); }
	v_cvt_pk_bf16_f32 v25, v30, v31

; #define LAS __attribute__((address_space(3)))
; __device__ __forceinline__ unsigned cvt_pk_bf16(float lo, float hi) { unsigned r; asm("v_cvt_pk_bf16_f32 %0, %1, %2" : "=v"(r) : "v"(lo), "v"(hi)); return r; }
; template <bool QK, bool SM>
; __device__ __forceinline__ void attn_step(const LAS unsigned char* kb, const LAS unsigned char* vbp, const bf16x8 (&qr)[6],
;                                           f32x16& s0, f32x16& s1, f32x16& o0, f32x16& o1, float& mrow, float& lsum) {
;     ...
;             s0[r] = a.x; s0[r + 1] = a.y; s1[r] = b.x; s1[r + 1] = b.y; ps2 += a + b; }
;         const float ps = ps2.x + ps2.y;
;         lsum = lsum * alpha + ps;
; #pragma unroll
;         for (int r = 0; r < 16; ++r) { o0[r] *= alpha; o1[r] *= alpha; }
;         bf16x8 pb[4];
; #pragma unroll
;         for (int S = 0; S < 4; ++S) { u32x4 w;
;             if (S < 2) { w.x = cvt_pk_bf16(s0[8 * S + 0], s0[8 * S + 1]); w.y = cvt_pk_bf16(s0[8 * S + 2], s0[8 * S + 3]); w.z = cvt_pk_bf16(s0[8 * S + 4], s0[8 * S + 5]); w.w = cvt_pk_bf16(s0[8 * S + 6], s0[8 * S + 7]); }
;             else { w.x = cvt_pk_bf16(s1[8 * S - 16], s1[8 * S - 15]); w.y = cvt_pk_bf16(s1[8 * S - 14], s1[8 * S - 13]); w.z = cvt_pk_bf16(s1[8 * S - 12], s1[8 * S - 11]); w.w = cvt_pk_bf16(s1[8 * S - 10], s1[8 * S - 9]); }
;             pb[S] = __builtin_bit_cast(bf16x8, w); }
; #pragma unroll
;         for (int S = 0; S < 4; ++S) {
;             const u32x2 a0 = *(const LAS u32x2*)(vbp + S * 32), a1 = *(const LAS u32x2*)(vbp + S * 32 + 16);
;             const u32x2 c0 = *(const LAS u32x2*)(vbp + 32 * VPITCH + S * 32), c1 = *(const LAS u32x2*)(vbp + 32 * VPITCH + S * 32 + 16);
;             const bf16x8 va = __builtin_bit_cast(bf16x8, (u32x4){a0.x, a0.y, a1.x, a1.y}), vc = __builtin_bit_cast(bf16x8, (u32x4){c0.x, c0.y, c1.x, c1.y});
;             o0 = __builtin_amdgcn_mfma_f32_32x32x16_bf16(va, pb[S], o0, 0, 0, 0); o1 = __builtin_amdgcn_mfma_f32_32x32x16_bf16(vc, pb[S], o1, 0, 0, 0); }
	s_waitcnt lgkmcnt(0)
	s_nop 0
	v_mfma_f32_32x32x16_bf16 v[32:47], v[6:9], v[22:25], v[32:47]
	v_add_f32_e32 v6, v12, v14
	v_add_f32_e32 v7, v13, v15
	v_add_f32_e32 v8, v16, v106
	v_add_f32_e32 v9, v17, v107
	v_add_f32_e32 v6, v6, v10
	v_add_f32_e32 v7, v7, v11
	v_add_f32_e32 v6, v8, v6
	v_add_f32_e32 v7, v9, v7
	v_add_f32_e32 v8, v18, v108
	v_add_f32_e32 v9, v19, v109
	v_mfma_f32_32x32x16_bf16 v[64:79], v[26:29], v[22:25], v[64:79]
	v_add_f32_e32 v6, v8, v6
	v_add_f32_e32 v7, v9, v7
	v_add_f32_e32 v8, v20, v100
	v_add_f32_e32 v9, v21, v101
	v_add_f32_e32 v6, v8, v6
	v_add_f32_e32 v7, v9, v7
	v_add_f32_e32 v8, v52, v102
	v_add_f32_e32 v9, v53, v103
	s_nop 0
	v_add_f32_e32 v6, v8, v6
	v_add_f32_e32 v7, v9, v7
	v_add_f32_e32 v8, v104, v30
	v_add_f32_e32 v9, v105, v31
	s_nop 0
	v_add_f32_e32 v6, v8, v6
	v_add_f32_e32 v7, v9, v7
	s_nop 0
	v_add_f32_e32 v216, v6, v7
	v_add_f32_e32 v216, v216, v215
	s_cmp_lg_u32 s99, 0
	s_cbranch_scc1 .Latt_slow2A

; #define LAS __attribute__((address_space(3)))
; template <bool QK, bool SM>
; __device__ __forceinline__ void attn_step(const LAS unsigned char* kb, const LAS unsigned char* vbp, const bf16x8 (&qr)[6],
;                                           f32x16& s0, f32x16& s1, f32x16& o0, f32x16& o1, float& mrow, float& lsum) {
;     ...
;         for (int s = 0; s < 6; ++s) { const bf16x8 ka = *(const LAS bf16x8*)(kb + s * 32), kc = *(const LAS bf16x8*)(kb + 32 * KPITCH + s * 32);
;             n0 = __builtin_amdgcn_mfma_f32_32x32x16_bf16(ka, qr[s], n0, 0, 0, 0); n1 = __builtin_amdgcn_mfma_f32_32x32x16_bf16(kc, qr[s], n1, 0, 0, 0); }
.LBB0_957:
	ds_read_b128 v[2:5], v213
	ds_read_b128 v[10:13], v213 offset:32
	ds_read_b128 v[14:17], v213 offset:6656
	ds_read_b128 v[96:99], v213 offset:6688
	ds_read_b128 v[18:21], v213 offset:64
	ds_read_b128 v[22:25], v213 offset:96
	s_waitcnt lgkmcnt(5)
	v_mfma_f32_32x32x16_bf16 v[48:63], v[2:5], v[164:167], v[218:233]

; __device__ __forceinline__ float max3f(float a, float b, float c) { float r; asm("v_max3_f32 %0, %1, %2, %3" : "=v"(r) : "v"(a), "v"(b), "v"(c)); return r; }
; template <bool QK, bool SM>
; __device__ __forceinline__ void attn_step(const LAS unsigned char* kb, const LAS unsigned char* vbp, const bf16x8 (&qr)[6],
;                                           f32x16& s0, f32x16& s1, f32x16& o0, f32x16& o1, float& mrow, float& lsum) {
;     ...
;         float mx = max3f(s0[0], s1[0], s0[1]); mx = max3f(mx, s1[1], s0[2]); float my = max3f(s1[2], s0[3], s1[3]);
	v_max3_f32 v0, v112, v80, v113

; #define LAS __attribute__((address_space(3)))
; template <bool QK, bool SM>
; __device__ __forceinline__ void attn_step(const LAS unsigned char* kb, const LAS unsigned char* vbp, const bf16x8 (&qr)[6],
;                                           f32x16& s0, f32x16& s1, f32x16& o0, f32x16& o1, float& mrow, float& lsum) {
;     ...
;         for (int s = 0; s < 6; ++s) { const bf16x8 ka = *(const LAS bf16x8*)(kb + s * 32), kc = *(const LAS bf16x8*)(kb + 32 * KPITCH + s * 32);
;             n0 = __builtin_amdgcn_mfma_f32_32x32x16_bf16(ka, qr[s], n0, 0, 0, 0); n1 = __builtin_amdgcn_mfma_f32_32x32x16_bf16(kc, qr[s], n1, 0, 0, 0); }
	ds_read_b128 v[100:103], v213 offset:6720
	ds_read_b128 v[104:107], v213 offset:6752
	ds_read_b128 v[26:29], v213 offset:128
	ds_read_b128 v[108:111], v213 offset:160
	ds_read_b128 v[6:9], v213 offset:6784
	ds_read_b128 v[2:5], v213 offset:6816

; __device__ __forceinline__ float max3f(float a, float b, float c) { float r; asm("v_max3_f32 %0, %1, %2, %3" : "=v"(r) : "v"(a), "v"(b), "v"(c)); return r; }
; template <bool QK, bool SM>
; __device__ __forceinline__ void attn_step(const LAS unsigned char* kb, const LAS unsigned char* vbp, const bf16x8 (&qr)[6],
;                                           f32x16& s0, f32x16& s1, f32x16& o0, f32x16& o1, float& mrow, float& lsum) {
;     ...
;         float mx = max3f(s0[0], s1[0], s0[1]); mx = max3f(mx, s1[1], s0[2]); float my = max3f(s1[2], s0[3], s1[3]);
	v_max3_f32 v0, v0, v81, v114

; #define LAS __attribute__((address_space(3)))
; template <bool QK, bool SM>
; __device__ __forceinline__ void attn_step(const LAS unsigned char* kb, const LAS unsigned char* vbp, const bf16x8 (&qr)[6],
;                                           f32x16& s0, f32x16& s1, f32x16& o0, f32x16& o1, float& mrow, float& lsum) {
;     ...
;             const u32x2 a0 = *(const LAS u32x2*)(vbp + S * 32), a1 = *(const LAS u32x2*)(vbp + S * 32 + 16);
;             const u32x2 c0 = *(const LAS u32x2*)(vbp + 32 * VPITCH + S * 32), c1 = *(const LAS u32x2*)(vbp + 32 * VPITCH + S * 32 + 16);
	v_add_u32_e32 v132, v214, v204

; __device__ __forceinline__ float max3f(float a, float b, float c) { float r; asm("v_max3_f32 %0, %1, %2, %3" : "=v"(r) : "v"(a), "v"(b), "v"(c)); return r; }
; template <bool QK, bool SM>
; __device__ __forceinline__ void attn_step(const LAS unsigned char* kb, const LAS unsigned char* vbp, const bf16x8 (&qr)[6],
;                                           f32x16& s0, f32x16& s1, f32x16& o0, f32x16& o1, float& mrow, float& lsum) {
;     ...
;         float mx = max3f(s0[0], s1[0], s0[1]); mx = max3f(mx, s1[1], s0[2]); float my = max3f(s1[2], s0[3], s1[3]);
; #pragma unroll
;         for (int r = 4; r < 16; r += 4) { mx = max3f(mx, s0[r], s1[r]); my = max3f(my, s0[r + 1], s1[r + 1]); mx = max3f(mx, s0[r + 2], s1[r + 2]); my = max3f(my, s0[r + 3], s1[r + 3]); }
	v_max3_f32 v0, v0, v116, v84


; __device__ __forceinline__ float max3f(float a, float b, float c) { float r; asm("v_max3_f32 %0, %1, %2, %3" : "=v"(r) : "v"(a), "v"(b), "v"(c)); return r; }
; template <bool QK, bool SM>
; __device__ __forceinline__ void attn_step(const LAS unsigned char* kb, const LAS unsigned char* vbp, const bf16x8 (&qr)[6],
;                                           f32x16& s0, f32x16& s1, f32x16& o0, f32x16& o1, float& mrow, float& lsum) {
;     ...
;         float mx = max3f(s0[0], s1[0], s0[1]); mx = max3f(mx, s1[1], s0[2]); float my = max3f(s1[2], s0[3], s1[3]);
; #pragma unroll
;         for (int r = 4; r < 16; r += 4) { mx = max3f(mx, s0[r], s1[r]); my = max3f(my, s0[r + 1], s1[r + 1]); mx = max3f(mx, s0[r + 2], s1[r + 2]); my = max3f(my, s0[r + 3], s1[r + 3]); }
	v_max3_f32 v0, v0, v118, v86

; #define LAS __attribute__((address_space(3)))
; template <bool QK, bool SM>
; __device__ __forceinline__ void attn_step(const LAS unsigned char* kb, const LAS unsigned char* vbp, const bf16x8 (&qr)[6],
;                                           f32x16& s0, f32x16& s1, f32x16& o0, f32x16& o1, float& mrow, float& lsum) {
;     ...
;         for (int s = 0; s < 6; ++s) { const bf16x8 ka = *(const LAS bf16x8*)(kb + s * 32), kc = *(const LAS bf16x8*)(kb + 32 * KPITCH + s * 32);
;             n0 = __builtin_amdgcn_mfma_f32_32x32x16_bf16(ka, qr[s], n0, 0, 0, 0); n1 = __builtin_amdgcn_mfma_f32_32x32x16_bf16(kc, qr[s], n1, 0, 0, 0); }
	s_waitcnt lgkmcnt(10)
	v_mfma_f32_32x32x16_bf16 v[48:63], v[10:13], v[160:163], v[48:63]

; __device__ __forceinline__ float max3f(float a, float b, float c) { float r; asm("v_max3_f32 %0, %1, %2, %3" : "=v"(r) : "v"(a), "v"(b), "v"(c)); return r; }
; template <bool QK, bool SM>
; __device__ __forceinline__ void attn_step(const LAS unsigned char* kb, const LAS unsigned char* vbp, const bf16x8 (&qr)[6],
;                                           f32x16& s0, f32x16& s1, f32x16& o0, f32x16& o1, float& mrow, float& lsum) {
;     ...
;         float mx = max3f(s0[0], s1[0], s0[1]); mx = max3f(mx, s1[1], s0[2]); float my = max3f(s1[2], s0[3], s1[3]);
	v_max3_f32 v10, v82, v115, v83


; __device__ __forceinline__ float max3f(float a, float b, float c) { float r; asm("v_max3_f32 %0, %1, %2, %3" : "=v"(r) : "v"(a), "v"(b), "v"(c)); return r; }
; template <bool QK, bool SM>
; __device__ __forceinline__ void attn_step(const LAS unsigned char* kb, const LAS unsigned char* vbp, const bf16x8 (&qr)[6],
;                                           f32x16& s0, f32x16& s1, f32x16& o0, f32x16& o1, float& mrow, float& lsum) {
;     ...
;         float mx = max3f(s0[0], s1[0], s0[1]); mx = max3f(mx, s1[1], s0[2]); float my = max3f(s1[2], s0[3], s1[3]);
; #pragma unroll
;         for (int r = 4; r < 16; r += 4) { mx = max3f(mx, s0[r], s1[r]); my = max3f(my, s0[r + 1], s1[r + 1]); mx = max3f(mx, s0[r + 2], s1[r + 2]); my = max3f(my, s0[r + 3], s1[r + 3]); }
	v_max3_f32 v0, v0, v120, v88


; __device__ __forceinline__ float max3f(float a, float b, float c) { float r; asm("v_max3_f32 %0, %1, %2, %3" : "=v"(r) : "v"(a), "v"(b), "v"(c)); return r; }
; template <bool QK, bool SM>
; __device__ __forceinline__ void attn_step(const LAS unsigned char* kb, const LAS unsigned char* vbp, const bf16x8 (&qr)[6],
;                                           f32x16& s0, f32x16& s1, f32x16& o0, f32x16& o1, float& mrow, float& lsum) {
;     ...
;         float mx = max3f(s0[0], s1[0], s0[1]); mx = max3f(mx, s1[1], s0[2]); float my = max3f(s1[2], s0[3], s1[3]);
; #pragma unroll
;         for (int r = 4; r < 16; r += 4) { mx = max3f(mx, s0[r], s1[r]); my = max3f(my, s0[r + 1], s1[r + 1]); mx = max3f(mx, s0[r + 2], s1[r + 2]); my = max3f(my, s0[r + 3], s1[r + 3]); }
	v_max3_f32 v10, v10, v117, v85


; __device__ __forceinline__ float max3f(float a, float b, float c) { float r; asm("v_max3_f32 %0, %1, %2, %3" : "=v"(r) : "v"(a), "v"(b), "v"(c)); return r; }
; template <bool QK, bool SM>
; __device__ __forceinline__ void attn_step(const LAS unsigned char* kb, const LAS unsigned char* vbp, const bf16x8 (&qr)[6],
;                                           f32x16& s0, f32x16& s1, f32x16& o0, f32x16& o1, float& mrow, float& lsum) {
;     ...
;         float mx = max3f(s0[0], s1[0], s0[1]); mx = max3f(mx, s1[1], s0[2]); float my = max3f(s1[2], s0[3], s1[3]);
; #pragma unroll
;         for (int r = 4; r < 16; r += 4) { mx = max3f(mx, s0[r], s1[r]); my = max3f(my, s0[r + 1], s1[r + 1]); mx = max3f(mx, s0[r + 2], s1[r + 2]); my = max3f(my, s0[r + 3], s1[r + 3]); }
	v_max3_f32 v0, v0, v122, v90


; __device__ __forceinline__ float max3f(float a, float b, float c) { float r; asm("v_max3_f32 %0, %1, %2, %3" : "=v"(r) : "v"(a), "v"(b), "v"(c)); return r; }
; template <bool QK, bool SM>
; __device__ __forceinline__ void attn_step(const LAS unsigned char* kb, const LAS unsigned char* vbp, const bf16x8 (&qr)[6],
;                                           f32x16& s0, f32x16& s1, f32x16& o0, f32x16& o1, float& mrow, float& lsum) {
;     ...
;         float mx = max3f(s0[0], s1[0], s0[1]); mx = max3f(mx, s1[1], s0[2]); float my = max3f(s1[2], s0[3], s1[3]);
; #pragma unroll
;         for (int r = 4; r < 16; r += 4) { mx = max3f(mx, s0[r], s1[r]); my = max3f(my, s0[r + 1], s1[r + 1]); mx = max3f(mx, s0[r + 2], s1[r + 2]); my = max3f(my, s0[r + 3], s1[r + 3]); }
	v_max3_f32 v10, v10, v119, v87

; #define LAS __attribute__((address_space(3)))
; template <bool QK, bool SM>
; __device__ __forceinline__ void attn_step(const LAS unsigned char* kb, const LAS unsigned char* vbp, const bf16x8 (&qr)[6],
;                                           f32x16& s0, f32x16& s1, f32x16& o0, f32x16& o1, float& mrow, float& lsum) {
;     ...
;         for (int s = 0; s < 6; ++s) { const bf16x8 ka = *(const LAS bf16x8*)(kb + s * 32), kc = *(const LAS bf16x8*)(kb + 32 * KPITCH + s * 32);
;             n0 = __builtin_amdgcn_mfma_f32_32x32x16_bf16(ka, qr[s], n0, 0, 0, 0); n1 = __builtin_amdgcn_mfma_f32_32x32x16_bf16(kc, qr[s], n1, 0, 0, 0); }
	s_waitcnt lgkmcnt(7)
	v_mfma_f32_32x32x16_bf16 v[48:63], v[18:21], v[156:159], v[48:63]

; __device__ __forceinline__ float max3f(float a, float b, float c) { float r; asm("v_max3_f32 %0, %1, %2, %3" : "=v"(r) : "v"(a), "v"(b), "v"(c)); return r; }
; template <bool QK, bool SM>
; __device__ __forceinline__ void attn_step(const LAS unsigned char* kb, const LAS unsigned char* vbp, const bf16x8 (&qr)[6],
;                                           f32x16& s0, f32x16& s1, f32x16& o0, f32x16& o1, float& mrow, float& lsum) {
;     ...
;         float mx = max3f(s0[0], s1[0], s0[1]); mx = max3f(mx, s1[1], s0[2]); float my = max3f(s1[2], s0[3], s1[3]);
; #pragma unroll
;         for (int r = 4; r < 16; r += 4) { mx = max3f(mx, s0[r], s1[r]); my = max3f(my, s0[r + 1], s1[r + 1]); mx = max3f(mx, s0[r + 2], s1[r + 2]); my = max3f(my, s0[r + 3], s1[r + 3]); }
	v_max3_f32 v10, v10, v121, v89


; __device__ __forceinline__ float max3f(float a, float b, float c) { float r; asm("v_max3_f32 %0, %1, %2, %3" : "=v"(r) : "v"(a), "v"(b), "v"(c)); return r; }
; template <bool QK, bool SM>
; __device__ __forceinline__ void attn_step(const LAS unsigned char* kb, const LAS unsigned char* vbp, const bf16x8 (&qr)[6],
;                                           f32x16& s0, f32x16& s1, f32x16& o0, f32x16& o1, float& mrow, float& lsum) {
;     ...
;         float mx = max3f(s0[0], s1[0], s0[1]); mx = max3f(mx, s1[1], s0[2]); float my = max3f(s1[2], s0[3], s1[3]);
; #pragma unroll
;         for (int r = 4; r < 16; r += 4) { mx = max3f(mx, s0[r], s1[r]); my = max3f(my, s0[r + 1], s1[r + 1]); mx = max3f(mx, s0[r + 2], s1[r + 2]); my = max3f(my, s0[r + 3], s1[r + 3]); }
	v_max3_f32 v0, v0, v124, v92


; __device__ __forceinline__ float max3f(float a, float b, float c) { float r; asm("v_max3_f32 %0, %1, %2, %3" : "=v"(r) : "v"(a), "v"(b), "v"(c)); return r; }
; template <bool QK, bool SM>
; __device__ __forceinline__ void attn_step(const LAS unsigned char* kb, const LAS unsigned char* vbp, const bf16x8 (&qr)[6],
;                                           f32x16& s0, f32x16& s1, f32x16& o0, f32x16& o1, float& mrow, float& lsum) {
;     ...
;         float mx = max3f(s0[0], s1[0], s0[1]); mx = max3f(mx, s1[1], s0[2]); float my = max3f(s1[2], s0[3], s1[3]);
; #pragma unroll
;         for (int r = 4; r < 16; r += 4) { mx = max3f(mx, s0[r], s1[r]); my = max3f(my, s0[r + 1], s1[r + 1]); mx = max3f(mx, s0[r + 2], s1[r + 2]); my = max3f(my, s0[r + 3], s1[r + 3]); }
	v_max3_f32 v10, v10, v123, v91


; __device__ __forceinline__ float max3f(float a, float b, float c) { float r; asm("v_max3_f32 %0, %1, %2, %3" : "=v"(r) : "v"(a), "v"(b), "v"(c)); return r; }
; template <bool QK, bool SM>
; __device__ __forceinline__ void attn_step(const LAS unsigned char* kb, const LAS unsigned char* vbp, const bf16x8 (&qr)[6],
;                                           f32x16& s0, f32x16& s1, f32x16& o0, f32x16& o1, float& mrow, float& lsum) {
;     ...
;         float mx = max3f(s0[0], s1[0], s0[1]); mx = max3f(mx, s1[1], s0[2]); float my = max3f(s1[2], s0[3], s1[3]);
; #pragma unroll
;         for (int r = 4; r < 16; r += 4) { mx = max3f(mx, s0[r], s1[r]); my = max3f(my, s0[r + 1], s1[r + 1]); mx = max3f(mx, s0[r + 2], s1[r + 2]); my = max3f(my, s0[r + 3], s1[r + 3]); }
	v_max3_f32 v0, v0, v126, v94


; __device__ __forceinline__ float max3f(float a, float b, float c) { float r; asm("v_max3_f32 %0, %1, %2, %3" : "=v"(r) : "v"(a), "v"(b), "v"(c)); return r; }
; template <bool QK, bool SM>
; __device__ __forceinline__ void attn_step(const LAS unsigned char* kb, const LAS unsigned char* vbp, const bf16x8 (&qr)[6],
;                                           f32x16& s0, f32x16& s1, f32x16& o0, f32x16& o1, float& mrow, float& lsum) {
;     ...
;         float mx = max3f(s0[0], s1[0], s0[1]); mx = max3f(mx, s1[1], s0[2]); float my = max3f(s1[2], s0[3], s1[3]);
; #pragma unroll
;         for (int r = 4; r < 16; r += 4) { mx = max3f(mx, s0[r], s1[r]); my = max3f(my, s0[r + 1], s1[r + 1]); mx = max3f(mx, s0[r + 2], s1[r + 2]); my = max3f(my, s0[r + 3], s1[r + 3]); }
	v_max3_f32 v10, v10, v125, v93

; #define LAS __attribute__((address_space(3)))
; template <bool QK, bool SM>
; __device__ __forceinline__ void attn_step(const LAS unsigned char* kb, const LAS unsigned char* vbp, const bf16x8 (&qr)[6],
;                                           f32x16& s0, f32x16& s1, f32x16& o0, f32x16& o1, float& mrow, float& lsum) {
;     ...
;         for (int s = 0; s < 6; ++s) { const bf16x8 ka = *(const LAS bf16x8*)(kb + s * 32), kc = *(const LAS bf16x8*)(kb + 32 * KPITCH + s * 32);
;             n0 = __builtin_amdgcn_mfma_f32_32x32x16_bf16(ka, qr[s], n0, 0, 0, 0); n1 = __builtin_amdgcn_mfma_f32_32x32x16_bf16(kc, qr[s], n1, 0, 0, 0); }
	s_waitcnt lgkmcnt(6)
	v_mfma_f32_32x32x16_bf16 v[48:63], v[22:25], v[152:155], v[48:63]

; __device__ __forceinline__ float max3f(float a, float b, float c) { float r; asm("v_max3_f32 %0, %1, %2, %3" : "=v"(r) : "v"(a), "v"(b), "v"(c)); return r; }
; template <bool QK, bool SM>
; __device__ __forceinline__ void attn_step(const LAS unsigned char* kb, const LAS unsigned char* vbp, const bf16x8 (&qr)[6],
;                                           f32x16& s0, f32x16& s1, f32x16& o0, f32x16& o1, float& mrow, float& lsum) {
;     ...
;         float mx = max3f(s0[0], s1[0], s0[1]); mx = max3f(mx, s1[1], s0[2]); float my = max3f(s1[2], s0[3], s1[3]);
; #pragma unroll
;         for (int r = 4; r < 16; r += 4) { mx = max3f(mx, s0[r], s1[r]); my = max3f(my, s0[r + 1], s1[r + 1]); mx = max3f(mx, s0[r + 2], s1[r + 2]); my = max3f(my, s0[r + 3], s1[r + 3]); }
	v_max3_f32 v10, v10, v127, v95

; #define LAS __attribute__((address_space(3)))
; __device__ __forceinline__ float max3f(float a, float b, float c) { float r; asm("v_max3_f32 %0, %1, %2, %3" : "=v"(r) : "v"(a), "v"(b), "v"(c)); return r; }
; template <bool QK, bool SM>
; __device__ __forceinline__ void attn_step(const LAS unsigned char* kb, const LAS unsigned char* vbp, const bf16x8 (&qr)[6],
;                                           f32x16& s0, f32x16& s1, f32x16& o0, f32x16& o1, float& mrow, float& lsum) {
;     ...
;         for (int s = 0; s < 6; ++s) { const bf16x8 ka = *(const LAS bf16x8*)(kb + s * 32), kc = *(const LAS bf16x8*)(kb + 32 * KPITCH + s * 32);
;             n0 = __builtin_amdgcn_mfma_f32_32x32x16_bf16(ka, qr[s], n0, 0, 0, 0); n1 = __builtin_amdgcn_mfma_f32_32x32x16_bf16(kc, qr[s], n1, 0, 0, 0); }
;     }
;     if constexpr (SM) {
;         float mx = max3f(s0[0], s1[0], s0[1]); mx = max3f(mx, s1[1], s0[2]); float my = max3f(s1[2], s0[3], s1[3]);
; #pragma unroll
;         for (int r = 4; r < 16; r += 4) { mx = max3f(mx, s0[r], s1[r]); my = max3f(my, s0[r + 1], s1[r + 1]); mx = max3f(mx, s0[r + 2], s1[r + 2]); my = max3f(my, s0[r + 3], s1[r + 3]); }
;         mx = fmaxf(mx, my);
;         { const auto rr = __builtin_amdgcn_permlane32_swap(__float_as_uint(mx), __float_as_uint(mx), false, false); mx = fmaxf(__uint_as_float(rr[0]), __uint_as_float(rr[1])); }
;         const float mnew = fmaxf(mrow, mx), alpha = __builtin_amdgcn_exp2f(mrow - mnew); mrow = mnew;
;         const f32x2 m2 = (f32x2){mnew, mnew}; f32x2 ps2 = (f32x2){0.f, 0.f};
; #pragma unroll
;         for (int r = 0; r < 16; r += 2) { f32x2 a = (f32x2){s0[r], s0[r + 1]} - m2, b = (f32x2){s1[r], s1[r + 1]} - m2;
;             a.x = __builtin_amdgcn_exp2f(a.x); a.y = __builtin_amdgcn_exp2f(a.y); b.x = __builtin_amdgcn_exp2f(b.x); b.y = __builtin_amdgcn_exp2f(b.y);
;             s0[r] = a.x; s0[r + 1] = a.y; s1[r] = b.x; s1[r + 1] = b.y; ps2 += a + b; }
;         const float ps = ps2.x + ps2.y;
;         lsum = lsum * alpha + ps;
	v_max_f32_e32 v0, v0, v0
	v_max_f32_e32 v10, v10, v10
	v_max_f32_e32 v0, v0, v10
	v_mov_b32_e32 v10, v0
	s_nop 1
	v_permlane32_swap_b32_e32 v0, v10
	v_max_f32_e32 v0, v0, v10
	v_sub_f32_e32 v10, v0, v208
	v_cmp_lt_f32_e32 vcc, 0x41000000, v10
	v_mov_b32_e32 v206, v208
	s_nop 0
	s_cbranch_vccnz .Latt_slowB
.Latt_contB:
	s_waitcnt lgkmcnt(3)
	v_mfma_f32_32x32x16_bf16 v[48:63], v[26:29], v[148:151], v[48:63]
	v_exp_f32_e32 v130, v114
	v_exp_f32_e32 v131, v115
	v_exp_f32_e32 v114, v82
	v_exp_f32_e32 v115, v83
	v_mfma_f32_32x32x16_bf16 v[16:31], v[14:17], v[164:167], v[218:233]
	v_exp_f32_e32 v128, v112
	v_exp_f32_e32 v129, v113
	v_exp_f32_e32 v112, v80
	v_exp_f32_e32 v113, v81
	v_add_f32_e32 v12, v130, v114
	v_add_f32_e32 v13, v131, v115
	v_mov_b32_e32 v14, v84
	v_mov_b32_e32 v15, v85
	v_mfma_f32_32x32x16_bf16 v[16:31], v[96:99], v[160:163], v[16:31]
	v_add_f32_e32 v10, v128, v112
	v_add_f32_e32 v11, v129, v113
	v_exp_f32_e32 v80, v118
	v_exp_f32_e32 v81, v119
	v_exp_f32_e32 v82, v120
	v_mfma_f32_32x32x16_bf16 v[16:31], v[100:103], v[156:159], v[16:31]
	v_exp_f32_e32 v83, v121
	v_add_f32_e32 v10, v12, v10
	v_add_f32_e32 v11, v13, v11
	v_exp_f32_e32 v84, v122
	v_exp_f32_e32 v85, v123
	v_mfma_f32_32x32x16_bf16 v[16:31], v[104:107], v[152:155], v[16:31]
	v_mov_b32_e32 v12, v116
	v_mov_b32_e32 v13, v117
	v_exp_f32_e32 v116, v124
	v_exp_f32_e32 v117, v125
	s_waitcnt lgkmcnt(2)
	v_mfma_f32_32x32x16_bf16 v[48:63], v[108:111], v[144:147], v[48:63]
	v_add_u32_e32 v110, 0x8800, v132
	v_add_u32_e32 v111, 0x9800, v132
	ds_read2_b64 v[100:103], v111 offset0:96 offset1:98
	v_exp_f32_e32 v12, v12
	s_waitcnt lgkmcnt(2)
	v_mfma_f32_32x32x16_bf16 v[16:31], v[6:9], v[148:151], v[16:31]
	ds_read2_b64 v[6:9], v110 offset0:64 offset1:66
	v_exp_f32_e32 v13, v13

; __device__ __forceinline__ unsigned cvt_pk_bf16(float lo, float hi) { unsigned r; asm("v_cvt_pk_bf16_f32 %0, %1, %2" : "=v"(r) : "v"(lo), "v"(hi)); return r; }
; template <bool QK, bool SM>
; __device__ __forceinline__ void attn_step(const LAS unsigned char* kb, const LAS unsigned char* vbp, const bf16x8 (&qr)[6],
;                                           f32x16& s0, f32x16& s1, f32x16& o0, f32x16& o1, float& mrow, float& lsum) {
;     ...
;         for (int S = 0; S < 4; ++S) { u32x4 w;
;             if (S < 2) { w.x = cvt_pk_bf16(s0[8 * S + 0], s0[8 * S + 1]); w.y = cvt_pk_bf16(s0[8 * S + 2], s0[8 * S + 3]); w.z = cvt_pk_bf16(s0[8 * S + 4], s0[8 * S + 5]); w.w = cvt_pk_bf16(s0[8 * S + 6], s0[8 * S + 7]); }
;             else { w.x = cvt_pk_bf16(s1[8 * S - 16], s1[8 * S - 15]); w.y = cvt_pk_bf16(s1[8 * S - 14], s1[8 * S - 13]); w.z = cvt_pk_bf16(s1[8 * S - 12], s1[8 * S - 11]); w.w = cvt_pk_bf16(s1[8 * S - 10], s1[8 * S - 9]); }
;             pb[S] = __builtin_bit_cast(bf16x8, w); }
	v_cvt_pk_bf16_f32 v96, v128, v129


; __device__ __forceinline__ unsigned cvt_pk_bf16(float lo, float hi) { unsigned r; asm("v_cvt_pk_bf16_f32 %0, %1, %2" : "=v"(r) : "v"(lo), "v"(hi)); return r; }
; template <bool QK, bool SM>
; __device__ __forceinline__ void attn_step(const LAS unsigned char* kb, const LAS unsigned char* vbp, const bf16x8 (&qr)[6],
;                                           f32x16& s0, f32x16& s1, f32x16& o0, f32x16& o1, float& mrow, float& lsum) {
;     ...
;         for (int S = 0; S < 4; ++S) { u32x4 w;
;             if (S < 2) { w.x = cvt_pk_bf16(s0[8 * S + 0], s0[8 * S + 1]); w.y = cvt_pk_bf16(s0[8 * S + 2], s0[8 * S + 3]); w.z = cvt_pk_bf16(s0[8 * S + 4], s0[8 * S + 5]); w.w = cvt_pk_bf16(s0[8 * S + 6], s0[8 * S + 7]); }
;             else { w.x = cvt_pk_bf16(s1[8 * S - 16], s1[8 * S - 15]); w.y = cvt_pk_bf16(s1[8 * S - 14], s1[8 * S - 13]); w.z = cvt_pk_bf16(s1[8 * S - 12], s1[8 * S - 11]); w.w = cvt_pk_bf16(s1[8 * S - 10], s1[8 * S - 9]); }
;             pb[S] = __builtin_bit_cast(bf16x8, w); }
	v_cvt_pk_bf16_f32 v97, v130, v131


; __device__ __forceinline__ unsigned cvt_pk_bf16(float lo, float hi) { unsigned r; asm("v_cvt_pk_bf16_f32 %0, %1, %2" : "=v"(r) : "v"(lo), "v"(hi)); return r; }
; template <bool QK, bool SM>
; __device__ __forceinline__ void attn_step(const LAS unsigned char* kb, const LAS unsigned char* vbp, const bf16x8 (&qr)[6],
;                                           f32x16& s0, f32x16& s1, f32x16& o0, f32x16& o1, float& mrow, float& lsum) {
;     ...
;         for (int S = 0; S < 4; ++S) { u32x4 w;
;             if (S < 2) { w.x = cvt_pk_bf16(s0[8 * S + 0], s0[8 * S + 1]); w.y = cvt_pk_bf16(s0[8 * S + 2], s0[8 * S + 3]); w.z = cvt_pk_bf16(s0[8 * S + 4], s0[8 * S + 5]); w.w = cvt_pk_bf16(s0[8 * S + 6], s0[8 * S + 7]); }
;             else { w.x = cvt_pk_bf16(s1[8 * S - 16], s1[8 * S - 15]); w.y = cvt_pk_bf16(s1[8 * S - 14], s1[8 * S - 13]); w.z = cvt_pk_bf16(s1[8 * S - 12], s1[8 * S - 11]); w.w = cvt_pk_bf16(s1[8 * S - 10], s1[8 * S - 9]); }
;             pb[S] = __builtin_bit_cast(bf16x8, w); }
	v_cvt_pk_bf16_f32 v98, v12, v13


; __device__ __forceinline__ unsigned cvt_pk_bf16(float lo, float hi) { unsigned r; asm("v_cvt_pk_bf16_f32 %0, %1, %2" : "=v"(r) : "v"(lo), "v"(hi)); return r; }
; template <bool QK, bool SM>
; __device__ __forceinline__ void attn_step(const LAS unsigned char* kb, const LAS unsigned char* vbp, const bf16x8 (&qr)[6],
;                                           f32x16& s0, f32x16& s1, f32x16& o0, f32x16& o1, float& mrow, float& lsum) {
;     ...
;         for (int S = 0; S < 4; ++S) { u32x4 w;
;             if (S < 2) { w.x = cvt_pk_bf16(s0[8 * S + 0], s0[8 * S + 1]); w.y = cvt_pk_bf16(s0[8 * S + 2], s0[8 * S + 3]); w.z = cvt_pk_bf16(s0[8 * S + 4], s0[8 * S + 5]); w.w = cvt_pk_bf16(s0[8 * S + 6], s0[8 * S + 7]); }
;             else { w.x = cvt_pk_bf16(s1[8 * S - 16], s1[8 * S - 15]); w.y = cvt_pk_bf16(s1[8 * S - 14], s1[8 * S - 13]); w.z = cvt_pk_bf16(s1[8 * S - 12], s1[8 * S - 11]); w.w = cvt_pk_bf16(s1[8 * S - 10], s1[8 * S - 9]); }
;             pb[S] = __builtin_bit_cast(bf16x8, w); }
	v_cvt_pk_bf16_f32 v99, v80, v81

; #define LAS __attribute__((address_space(3)))
; __device__ __forceinline__ unsigned cvt_pk_bf16(float lo, float hi) { unsigned r; asm("v_cvt_pk_bf16_f32 %0, %1, %2" : "=v"(r) : "v"(lo), "v"(hi)); return r; }
; template <bool QK, bool SM>
; __device__ __forceinline__ void attn_step(const LAS unsigned char* kb, const LAS unsigned char* vbp, const bf16x8 (&qr)[6],
;                                           f32x16& s0, f32x16& s1, f32x16& o0, f32x16& o1, float& mrow, float& lsum) {
;     ...
;             s0[r] = a.x; s0[r + 1] = a.y; s1[r] = b.x; s1[r + 1] = b.y; ps2 += a + b; }
;         const float ps = ps2.x + ps2.y;
;         lsum = lsum * alpha + ps;
; #pragma unroll
;         for (int r = 0; r < 16; ++r) { o0[r] *= alpha; o1[r] *= alpha; }
;         bf16x8 pb[4];
; #pragma unroll
;         for (int S = 0; S < 4; ++S) { u32x4 w;
;             if (S < 2) { w.x = cvt_pk_bf16(s0[8 * S + 0], s0[8 * S + 1]); w.y = cvt_pk_bf16(s0[8 * S + 2], s0[8 * S + 3]); w.z = cvt_pk_bf16(s0[8 * S + 4], s0[8 * S + 5]); w.w = cvt_pk_bf16(s0[8 * S + 6], s0[8 * S + 7]); }
;             else { w.x = cvt_pk_bf16(s1[8 * S - 16], s1[8 * S - 15]); w.y = cvt_pk_bf16(s1[8 * S - 14], s1[8 * S - 13]); w.z = cvt_pk_bf16(s1[8 * S - 12], s1[8 * S - 11]); w.w = cvt_pk_bf16(s1[8 * S - 10], s1[8 * S - 9]); }
;             pb[S] = __builtin_bit_cast(bf16x8, w); }
; #pragma unroll
;         for (int S = 0; S < 4; ++S) {
;             const u32x2 a0 = *(const LAS u32x2*)(vbp + S * 32), a1 = *(const LAS u32x2*)(vbp + S * 32 + 16);
;             const u32x2 c0 = *(const LAS u32x2*)(vbp + 32 * VPITCH + S * 32), c1 = *(const LAS u32x2*)(vbp + 32 * VPITCH + S * 32 + 16);
;             const bf16x8 va = __builtin_bit_cast(bf16x8, (u32x4){a0.x, a0.y, a1.x, a1.y}), vc = __builtin_bit_cast(bf16x8, (u32x4){c0.x, c0.y, c1.x, c1.y});
;             o0 = __builtin_amdgcn_mfma_f32_32x32x16_bf16(va, pb[S], o0, 0, 0, 0); o1 = __builtin_amdgcn_mfma_f32_32x32x16_bf16(vc, pb[S], o1, 0, 0, 0); }
	s_waitcnt lgkmcnt(0)
	s_nop 0
	s_waitcnt vmcnt(5)
	ds_write_b128 v197, v[184:187] offset:13312
	s_and_saveexec_b64 s[10:11], s[0:1]
	s_waitcnt vmcnt(4)
	ds_write_b128 v212, v[180:183] offset:13312
	s_or_b64 exec, exec, s[10:11]
	s_waitcnt vmcnt(3)
	ds_write2_b64 v205, v[188:189], v[190:191] offset1:1
	v_mfma_f32_32x32x16_bf16 v[32:47], v[6:9], v[96:99], v[32:47]
	ds_read2_b64 v[6:9], v110 offset0:68 offset1:70
	v_exp_f32_e32 v14, v14
	v_mfma_f32_32x32x16_bf16 v[64:79], v[100:103], v[96:99], v[64:79]
	ds_read2_b64 v[100:103], v111 offset0:100 offset1:102
	v_exp_f32_e32 v104, v126
	v_exp_f32_e32 v105, v127
	v_cvt_pk_bf16_f32 v96, v82, v83
	v_cvt_pk_bf16_f32 v97, v84, v85
	v_cvt_pk_bf16_f32 v98, v116, v117
	v_cvt_pk_bf16_f32 v99, v104, v105
	v_exp_f32_e32 v15, v15
	s_waitcnt lgkmcnt(1)
	v_mfma_f32_32x32x16_bf16 v[32:47], v[6:9], v[96:99], v[32:47]
	v_exp_f32_e32 v106, v86
	v_exp_f32_e32 v107, v87
	ds_read2_b64 v[6:9], v110 offset0:72 offset1:74
	v_exp_f32_e32 v108, v88
	v_exp_f32_e32 v109, v89
	s_waitcnt lgkmcnt(1)
	v_mfma_f32_32x32x16_bf16 v[64:79], v[100:103], v[96:99], v[64:79]
	ds_read2_b64 v[96:99], v111 offset0:104 offset1:106
	v_cvt_pk_bf16_f32 v86, v112, v113
	v_cvt_pk_bf16_f32 v87, v114, v115
	v_cvt_pk_bf16_f32 v88, v14, v15
	v_cvt_pk_bf16_f32 v89, v106, v107
	s_waitcnt lgkmcnt(1)
	s_nop 0
	v_mfma_f32_32x32x16_bf16 v[32:47], v[6:9], v[86:89], v[32:47]
	v_exp_f32_e32 v100, v90
	v_exp_f32_e32 v101, v91
	v_exp_f32_e32 v102, v92
	v_exp_f32_e32 v103, v93
	ds_read2_b64 v[6:9], v110 offset0:76 offset1:78
	v_exp_f32_e32 v94, v94
	v_exp_f32_e32 v95, v95
	ds_read2_b64 v[90:93], v111 offset0:108 offset1:110
	s_waitcnt lgkmcnt(2)
	v_mfma_f32_32x32x16_bf16 v[64:79], v[96:99], v[86:89], v[64:79]
	v_cvt_pk_bf16_f32 v86, v108, v109
	v_cvt_pk_bf16_f32 v87, v100, v101
	v_cvt_pk_bf16_f32 v88, v102, v103
	v_cvt_pk_bf16_f32 v89, v94, v95
	s_waitcnt lgkmcnt(1)
	s_nop 0
	v_mfma_f32_32x32x16_bf16 v[32:47], v[6:9], v[86:89], v[32:47]
	v_add_f32_e32 v6, v12, v14
	v_add_f32_e32 v7, v13, v15
	v_add_f32_e32 v8, v80, v106
	v_add_f32_e32 v9, v81, v107
	v_add_f32_e32 v6, v6, v10
	v_add_f32_e32 v7, v7, v11
	v_add_f32_e32 v6, v8, v6
	v_add_f32_e32 v7, v9, v7
	v_add_f32_e32 v8, v82, v108
	v_add_f32_e32 v9, v83, v109
	s_waitcnt lgkmcnt(0)
	v_mfma_f32_32x32x16_bf16 v[64:79], v[90:93], v[86:89], v[64:79]
	v_add_f32_e32 v6, v8, v6
	v_add_f32_e32 v7, v9, v7
	v_add_f32_e32 v8, v84, v100
	v_add_f32_e32 v9, v85, v101
	v_add_f32_e32 v6, v8, v6
	v_add_f32_e32 v7, v9, v7
	v_add_f32_e32 v8, v116, v102
	v_add_f32_e32 v9, v117, v103
	s_nop 0
	v_add_f32_e32 v6, v8, v6
	v_add_f32_e32 v7, v9, v7
	v_mfma_f32_32x32x16_bf16 v[16:31], v[2:5], v[144:147], v[16:31]
	v_add_f32_e32 v8, v104, v94
	v_add_f32_e32 v9, v105, v95
	v_add_f32_e32 v6, v8, v6
	v_add_f32_e32 v7, v9, v7
	v_add_f32_e32 v215, v6, v7
	v_add_f32_e32 v215, v215, v216
	s_cmp_lg_u32 s99, 0
	s_cbranch_scc1 .Latt_slow2B
